# v5 plus: b_alpha quads loaded once per log-decay tile, activation tile stored as dwordx4, mid-block setprio flips removed
# baseline (speedup 1.0000x reference)
.LBB0_147:
	s_add_u32 s10, s8, 0xfffc0080
	s_addc_u32 s11, s9, -1
	s_add_i32 s70, 0, 0x10000
	s_cmp_eq_u32 s57, 12
	s_cselect_b32 s31, s25, s11
	s_cselect_b32 s30, s36, s10
	v_add_u32_e32 v154, s70, v174
	s_cselect_b32 s11, s23, s56
	s_cselect_b32 s10, s37, s55
	s_add_i32 s72, 0, 0x14000
	ds_read_b128 v[132:135], v154
	ds_read_b128 v[136:139], v154 offset:1024
	ds_read_b128 v[150:153], v154 offset:2048
	ds_read_b128 v[170:173], v154 offset:3072
	v_add_u32_e32 v154, s72, v174
	ds_read_b128 v[176:179], v154
	ds_read_b128 v[180:183], v154 offset:1024
	ds_read_b128 v[184:187], v154 offset:2048
	ds_read_b128 v[188:191], v154 offset:3072
	v_lshl_add_u64 v[154:155], s[8:9], 0, v[146:147]
	s_add_i32 m0, s43, 0xc000
	ds_read_b128 v[192:195], v175
	ds_read_b128 v[196:199], v175 offset:1024
	ds_read_b128 v[200:203], v175 offset:2048
	ds_read_b128 v[204:207], v175 offset:3072
	ds_read_b128 v[220:223], v175 offset:4096
	ds_read_b128 v[224:227], v175 offset:5120
	ds_read_b128 v[228:231], v175 offset:6144
	ds_read_b128 v[232:235], v175 offset:7168
	global_load_lds_dwordx4 v[154:155], off
	v_lshl_add_u64 v[154:155], s[8:9], 0, v[148:149]
	s_add_i32 m0, s43, 0xe000
	s_nop 0
	global_load_lds_dwordx4 v[154:155], off
	s_waitcnt vmcnt(8)
	s_waitcnt lgkmcnt(0)
	s_barrier
	s_setprio 1
	s_waitcnt lgkmcnt(0)
	v_mfma_f32_16x16x32_bf16 v[128:131], v[132:135], v[192:195], v[128:131]
	v_mfma_f32_16x16x32_bf16 v[124:127], v[150:153], v[192:195], v[124:127]
	v_mfma_f32_16x16x32_bf16 v[112:115], v[132:135], v[200:203], v[112:115]
	v_mfma_f32_16x16x32_bf16 v[108:111], v[150:153], v[200:203], v[108:111]
	v_mfma_f32_16x16x32_bf16 v[96:99], v[132:135], v[220:223], v[96:99]
	v_mfma_f32_16x16x32_bf16 v[92:95], v[150:153], v[220:223], v[92:95]
	v_mfma_f32_16x16x32_bf16 v[80:83], v[132:135], v[228:231], v[80:83]
	v_mfma_f32_16x16x32_bf16 v[76:79], v[150:153], v[228:231], v[76:79]
	v_mfma_f32_16x16x32_bf16 v[128:131], v[136:139], v[196:199], v[128:131]
	v_mfma_f32_16x16x32_bf16 v[124:127], v[170:173], v[196:199], v[124:127]
	v_mfma_f32_16x16x32_bf16 v[112:115], v[136:139], v[204:207], v[112:115]
	v_mfma_f32_16x16x32_bf16 v[108:111], v[170:173], v[204:207], v[108:111]
	v_mfma_f32_16x16x32_bf16 v[96:99], v[136:139], v[224:227], v[96:99]
	v_mfma_f32_16x16x32_bf16 v[92:95], v[170:173], v[224:227], v[92:95]
	v_mfma_f32_16x16x32_bf16 v[80:83], v[136:139], v[232:235], v[80:83]
	v_mfma_f32_16x16x32_bf16 v[76:79], v[170:173], v[232:235], v[76:79]
	v_mfma_f32_16x16x32_bf16 v[120:123], v[176:179], v[192:195], v[120:123]
	v_mfma_f32_16x16x32_bf16 v[116:119], v[184:187], v[192:195], v[116:119]
	v_mfma_f32_16x16x32_bf16 v[104:107], v[176:179], v[200:203], v[104:107]
	v_mfma_f32_16x16x32_bf16 v[100:103], v[184:187], v[200:203], v[100:103]
	v_mfma_f32_16x16x32_bf16 v[88:91], v[176:179], v[220:223], v[88:91]
	v_mfma_f32_16x16x32_bf16 v[84:87], v[184:187], v[220:223], v[84:87]
	v_mfma_f32_16x16x32_bf16 v[72:75], v[176:179], v[228:231], v[72:75]
	v_mfma_f32_16x16x32_bf16 v[68:71], v[184:187], v[228:231], v[68:71]
	v_mfma_f32_16x16x32_bf16 v[120:123], v[180:183], v[196:199], v[120:123]
	v_mfma_f32_16x16x32_bf16 v[116:119], v[188:191], v[196:199], v[116:119]
	v_mfma_f32_16x16x32_bf16 v[104:107], v[180:183], v[204:207], v[104:107]
	v_mfma_f32_16x16x32_bf16 v[100:103], v[188:191], v[204:207], v[100:103]
	v_mfma_f32_16x16x32_bf16 v[88:91], v[180:183], v[224:227], v[88:91]
	v_mfma_f32_16x16x32_bf16 v[84:87], v[188:191], v[224:227], v[84:87]
	v_mfma_f32_16x16x32_bf16 v[72:75], v[180:183], v[232:235], v[72:75]
	v_mfma_f32_16x16x32_bf16 v[68:71], v[188:191], v[232:235], v[68:71]
	s_setprio 0
	s_barrier
	s_add_i32 s70, s70, s38
	v_lshl_add_u64 v[154:155], s[10:11], 0, v[142:143]
	s_mov_b32 m0, s70
	ds_read_b128 v[192:195], v175 offset:16384
	ds_read_b128 v[196:199], v175 offset:17408
	ds_read_b128 v[200:203], v175 offset:18432
	ds_read_b128 v[204:207], v175 offset:19456
	ds_read_b128 v[220:223], v175 offset:20480
	ds_read_b128 v[224:227], v175 offset:21504
	ds_read_b128 v[228:231], v175 offset:22528
	ds_read_b128 v[232:235], v175 offset:23552
	global_load_lds_dwordx4 v[154:155], off
	s_add_i32 m0, s70, 0x2000
	s_add_u32 s70, s10, 0x40000
	v_lshl_add_u64 v[158:159], s[10:11], 0, v[0:1]
	s_addc_u32 s71, s11, 0
	s_add_i32 s72, s72, s38
	global_load_lds_dwordx4 v[158:159], off
	v_lshl_add_u64 v[160:161], s[70:71], 0, v[142:143]
	s_mov_b32 m0, s72
	v_lshl_add_u64 v[236:237], s[30:31], 0, v[140:141]
	global_load_lds_dwordx4 v[160:161], off
	v_lshl_add_u64 v[160:161], s[70:71], 0, v[0:1]
	s_add_i32 m0, s72, 0x2000
	s_nop 0
	global_load_lds_dwordx4 v[160:161], off
	v_lshl_add_u64 v[160:161], s[30:31], 0, v[144:145]
	s_mov_b32 m0, s43
	s_nop 0
	global_load_lds_dwordx4 v[160:161], off
	s_mov_b32 m0, s44
	s_nop 0
	global_load_lds_dwordx4 v[236:237], off
	s_waitcnt vmcnt(8)
	s_waitcnt lgkmcnt(0)
	s_barrier
	s_setprio 1
	s_waitcnt lgkmcnt(0)
	v_mfma_f32_16x16x32_bf16 v[64:67], v[132:135], v[192:195], v[64:67]
	v_mfma_f32_16x16x32_bf16 v[60:63], v[150:153], v[192:195], v[60:63]
	v_mfma_f32_16x16x32_bf16 v[48:51], v[132:135], v[200:203], v[48:51]
	v_mfma_f32_16x16x32_bf16 v[44:47], v[150:153], v[200:203], v[44:47]
	v_mfma_f32_16x16x32_bf16 v[32:35], v[132:135], v[220:223], v[32:35]
	v_mfma_f32_16x16x32_bf16 v[28:31], v[150:153], v[220:223], v[28:31]
	v_mfma_f32_16x16x32_bf16 v[16:19], v[132:135], v[228:231], v[16:19]
	v_mfma_f32_16x16x32_bf16 v[12:15], v[150:153], v[228:231], v[12:15]
	v_mfma_f32_16x16x32_bf16 v[64:67], v[136:139], v[196:199], v[64:67]
	v_mfma_f32_16x16x32_bf16 v[60:63], v[170:173], v[196:199], v[60:63]
	v_mfma_f32_16x16x32_bf16 v[48:51], v[136:139], v[204:207], v[48:51]
	v_mfma_f32_16x16x32_bf16 v[44:47], v[170:173], v[204:207], v[44:47]
	v_mfma_f32_16x16x32_bf16 v[32:35], v[136:139], v[224:227], v[32:35]
	v_mfma_f32_16x16x32_bf16 v[28:31], v[170:173], v[224:227], v[28:31]
	v_mfma_f32_16x16x32_bf16 v[16:19], v[136:139], v[232:235], v[16:19]
	v_mfma_f32_16x16x32_bf16 v[12:15], v[170:173], v[232:235], v[12:15]
	v_mfma_f32_16x16x32_bf16 v[56:59], v[176:179], v[192:195], v[56:59]
	v_mfma_f32_16x16x32_bf16 v[52:55], v[184:187], v[192:195], v[52:55]
	v_mfma_f32_16x16x32_bf16 v[40:43], v[176:179], v[200:203], v[40:43]
	v_mfma_f32_16x16x32_bf16 v[36:39], v[184:187], v[200:203], v[36:39]
	v_mfma_f32_16x16x32_bf16 v[24:27], v[176:179], v[220:223], v[24:27]
	v_mfma_f32_16x16x32_bf16 v[20:23], v[184:187], v[220:223], v[20:23]
	v_mfma_f32_16x16x32_bf16 v[8:11], v[176:179], v[228:231], v[8:11]
	v_mfma_f32_16x16x32_bf16 v[4:7], v[184:187], v[228:231], v[4:7]
	v_mfma_f32_16x16x32_bf16 v[56:59], v[180:183], v[196:199], v[56:59]
	v_mfma_f32_16x16x32_bf16 v[52:55], v[188:191], v[196:199], v[52:55]
	v_mfma_f32_16x16x32_bf16 v[40:43], v[180:183], v[204:207], v[40:43]
	v_mfma_f32_16x16x32_bf16 v[36:39], v[188:191], v[204:207], v[36:39]
	v_mfma_f32_16x16x32_bf16 v[24:27], v[180:183], v[224:227], v[24:27]
	v_mfma_f32_16x16x32_bf16 v[20:23], v[188:191], v[224:227], v[20:23]
	v_mfma_f32_16x16x32_bf16 v[8:11], v[180:183], v[232:235], v[8:11]
	v_mfma_f32_16x16x32_bf16 v[4:7], v[188:191], v[232:235], v[4:7]
	s_setprio 0
	s_barrier
	s_add_i32 s70, 0, 0x18000
	s_add_i32 s71, 0, 0x1c000
	v_add_u32_e32 v170, s70, v174
	v_add_u32_e32 v188, s71, v174
	ds_read_b128 v[132:135], v170
	ds_read_b128 v[136:139], v170 offset:1024
	ds_read_b128 v[150:153], v170 offset:2048
	ds_read_b128 v[170:173], v170 offset:3072
	ds_read_b128 v[176:179], v188
	ds_read_b128 v[180:183], v188 offset:1024
	ds_read_b128 v[184:187], v188 offset:2048
	ds_read_b128 v[188:191], v188 offset:3072
	s_add_u32 s30, s30, 0x40000
	s_addc_u32 s31, s31, 0
	s_mov_b32 m0, s45
	v_lshl_add_u64 v[238:239], s[30:31], 0, v[144:145]
	ds_read_b128 v[192:195], v175 offset:32768
	ds_read_b128 v[196:199], v175 offset:33792
	ds_read_b128 v[200:203], v175 offset:34816
	ds_read_b128 v[204:207], v175 offset:35840
	ds_read_b128 v[220:223], v175 offset:36864
	ds_read_b128 v[224:227], v175 offset:37888
	ds_read_b128 v[228:231], v175 offset:38912
	ds_read_b128 v[232:235], v175 offset:39936
	global_load_lds_dwordx4 v[238:239], off
	v_lshl_add_u64 v[238:239], s[30:31], 0, v[140:141]
	s_mov_b32 m0, s46
	s_nop 0
	global_load_lds_dwordx4 v[238:239], off
	s_waitcnt vmcnt(8)
	s_waitcnt lgkmcnt(0)
	s_barrier
	s_setprio 1
	s_waitcnt lgkmcnt(0)
	v_mfma_f32_16x16x32_bf16 v[128:131], v[132:135], v[192:195], v[128:131]
	v_mfma_f32_16x16x32_bf16 v[124:127], v[150:153], v[192:195], v[124:127]
	v_mfma_f32_16x16x32_bf16 v[112:115], v[132:135], v[200:203], v[112:115]
	v_mfma_f32_16x16x32_bf16 v[108:111], v[150:153], v[200:203], v[108:111]
	v_mfma_f32_16x16x32_bf16 v[96:99], v[132:135], v[220:223], v[96:99]
	v_mfma_f32_16x16x32_bf16 v[92:95], v[150:153], v[220:223], v[92:95]
	v_mfma_f32_16x16x32_bf16 v[80:83], v[132:135], v[228:231], v[80:83]
	v_mfma_f32_16x16x32_bf16 v[76:79], v[150:153], v[228:231], v[76:79]
	v_mfma_f32_16x16x32_bf16 v[128:131], v[136:139], v[196:199], v[128:131]
	v_mfma_f32_16x16x32_bf16 v[124:127], v[170:173], v[196:199], v[124:127]
	v_mfma_f32_16x16x32_bf16 v[112:115], v[136:139], v[204:207], v[112:115]
	v_mfma_f32_16x16x32_bf16 v[108:111], v[170:173], v[204:207], v[108:111]
	v_mfma_f32_16x16x32_bf16 v[96:99], v[136:139], v[224:227], v[96:99]
	v_mfma_f32_16x16x32_bf16 v[92:95], v[170:173], v[224:227], v[92:95]
	v_mfma_f32_16x16x32_bf16 v[80:83], v[136:139], v[232:235], v[80:83]
	v_mfma_f32_16x16x32_bf16 v[76:79], v[170:173], v[232:235], v[76:79]
	v_mfma_f32_16x16x32_bf16 v[120:123], v[176:179], v[192:195], v[120:123]
	v_mfma_f32_16x16x32_bf16 v[116:119], v[184:187], v[192:195], v[116:119]
	v_mfma_f32_16x16x32_bf16 v[104:107], v[176:179], v[200:203], v[104:107]
	v_mfma_f32_16x16x32_bf16 v[100:103], v[184:187], v[200:203], v[100:103]
	v_mfma_f32_16x16x32_bf16 v[88:91], v[176:179], v[220:223], v[88:91]
	v_mfma_f32_16x16x32_bf16 v[84:87], v[184:187], v[220:223], v[84:87]
	v_mfma_f32_16x16x32_bf16 v[72:75], v[176:179], v[228:231], v[72:75]
	v_mfma_f32_16x16x32_bf16 v[68:71], v[184:187], v[228:231], v[68:71]
	v_mfma_f32_16x16x32_bf16 v[120:123], v[180:183], v[196:199], v[120:123]
	v_mfma_f32_16x16x32_bf16 v[116:119], v[188:191], v[196:199], v[116:119]
	v_mfma_f32_16x16x32_bf16 v[104:107], v[180:183], v[204:207], v[104:107]
	v_mfma_f32_16x16x32_bf16 v[100:103], v[188:191], v[204:207], v[100:103]
	v_mfma_f32_16x16x32_bf16 v[88:91], v[180:183], v[224:227], v[88:91]
	v_mfma_f32_16x16x32_bf16 v[84:87], v[188:191], v[224:227], v[84:87]
	v_mfma_f32_16x16x32_bf16 v[72:75], v[180:183], v[232:235], v[72:75]
	v_mfma_f32_16x16x32_bf16 v[68:71], v[188:191], v[232:235], v[68:71]
	s_setprio 0
	s_barrier
	s_add_i32 s30, s70, s38
	v_lshl_add_u64 v[154:155], v[154:155], 0, s[76:77]
	s_mov_b32 m0, s30
	ds_read_b128 v[192:195], v175 offset:49152
	ds_read_b128 v[196:199], v175 offset:50176
	ds_read_b128 v[200:203], v175 offset:51200
	ds_read_b128 v[204:207], v175 offset:52224
	ds_read_b128 v[220:223], v175 offset:53248
	ds_read_b128 v[224:227], v175 offset:54272
	ds_read_b128 v[228:231], v175 offset:55296
	ds_read_b128 v[232:235], v175 offset:56320
	global_load_lds_dwordx4 v[154:155], off
	s_add_i32 m0, s30, 0x2000
	s_add_u32 s10, s10, 0x40080
	v_lshl_add_u64 v[154:155], v[158:159], 0, s[76:77]
	s_addc_u32 s11, s11, 0
	s_add_i32 s30, s71, s38
	global_load_lds_dwordx4 v[154:155], off
	v_lshl_add_u64 v[154:155], s[10:11], 0, v[142:143]
	s_mov_b32 m0, s30
	s_nop 0
	global_load_lds_dwordx4 v[154:155], off
	v_lshl_add_u64 v[154:155], s[10:11], 0, v[0:1]
	s_add_i32 m0, s30, 0x2000
	s_nop 0
	global_load_lds_dwordx4 v[154:155], off
	v_lshl_add_u64 v[154:155], v[160:161], 0, s[76:77]
	s_mov_b32 m0, s49
	s_nop 0
	global_load_lds_dwordx4 v[154:155], off
	v_lshl_add_u64 v[154:155], v[236:237], 0, s[76:77]
	s_mov_b32 m0, s50
	s_nop 0
	global_load_lds_dwordx4 v[154:155], off
	s_waitcnt vmcnt(8)
	s_waitcnt lgkmcnt(0)
	s_barrier
	s_setprio 1
	s_waitcnt lgkmcnt(0)
	v_mfma_f32_16x16x32_bf16 v[64:67], v[132:135], v[192:195], v[64:67]
	v_mfma_f32_16x16x32_bf16 v[60:63], v[150:153], v[192:195], v[60:63]
	v_mfma_f32_16x16x32_bf16 v[48:51], v[132:135], v[200:203], v[48:51]
	v_mfma_f32_16x16x32_bf16 v[44:47], v[150:153], v[200:203], v[44:47]
	v_mfma_f32_16x16x32_bf16 v[32:35], v[132:135], v[220:223], v[32:35]
	v_mfma_f32_16x16x32_bf16 v[28:31], v[150:153], v[220:223], v[28:31]
	v_mfma_f32_16x16x32_bf16 v[16:19], v[132:135], v[228:231], v[16:19]
	v_mfma_f32_16x16x32_bf16 v[12:15], v[150:153], v[228:231], v[12:15]
	v_mfma_f32_16x16x32_bf16 v[64:67], v[136:139], v[196:199], v[64:67]
	v_mfma_f32_16x16x32_bf16 v[60:63], v[170:173], v[196:199], v[60:63]
	v_mfma_f32_16x16x32_bf16 v[48:51], v[136:139], v[204:207], v[48:51]
	v_mfma_f32_16x16x32_bf16 v[44:47], v[170:173], v[204:207], v[44:47]
	v_mfma_f32_16x16x32_bf16 v[32:35], v[136:139], v[224:227], v[32:35]
	v_mfma_f32_16x16x32_bf16 v[28:31], v[170:173], v[224:227], v[28:31]
	v_mfma_f32_16x16x32_bf16 v[16:19], v[136:139], v[232:235], v[16:19]
	v_mfma_f32_16x16x32_bf16 v[12:15], v[170:173], v[232:235], v[12:15]
	v_mfma_f32_16x16x32_bf16 v[56:59], v[176:179], v[192:195], v[56:59]
	v_mfma_f32_16x16x32_bf16 v[52:55], v[184:187], v[192:195], v[52:55]
	v_mfma_f32_16x16x32_bf16 v[40:43], v[176:179], v[200:203], v[40:43]
	v_mfma_f32_16x16x32_bf16 v[36:39], v[184:187], v[200:203], v[36:39]
	v_mfma_f32_16x16x32_bf16 v[24:27], v[176:179], v[220:223], v[24:27]
	v_mfma_f32_16x16x32_bf16 v[20:23], v[184:187], v[220:223], v[20:23]
	v_mfma_f32_16x16x32_bf16 v[8:11], v[176:179], v[228:231], v[8:11]
	v_mfma_f32_16x16x32_bf16 v[4:7], v[184:187], v[228:231], v[4:7]
	v_mfma_f32_16x16x32_bf16 v[56:59], v[180:183], v[196:199], v[56:59]
	v_mfma_f32_16x16x32_bf16 v[52:55], v[188:191], v[196:199], v[52:55]
	v_mfma_f32_16x16x32_bf16 v[40:43], v[180:183], v[204:207], v[40:43]
	v_mfma_f32_16x16x32_bf16 v[36:39], v[188:191], v[204:207], v[36:39]
	v_mfma_f32_16x16x32_bf16 v[24:27], v[180:183], v[224:227], v[24:27]
	v_mfma_f32_16x16x32_bf16 v[20:23], v[188:191], v[224:227], v[20:23]
	v_mfma_f32_16x16x32_bf16 v[8:11], v[180:183], v[232:235], v[8:11]
	v_mfma_f32_16x16x32_bf16 v[4:7], v[188:191], v[232:235], v[4:7]
	s_setprio 0
	s_barrier
	s_add_i32 s57, s57, 2
	s_add_u32 s8, s8, 0x100
	s_addc_u32 s9, s9, 0
	s_add_u32 s55, s55, 0x100
	s_addc_u32 s56, s56, 0
	s_cmp_gt_u32 s57, 13
	s_cbranch_scc0 .LBB0_147
	s_and_b64 vcc, exec, s[20:21]
	s_cbranch_vccz .LBB0_150
	s_barrier
.LBB0_150:
	s_lshl_b32 s8, s35, 8
	s_add_i32 s8, s8, s47
	s_and_b32 s9, s54, -2
	s_cmp_eq_u32 s9, 4
	s_cselect_b64 s[10:11], -1, 0
	s_lshl_b32 s9, s34, 10
	v_mov_b32_e32 v132, v3
	v_mov_b32_e32 v133, v157
	s_add_i32 s9, s51, s9
	s_mov_b32 s23, 0xbfb8aa3b
	v_lshl_add_u32 v176, v132, 2, s9
	ds_read_b32 v170, v176
	v_add_u32_e32 v152, s8, v132
	v_ashrrev_i32_e32 v153, 31, v152
	s_mov_b32 s25, 0x3f317217
	s_mov_b32 s55, 0x7f800000
	s_mov_b32 s57, 0x42fc0000
	s_mov_b32 s56, 0x3e000000
	v_lshl_add_u32 v150, v133, 3, s48
	v_lshlrev_b64 v[154:155], 9, v[152:153]
	s_waitcnt lgkmcnt(0)
	v_pk_mul_f32 v[130:131], v[130:131], v[170:171] op_sel_hi:[1,0]
	v_pk_mul_f32 v[128:129], v[128:129], v[170:171] op_sel_hi:[1,0]
	v_pk_mul_f32 v[126:127], v[126:127], v[170:171] op_sel_hi:[1,0]
	v_pk_mul_f32 v[124:125], v[124:125], v[170:171] op_sel_hi:[1,0]
	s_mov_b64 s[34:35], -1
	s_mov_b64 s[30:31], 0
	s_cmp_lt_i32 s54, 9
	s_mov_b64 s[8:9], 0
	s_cbranch_scc1 .LBB0_154
	s_cmp_eq_u32 s54, 9
	s_mov_b64 s[8:9], -1
	s_cbranch_scc0 .LBB0_153
	v_ashrrev_i32_e32 v151, 31, v150
	v_lshl_add_u64 v[136:137], v[150:151], 2, s[18:19]
	global_load_dwordx4 v[180:183], v[136:137], off
	global_load_dwordx4 v[184:187], v[136:137], off offset:16
	global_load_dwordx4 v[188:191], v[136:137], off offset:512
	global_load_dwordx4 v[192:195], v[136:137], off offset:528
	s_waitcnt vmcnt(0)
	v_mov_b64_e32 v[132:133], v[184:185]
	v_mov_b64_e32 v[134:135], v[186:187]
	v_mov_b64_e32 v[136:137], v[180:181]
	v_mov_b64_e32 v[138:139], v[182:183]
	v_add_f32_e32 v132, v124, v132
	v_add_f32_e32 v136, v128, v136
	v_min_f32_e32 v153, 0, v136
	v_mul_f32_e64 v136, |v136|, s23
	v_exp_f32_e32 v136, v136
	v_add_f32_e32 v137, v129, v137
	v_add_f32_e32 v133, v125, v133
	v_add_f32_e32 v138, v130, v138
	v_add_f32_e32 v136, 1.0, v136
	v_cmp_gt_f32_e32 vcc, s68, v136
	v_add_f32_e32 v134, v126, v134
	s_nop 0
	v_cndmask_b32_e64 v158, 0, 32, vcc
	v_ldexp_f32 v136, v136, v158
	v_log_f32_e32 v136, v136
	s_nop 0
	v_mul_f32_e32 v158, 0x3f317217, v136
	v_fma_f32 v158, v136, s25, -v158
	v_fmac_f32_e32 v158, 0x3377d1cf, v136
	v_fmac_f32_e32 v158, 0x3f317217, v136
	v_cmp_lt_f32_e64 s[8:9], |v136|, s55
	s_nop 1
	v_cndmask_b32_e64 v136, v136, v158, s[8:9]
	v_cndmask_b32_e32 v158, 0, v212, vcc
	v_sub_f32_e32 v136, v136, v158
	v_sub_f32_e32 v136, v153, v136
	v_min_f32_e32 v153, 0, v132
	v_mul_f32_e64 v132, |v132|, s23
	v_exp_f32_e32 v132, v132
	v_mul_f32_e32 v136, 0x3d800000, v136
	v_add_f32_e32 v132, 1.0, v132
	v_cmp_gt_f32_e32 vcc, s68, v132
	s_nop 1
	v_cndmask_b32_e64 v158, 0, 32, vcc
	v_ldexp_f32 v132, v132, v158
	v_log_f32_e32 v132, v132
	s_nop 0
	v_mul_f32_e32 v158, 0x3f317217, v132
	v_fma_f32 v158, v132, s25, -v158
	v_fmac_f32_e32 v158, 0x3377d1cf, v132
	v_fmac_f32_e32 v158, 0x3f317217, v132
	v_cmp_lt_f32_e64 s[8:9], |v132|, s55
	s_nop 1
	v_cndmask_b32_e64 v132, v132, v158, s[8:9]
	v_cndmask_b32_e32 v158, 0, v212, vcc
	v_sub_f32_e32 v132, v132, v158
	v_sub_f32_e32 v132, v153, v132
	v_min_f32_e32 v153, 0, v137
	v_mul_f32_e64 v137, |v137|, s23
	v_exp_f32_e32 v137, v137
	v_mul_f32_e32 v132, 0x3d800000, v132
	v_add_f32_e32 v137, 1.0, v137
	v_cmp_gt_f32_e32 vcc, s68, v137
	s_nop 1
	v_cndmask_b32_e64 v158, 0, 32, vcc
	v_ldexp_f32 v137, v137, v158
	v_log_f32_e32 v137, v137
	s_nop 0
	v_mul_f32_e32 v158, 0x3f317217, v137
	v_fma_f32 v158, v137, s25, -v158
	v_fmac_f32_e32 v158, 0x3377d1cf, v137
	v_fmac_f32_e32 v158, 0x3f317217, v137
	v_cmp_lt_f32_e64 s[8:9], |v137|, s55
	s_nop 1
	v_cndmask_b32_e64 v137, v137, v158, s[8:9]
	v_cndmask_b32_e32 v158, 0, v212, vcc
	v_sub_f32_e32 v137, v137, v158
	v_sub_f32_e32 v137, v153, v137
	v_min_f32_e32 v153, 0, v133
	v_mul_f32_e64 v133, |v133|, s23
	v_exp_f32_e32 v133, v133
	v_mul_f32_e32 v137, 0x3d800000, v137
	v_add_f32_e32 v133, 1.0, v133
	v_cmp_gt_f32_e32 vcc, s68, v133
	s_nop 1
	v_cndmask_b32_e64 v158, 0, 32, vcc
	v_ldexp_f32 v133, v133, v158
	v_log_f32_e32 v133, v133
	s_nop 0
	v_mul_f32_e32 v158, 0x3f317217, v133
	v_fma_f32 v158, v133, s25, -v158
	v_fmac_f32_e32 v158, 0x3377d1cf, v133
	v_fmac_f32_e32 v158, 0x3f317217, v133
	v_cmp_lt_f32_e64 s[8:9], |v133|, s55
	s_nop 1
	v_cndmask_b32_e64 v133, v133, v158, s[8:9]
	v_cndmask_b32_e32 v158, 0, v212, vcc
	v_sub_f32_e32 v133, v133, v158
	v_sub_f32_e32 v133, v153, v133
	v_min_f32_e32 v153, 0, v138
	v_mul_f32_e64 v138, |v138|, s23
	v_exp_f32_e32 v138, v138
	v_mul_f32_e32 v133, 0x3d800000, v133
	v_add_f32_e32 v138, 1.0, v138
	v_cmp_gt_f32_e32 vcc, s68, v138
	s_nop 1
	v_cndmask_b32_e64 v158, 0, 32, vcc
	v_ldexp_f32 v138, v138, v158
	v_log_f32_e32 v138, v138
	s_nop 0
	v_mul_f32_e32 v158, 0x3f317217, v138
	v_fma_f32 v158, v138, s25, -v158
	v_fmac_f32_e32 v158, 0x3377d1cf, v138
	v_fmac_f32_e32 v158, 0x3f317217, v138
	v_cmp_lt_f32_e64 s[8:9], |v138|, s55
	s_nop 1
	v_cndmask_b32_e64 v138, v138, v158, s[8:9]
	v_cndmask_b32_e32 v158, 0, v212, vcc
	v_sub_f32_e32 v138, v138, v158
	v_sub_f32_e32 v138, v153, v138
	v_min_f32_e32 v153, 0, v134
	v_mul_f32_e64 v134, |v134|, s23
	v_exp_f32_e32 v134, v134
	v_mul_f32_e32 v138, 0x3d800000, v138
	v_add_f32_e32 v134, 1.0, v134
	v_cmp_gt_f32_e32 vcc, s68, v134
	s_nop 1
	v_cndmask_b32_e64 v158, 0, 32, vcc
	v_ldexp_f32 v134, v134, v158
	v_log_f32_e32 v134, v134
	s_nop 0
	v_mul_f32_e32 v158, 0x3f317217, v134
	v_fma_f32 v158, v134, s25, -v158
	v_fmac_f32_e32 v158, 0x3377d1cf, v134
	v_fmac_f32_e32 v158, 0x3f317217, v134
	v_cmp_lt_f32_e64 s[8:9], |v134|, s55
	s_nop 1
	v_cndmask_b32_e64 v134, v134, v158, s[8:9]
	v_cndmask_b32_e32 v158, 0, v212, vcc
	v_sub_f32_e32 v134, v134, v158
	v_sub_f32_e32 v134, v153, v134
	v_mul_f32_e32 v153, 0x3d800000, v134
	v_add_f32_e32 v134, v131, v139
	v_min_f32_e32 v139, 0, v134
	v_mul_f32_e64 v134, |v134|, s23
	v_exp_f32_e32 v134, v134
	s_nop 0
	v_add_f32_e32 v134, 1.0, v134
	v_cmp_gt_f32_e32 vcc, s68, v134
	s_nop 1
	v_cndmask_b32_e64 v158, 0, 32, vcc
	v_ldexp_f32 v134, v134, v158
	v_log_f32_e32 v134, v134
	s_nop 0
	v_mul_f32_e32 v158, 0x3f317217, v134
	v_fma_f32 v158, v134, s25, -v158
	v_fmac_f32_e32 v158, 0x3377d1cf, v134
	v_fmac_f32_e32 v158, 0x3f317217, v134
	v_cmp_lt_f32_e64 s[8:9], |v134|, s55
	s_nop 1
	v_cndmask_b32_e64 v134, v134, v158, s[8:9]
	v_cndmask_b32_e32 v158, 0, v212, vcc
	v_sub_f32_e32 v134, v134, v158
	v_sub_f32_e32 v134, v139, v134
	v_mul_f32_e32 v139, 0x3d800000, v134
	v_add_f32_e32 v134, v127, v135
	v_min_f32_e32 v135, 0, v134
	v_mul_f32_e64 v134, |v134|, s23
	v_exp_f32_e32 v134, v134
	s_nop 0
	v_add_f32_e32 v134, 1.0, v134
	v_cmp_gt_f32_e32 vcc, s68, v134
	s_nop 1
	v_cndmask_b32_e64 v158, 0, 32, vcc
	v_ldexp_f32 v134, v134, v158
	v_log_f32_e32 v134, v134
	s_nop 0
	v_mul_f32_e32 v158, 0x3f317217, v134
	v_fma_f32 v158, v134, s25, -v158
	v_fmac_f32_e32 v158, 0x3377d1cf, v134
	v_fmac_f32_e32 v158, 0x3f317217, v134
	v_cmp_lt_f32_e64 s[8:9], |v134|, s55
	s_nop 1
	v_cndmask_b32_e64 v134, v134, v158, s[8:9]
	v_cndmask_b32_e32 v158, 0, v212, vcc
	v_sub_f32_e32 v134, v134, v158
	v_sub_f32_e32 v134, v135, v134
	v_mul_f32_e32 v158, 0x3d800000, v134
	v_cvt_pk_bf16_f32 v134, v136, v137
	v_cvt_pk_bf16_f32 v135, v138, v139
	v_cvt_pk_bf16_f32 v136, v132, v133
	v_lshl_add_u64 v[132:133], s[16:17], 0, v[154:155]
	v_lshl_add_u64 v[132:133], v[150:151], 1, v[132:133]
	v_cvt_pk_bf16_f32 v137, v153, v158
	global_store_dwordx4 v[132:133], v[134:137], off
	s_mov_b64 s[8:9], 0

.LBB0_164:
	v_mov_b32_e32 v171, v170
	s_nop 0
	v_mov_b32_e32 v124, v170
	v_mov_b32_e32 v125, v170
	v_pk_mul_f32 v[122:123], v[122:123], v[124:125]
	v_pk_mul_f32 v[120:121], v[120:121], v[170:171]
	v_pk_mul_f32 v[118:119], v[118:119], v[124:125]
	v_pk_mul_f32 v[116:117], v[116:117], v[170:171]
	s_mov_b64 s[36:37], -1
	s_mov_b64 s[34:35], 0
	s_cmp_lt_i32 s54, 9
	s_mov_b64 s[10:11], 0
	s_cbranch_scc1 .LBB0_168
	s_cmp_eq_u32 s54, 9
	s_mov_b64 s[10:11], -1
	s_cbranch_scc0 .LBB0_167
	v_mov_b64_e32 v[124:125], v[192:193]
	v_mov_b64_e32 v[126:127], v[194:195]
	v_mov_b64_e32 v[128:129], v[188:189]
	v_mov_b64_e32 v[130:131], v[190:191]
	v_add_f32_e32 v124, v116, v124
	v_add_f32_e32 v128, v120, v128
	v_min_f32_e32 v132, 0, v128
	v_mul_f32_e64 v128, |v128|, s23
	v_exp_f32_e32 v128, v128
	v_add_f32_e32 v129, v121, v129
	v_add_f32_e32 v125, v117, v125
	v_add_f32_e32 v130, v122, v130
	v_add_f32_e32 v128, 1.0, v128
	v_cmp_gt_f32_e32 vcc, s68, v128
	v_add_f32_e32 v126, v118, v126
	s_nop 0
	v_cndmask_b32_e64 v133, 0, 32, vcc
	v_ldexp_f32 v128, v128, v133
	v_log_f32_e32 v128, v128
	s_nop 0
	v_mul_f32_e32 v133, 0x3f317217, v128
	v_fma_f32 v133, v128, s25, -v133
	v_fmac_f32_e32 v133, 0x3377d1cf, v128
	v_fmac_f32_e32 v133, 0x3f317217, v128
	v_cmp_lt_f32_e64 s[10:11], |v128|, s55
	s_nop 1
	v_cndmask_b32_e64 v128, v128, v133, s[10:11]
	v_cndmask_b32_e32 v133, 0, v212, vcc
	v_sub_f32_e32 v128, v128, v133
	v_sub_f32_e32 v128, v132, v128
	v_min_f32_e32 v132, 0, v124
	v_mul_f32_e64 v124, |v124|, s23
	v_exp_f32_e32 v124, v124
	v_mul_f32_e32 v128, 0x3d800000, v128
	v_add_f32_e32 v124, 1.0, v124
	v_cmp_gt_f32_e32 vcc, s68, v124
	s_nop 1
	v_cndmask_b32_e64 v133, 0, 32, vcc
	v_ldexp_f32 v124, v124, v133
	v_log_f32_e32 v124, v124
	s_nop 0
	v_mul_f32_e32 v133, 0x3f317217, v124
	v_fma_f32 v133, v124, s25, -v133
	v_fmac_f32_e32 v133, 0x3377d1cf, v124
	v_fmac_f32_e32 v133, 0x3f317217, v124
	v_cmp_lt_f32_e64 s[10:11], |v124|, s55
	s_nop 1
	v_cndmask_b32_e64 v124, v124, v133, s[10:11]
	v_cndmask_b32_e32 v133, 0, v212, vcc
	v_sub_f32_e32 v124, v124, v133
	v_sub_f32_e32 v124, v132, v124
	v_min_f32_e32 v132, 0, v129
	v_mul_f32_e64 v129, |v129|, s23
	v_exp_f32_e32 v129, v129
	v_mul_f32_e32 v124, 0x3d800000, v124
	v_add_f32_e32 v129, 1.0, v129
	v_cmp_gt_f32_e32 vcc, s68, v129
	s_nop 1
	v_cndmask_b32_e64 v133, 0, 32, vcc
	v_ldexp_f32 v129, v129, v133
	v_log_f32_e32 v129, v129
	s_nop 0
	v_mul_f32_e32 v133, 0x3f317217, v129
	v_fma_f32 v133, v129, s25, -v133
	v_fmac_f32_e32 v133, 0x3377d1cf, v129
	v_fmac_f32_e32 v133, 0x3f317217, v129
	v_cmp_lt_f32_e64 s[10:11], |v129|, s55
	s_nop 1
	v_cndmask_b32_e64 v129, v129, v133, s[10:11]
	v_cndmask_b32_e32 v133, 0, v212, vcc
	v_sub_f32_e32 v129, v129, v133
	v_sub_f32_e32 v129, v132, v129
	v_min_f32_e32 v132, 0, v125
	v_mul_f32_e64 v125, |v125|, s23
	v_exp_f32_e32 v125, v125
	v_mul_f32_e32 v129, 0x3d800000, v129
	v_add_f32_e32 v125, 1.0, v125
	v_cmp_gt_f32_e32 vcc, s68, v125
	s_nop 1
	v_cndmask_b32_e64 v133, 0, 32, vcc
	v_ldexp_f32 v125, v125, v133
	v_log_f32_e32 v125, v125
	s_nop 0
	v_mul_f32_e32 v133, 0x3f317217, v125
	v_fma_f32 v133, v125, s25, -v133
	v_fmac_f32_e32 v133, 0x3377d1cf, v125
	v_fmac_f32_e32 v133, 0x3f317217, v125
	v_cmp_lt_f32_e64 s[10:11], |v125|, s55
	s_nop 1
	v_cndmask_b32_e64 v125, v125, v133, s[10:11]
	v_cndmask_b32_e32 v133, 0, v212, vcc
	v_sub_f32_e32 v125, v125, v133
	v_sub_f32_e32 v125, v132, v125
	v_min_f32_e32 v132, 0, v130
	v_mul_f32_e64 v130, |v130|, s23
	v_exp_f32_e32 v130, v130
	v_mul_f32_e32 v125, 0x3d800000, v125
	v_add_f32_e32 v130, 1.0, v130
	v_cmp_gt_f32_e32 vcc, s68, v130
	s_nop 1
	v_cndmask_b32_e64 v133, 0, 32, vcc
	v_ldexp_f32 v130, v130, v133
	v_log_f32_e32 v130, v130
	s_nop 0
	v_mul_f32_e32 v133, 0x3f317217, v130
	v_fma_f32 v133, v130, s25, -v133
	v_fmac_f32_e32 v133, 0x3377d1cf, v130
	v_fmac_f32_e32 v133, 0x3f317217, v130
	v_cmp_lt_f32_e64 s[10:11], |v130|, s55
	s_nop 1
	v_cndmask_b32_e64 v130, v130, v133, s[10:11]
	v_cndmask_b32_e32 v133, 0, v212, vcc
	v_sub_f32_e32 v130, v130, v133
	v_sub_f32_e32 v130, v132, v130
	v_min_f32_e32 v132, 0, v126
	v_mul_f32_e64 v126, |v126|, s23
	v_exp_f32_e32 v126, v126
	v_mul_f32_e32 v130, 0x3d800000, v130
	v_add_f32_e32 v126, 1.0, v126
	v_cmp_gt_f32_e32 vcc, s68, v126
	s_nop 1
	v_cndmask_b32_e64 v133, 0, 32, vcc
	v_ldexp_f32 v126, v126, v133
	v_log_f32_e32 v126, v126
	s_nop 0
	v_mul_f32_e32 v133, 0x3f317217, v126
	v_fma_f32 v133, v126, s25, -v133
	v_fmac_f32_e32 v133, 0x3377d1cf, v126
	v_fmac_f32_e32 v133, 0x3f317217, v126
	v_cmp_lt_f32_e64 s[10:11], |v126|, s55
	s_nop 1
	v_cndmask_b32_e64 v126, v126, v133, s[10:11]
	v_cndmask_b32_e32 v133, 0, v212, vcc
	v_sub_f32_e32 v126, v126, v133
	v_sub_f32_e32 v126, v132, v126
	v_mul_f32_e32 v132, 0x3d800000, v126
	v_add_f32_e32 v126, v123, v131
	v_min_f32_e32 v131, 0, v126
	v_mul_f32_e64 v126, |v126|, s23
	v_exp_f32_e32 v126, v126
	s_nop 0
	v_add_f32_e32 v126, 1.0, v126
	v_cmp_gt_f32_e32 vcc, s68, v126
	s_nop 1
	v_cndmask_b32_e64 v133, 0, 32, vcc
	v_ldexp_f32 v126, v126, v133
	v_log_f32_e32 v126, v126
	s_nop 0
	v_mul_f32_e32 v133, 0x3f317217, v126
	v_fma_f32 v133, v126, s25, -v133
	v_fmac_f32_e32 v133, 0x3377d1cf, v126
	v_fmac_f32_e32 v133, 0x3f317217, v126
	v_cmp_lt_f32_e64 s[10:11], |v126|, s55
	s_nop 1
	v_cndmask_b32_e64 v126, v126, v133, s[10:11]
	v_cndmask_b32_e32 v133, 0, v212, vcc
	v_sub_f32_e32 v126, v126, v133
	v_sub_f32_e32 v126, v131, v126
	v_mul_f32_e32 v131, 0x3d800000, v126
	v_add_f32_e32 v126, v119, v127
	v_min_f32_e32 v127, 0, v126
	v_mul_f32_e64 v126, |v126|, s23
	v_exp_f32_e32 v126, v126
	s_nop 0
	v_add_f32_e32 v126, 1.0, v126
	v_cmp_gt_f32_e32 vcc, s68, v126
	s_nop 1
	v_cndmask_b32_e64 v133, 0, 32, vcc
	v_ldexp_f32 v126, v126, v133
	v_log_f32_e32 v126, v126
	s_nop 0
	v_mul_f32_e32 v133, 0x3f317217, v126
	v_fma_f32 v133, v126, s25, -v133
	v_fmac_f32_e32 v133, 0x3377d1cf, v126
	v_fmac_f32_e32 v133, 0x3f317217, v126
	v_cmp_lt_f32_e64 s[10:11], |v126|, s55
	s_nop 1
	v_cndmask_b32_e64 v126, v126, v133, s[10:11]
	v_cndmask_b32_e32 v133, 0, v212, vcc
	v_sub_f32_e32 v126, v126, v133
	v_sub_f32_e32 v126, v127, v126
	v_mul_f32_e32 v133, 0x3d800000, v126
	v_cvt_pk_bf16_f32 v126, v128, v129
	v_cvt_pk_bf16_f32 v127, v130, v131
	v_cvt_pk_bf16_f32 v128, v124, v125
	v_lshl_add_u64 v[124:125], s[16:17], 0, v[154:155]
	v_lshl_add_u64 v[124:125], v[150:151], 1, v[124:125]
	v_cvt_pk_bf16_f32 v129, v132, v133
	global_store_dwordx4 v[124:125], v[126:129], off offset:256
	s_mov_b64 s[10:11], 0

.LBB0_176:
	ds_read_b32 v126, v176 offset:64
	v_add_u32_e32 v128, 16, v152
	v_ashrrev_i32_e32 v129, 31, v128
	v_lshlrev_b64 v[124:125], 9, v[128:129]
	s_mov_b64 s[36:37], -1
	s_waitcnt lgkmcnt(0)
	v_pk_mul_f32 v[114:115], v[114:115], v[126:127] op_sel_hi:[1,0]
	v_pk_mul_f32 v[112:113], v[112:113], v[126:127] op_sel_hi:[1,0]
	v_pk_mul_f32 v[110:111], v[110:111], v[126:127] op_sel_hi:[1,0]
	v_pk_mul_f32 v[108:109], v[108:109], v[126:127] op_sel_hi:[1,0]
	s_mov_b64 s[34:35], 0
	s_cmp_lt_i32 s54, 9
	s_mov_b64 s[10:11], 0
	s_cbranch_scc1 .LBB0_182
	s_cmp_eq_u32 s54, 9
	s_mov_b64 s[10:11], -1
	s_cbranch_scc0 .LBB0_179
	v_mov_b64_e32 v[116:117], v[184:185]
	v_mov_b64_e32 v[118:119], v[186:187]
	v_mov_b64_e32 v[120:121], v[180:181]
	v_mov_b64_e32 v[122:123], v[182:183]
	v_add_f32_e32 v116, v108, v116
	v_add_f32_e32 v120, v112, v120
	v_min_f32_e32 v127, 0, v120
	v_mul_f32_e64 v120, |v120|, s23
	v_exp_f32_e32 v120, v120
	v_add_f32_e32 v121, v113, v121
	v_add_f32_e32 v117, v109, v117
	v_add_f32_e32 v122, v114, v122
	v_add_f32_e32 v120, 1.0, v120
	v_cmp_gt_f32_e32 vcc, s68, v120
	v_add_f32_e32 v118, v110, v118
	s_nop 0
	v_cndmask_b32_e64 v129, 0, 32, vcc
	v_ldexp_f32 v120, v120, v129
	v_log_f32_e32 v120, v120
	s_nop 0
	v_mul_f32_e32 v129, 0x3f317217, v120
	v_fma_f32 v129, v120, s25, -v129
	v_fmac_f32_e32 v129, 0x3377d1cf, v120
	v_fmac_f32_e32 v129, 0x3f317217, v120
	v_cmp_lt_f32_e64 s[10:11], |v120|, s55
	s_nop 1
	v_cndmask_b32_e64 v120, v120, v129, s[10:11]
	v_cndmask_b32_e32 v129, 0, v212, vcc
	v_sub_f32_e32 v120, v120, v129
	v_sub_f32_e32 v120, v127, v120
	v_min_f32_e32 v127, 0, v116
	v_mul_f32_e64 v116, |v116|, s23
	v_exp_f32_e32 v116, v116
	v_mul_f32_e32 v120, 0x3d800000, v120
	v_add_f32_e32 v116, 1.0, v116
	v_cmp_gt_f32_e32 vcc, s68, v116
	s_nop 1
	v_cndmask_b32_e64 v129, 0, 32, vcc
	v_ldexp_f32 v116, v116, v129
	v_log_f32_e32 v116, v116
	s_nop 0
	v_mul_f32_e32 v129, 0x3f317217, v116
	v_fma_f32 v129, v116, s25, -v129
	v_fmac_f32_e32 v129, 0x3377d1cf, v116
	v_fmac_f32_e32 v129, 0x3f317217, v116
	v_cmp_lt_f32_e64 s[10:11], |v116|, s55
	s_nop 1
	v_cndmask_b32_e64 v116, v116, v129, s[10:11]
	v_cndmask_b32_e32 v129, 0, v212, vcc
	v_sub_f32_e32 v116, v116, v129
	v_sub_f32_e32 v116, v127, v116
	v_min_f32_e32 v127, 0, v121
	v_mul_f32_e64 v121, |v121|, s23
	v_exp_f32_e32 v121, v121
	v_mul_f32_e32 v116, 0x3d800000, v116
	v_add_f32_e32 v121, 1.0, v121
	v_cmp_gt_f32_e32 vcc, s68, v121
	s_nop 1
	v_cndmask_b32_e64 v129, 0, 32, vcc
	v_ldexp_f32 v121, v121, v129
	v_log_f32_e32 v121, v121
	s_nop 0
	v_mul_f32_e32 v129, 0x3f317217, v121
	v_fma_f32 v129, v121, s25, -v129
	v_fmac_f32_e32 v129, 0x3377d1cf, v121
	v_fmac_f32_e32 v129, 0x3f317217, v121
	v_cmp_lt_f32_e64 s[10:11], |v121|, s55
	s_nop 1
	v_cndmask_b32_e64 v121, v121, v129, s[10:11]
	v_cndmask_b32_e32 v129, 0, v212, vcc
	v_sub_f32_e32 v121, v121, v129
	v_sub_f32_e32 v121, v127, v121
	v_min_f32_e32 v127, 0, v117
	v_mul_f32_e64 v117, |v117|, s23
	v_exp_f32_e32 v117, v117
	v_mul_f32_e32 v121, 0x3d800000, v121
	v_add_f32_e32 v117, 1.0, v117
	v_cmp_gt_f32_e32 vcc, s68, v117
	s_nop 1
	v_cndmask_b32_e64 v129, 0, 32, vcc
	v_ldexp_f32 v117, v117, v129
	v_log_f32_e32 v117, v117
	s_nop 0
	v_mul_f32_e32 v129, 0x3f317217, v117
	v_fma_f32 v129, v117, s25, -v129
	v_fmac_f32_e32 v129, 0x3377d1cf, v117
	v_fmac_f32_e32 v129, 0x3f317217, v117
	v_cmp_lt_f32_e64 s[10:11], |v117|, s55
	s_nop 1
	v_cndmask_b32_e64 v117, v117, v129, s[10:11]
	v_cndmask_b32_e32 v129, 0, v212, vcc
	v_sub_f32_e32 v117, v117, v129
	v_sub_f32_e32 v117, v127, v117
	v_min_f32_e32 v127, 0, v122
	v_mul_f32_e64 v122, |v122|, s23
	v_exp_f32_e32 v122, v122
	v_mul_f32_e32 v117, 0x3d800000, v117
	v_add_f32_e32 v122, 1.0, v122
	v_cmp_gt_f32_e32 vcc, s68, v122
	s_nop 1
	v_cndmask_b32_e64 v129, 0, 32, vcc
	v_ldexp_f32 v122, v122, v129
	v_log_f32_e32 v122, v122
	s_nop 0
	v_mul_f32_e32 v129, 0x3f317217, v122
	v_fma_f32 v129, v122, s25, -v129
	v_fmac_f32_e32 v129, 0x3377d1cf, v122
	v_fmac_f32_e32 v129, 0x3f317217, v122
	v_cmp_lt_f32_e64 s[10:11], |v122|, s55
	s_nop 1
	v_cndmask_b32_e64 v122, v122, v129, s[10:11]
	v_cndmask_b32_e32 v129, 0, v212, vcc
	v_sub_f32_e32 v122, v122, v129
	v_sub_f32_e32 v122, v127, v122
	v_min_f32_e32 v127, 0, v118
	v_mul_f32_e64 v118, |v118|, s23
	v_exp_f32_e32 v118, v118
	v_mul_f32_e32 v122, 0x3d800000, v122
	v_add_f32_e32 v118, 1.0, v118
	v_cmp_gt_f32_e32 vcc, s68, v118
	s_nop 1
	v_cndmask_b32_e64 v129, 0, 32, vcc
	v_ldexp_f32 v118, v118, v129
	v_log_f32_e32 v118, v118
	s_nop 0
	v_mul_f32_e32 v129, 0x3f317217, v118
	v_fma_f32 v129, v118, s25, -v129
	v_fmac_f32_e32 v129, 0x3377d1cf, v118
	v_fmac_f32_e32 v129, 0x3f317217, v118
	v_cmp_lt_f32_e64 s[10:11], |v118|, s55
	s_nop 1
	v_cndmask_b32_e64 v118, v118, v129, s[10:11]
	v_cndmask_b32_e32 v129, 0, v212, vcc
	v_sub_f32_e32 v118, v118, v129
	v_sub_f32_e32 v118, v127, v118
	v_mul_f32_e32 v127, 0x3d800000, v118
	v_add_f32_e32 v118, v115, v123
	v_min_f32_e32 v123, 0, v118
	v_mul_f32_e64 v118, |v118|, s23
	v_exp_f32_e32 v118, v118
	s_nop 0
	v_add_f32_e32 v118, 1.0, v118
	v_cmp_gt_f32_e32 vcc, s68, v118
	s_nop 1
	v_cndmask_b32_e64 v129, 0, 32, vcc
	v_ldexp_f32 v118, v118, v129
	v_log_f32_e32 v118, v118
	s_nop 0
	v_mul_f32_e32 v129, 0x3f317217, v118
	v_fma_f32 v129, v118, s25, -v129
	v_fmac_f32_e32 v129, 0x3377d1cf, v118
	v_fmac_f32_e32 v129, 0x3f317217, v118
	v_cmp_lt_f32_e64 s[10:11], |v118|, s55
	s_nop 1
	v_cndmask_b32_e64 v118, v118, v129, s[10:11]
	v_cndmask_b32_e32 v129, 0, v212, vcc
	v_sub_f32_e32 v118, v118, v129
	v_sub_f32_e32 v118, v123, v118
	v_mul_f32_e32 v123, 0x3d800000, v118
	v_add_f32_e32 v118, v111, v119
	v_min_f32_e32 v119, 0, v118
	v_mul_f32_e64 v118, |v118|, s23
	v_exp_f32_e32 v118, v118
	s_nop 0
	v_add_f32_e32 v118, 1.0, v118
	v_cmp_gt_f32_e32 vcc, s68, v118
	s_nop 1
	v_cndmask_b32_e64 v129, 0, 32, vcc
	v_ldexp_f32 v118, v118, v129
	v_log_f32_e32 v118, v118
	s_nop 0
	v_mul_f32_e32 v129, 0x3f317217, v118
	v_fma_f32 v129, v118, s25, -v129
	v_fmac_f32_e32 v129, 0x3377d1cf, v118
	v_fmac_f32_e32 v129, 0x3f317217, v118
	v_cmp_lt_f32_e64 s[10:11], |v118|, s55
	s_nop 1
	v_cndmask_b32_e64 v118, v118, v129, s[10:11]
	v_cndmask_b32_e32 v129, 0, v212, vcc
	v_sub_f32_e32 v118, v118, v129
	v_sub_f32_e32 v118, v119, v118
	v_mul_f32_e32 v129, 0x3d800000, v118
	v_cvt_pk_bf16_f32 v118, v120, v121
	v_cvt_pk_bf16_f32 v119, v122, v123
	v_cvt_pk_bf16_f32 v120, v116, v117
	v_lshl_add_u64 v[116:117], s[16:17], 0, v[124:125]
	v_lshl_add_u64 v[116:117], v[150:151], 1, v[116:117]
	v_cvt_pk_bf16_f32 v121, v127, v129
	global_store_dwordx4 v[116:117], v[118:121], off
	s_mov_b64 s[10:11], 0

.LBB0_192:
	v_mov_b32_e32 v127, v126
	s_nop 0
	v_mov_b32_e32 v108, v126
	v_mov_b32_e32 v109, v126
	v_pk_mul_f32 v[106:107], v[106:107], v[108:109]
	v_pk_mul_f32 v[104:105], v[104:105], v[126:127]
	v_pk_mul_f32 v[102:103], v[102:103], v[108:109]
	v_pk_mul_f32 v[100:101], v[100:101], v[126:127]
	s_mov_b64 s[36:37], -1
	s_mov_b64 s[34:35], 0
	s_cmp_lt_i32 s54, 9
	s_mov_b64 s[10:11], 0
	s_cbranch_scc1 .LBB0_196
	s_cmp_eq_u32 s54, 9
	s_mov_b64 s[10:11], -1
	s_cbranch_scc0 .LBB0_195
	v_mov_b64_e32 v[108:109], v[192:193]
	v_mov_b64_e32 v[110:111], v[194:195]
	v_mov_b64_e32 v[112:113], v[188:189]
	v_mov_b64_e32 v[114:115], v[190:191]
	v_add_f32_e32 v108, v100, v108
	v_add_f32_e32 v112, v104, v112
	v_min_f32_e32 v116, 0, v112
	v_mul_f32_e64 v112, |v112|, s23
	v_exp_f32_e32 v112, v112
	v_add_f32_e32 v113, v105, v113
	v_add_f32_e32 v109, v101, v109
	v_add_f32_e32 v114, v106, v114
	v_add_f32_e32 v112, 1.0, v112
	v_cmp_gt_f32_e32 vcc, s68, v112
	v_add_f32_e32 v110, v102, v110
	s_nop 0
	v_cndmask_b32_e64 v117, 0, 32, vcc
	v_ldexp_f32 v112, v112, v117
	v_log_f32_e32 v112, v112
	s_nop 0
	v_mul_f32_e32 v117, 0x3f317217, v112
	v_fma_f32 v117, v112, s25, -v117
	v_fmac_f32_e32 v117, 0x3377d1cf, v112
	v_fmac_f32_e32 v117, 0x3f317217, v112
	v_cmp_lt_f32_e64 s[10:11], |v112|, s55
	s_nop 1
	v_cndmask_b32_e64 v112, v112, v117, s[10:11]
	v_cndmask_b32_e32 v117, 0, v212, vcc
	v_sub_f32_e32 v112, v112, v117
	v_sub_f32_e32 v112, v116, v112
	v_min_f32_e32 v116, 0, v108
	v_mul_f32_e64 v108, |v108|, s23
	v_exp_f32_e32 v108, v108
	v_mul_f32_e32 v112, 0x3d800000, v112
	v_add_f32_e32 v108, 1.0, v108
	v_cmp_gt_f32_e32 vcc, s68, v108
	s_nop 1
	v_cndmask_b32_e64 v117, 0, 32, vcc
	v_ldexp_f32 v108, v108, v117
	v_log_f32_e32 v108, v108
	s_nop 0
	v_mul_f32_e32 v117, 0x3f317217, v108
	v_fma_f32 v117, v108, s25, -v117
	v_fmac_f32_e32 v117, 0x3377d1cf, v108
	v_fmac_f32_e32 v117, 0x3f317217, v108
	v_cmp_lt_f32_e64 s[10:11], |v108|, s55
	s_nop 1
	v_cndmask_b32_e64 v108, v108, v117, s[10:11]
	v_cndmask_b32_e32 v117, 0, v212, vcc
	v_sub_f32_e32 v108, v108, v117
	v_sub_f32_e32 v108, v116, v108
	v_min_f32_e32 v116, 0, v113
	v_mul_f32_e64 v113, |v113|, s23
	v_exp_f32_e32 v113, v113
	v_mul_f32_e32 v108, 0x3d800000, v108
	v_add_f32_e32 v113, 1.0, v113
	v_cmp_gt_f32_e32 vcc, s68, v113
	s_nop 1
	v_cndmask_b32_e64 v117, 0, 32, vcc
	v_ldexp_f32 v113, v113, v117
	v_log_f32_e32 v113, v113
	s_nop 0
	v_mul_f32_e32 v117, 0x3f317217, v113
	v_fma_f32 v117, v113, s25, -v117
	v_fmac_f32_e32 v117, 0x3377d1cf, v113
	v_fmac_f32_e32 v117, 0x3f317217, v113
	v_cmp_lt_f32_e64 s[10:11], |v113|, s55
	s_nop 1
	v_cndmask_b32_e64 v113, v113, v117, s[10:11]
	v_cndmask_b32_e32 v117, 0, v212, vcc
	v_sub_f32_e32 v113, v113, v117
	v_sub_f32_e32 v113, v116, v113
	v_min_f32_e32 v116, 0, v109
	v_mul_f32_e64 v109, |v109|, s23
	v_exp_f32_e32 v109, v109
	v_mul_f32_e32 v113, 0x3d800000, v113
	v_add_f32_e32 v109, 1.0, v109
	v_cmp_gt_f32_e32 vcc, s68, v109
	s_nop 1
	v_cndmask_b32_e64 v117, 0, 32, vcc
	v_ldexp_f32 v109, v109, v117
	v_log_f32_e32 v109, v109
	s_nop 0
	v_mul_f32_e32 v117, 0x3f317217, v109
	v_fma_f32 v117, v109, s25, -v117
	v_fmac_f32_e32 v117, 0x3377d1cf, v109
	v_fmac_f32_e32 v117, 0x3f317217, v109
	v_cmp_lt_f32_e64 s[10:11], |v109|, s55
	s_nop 1
	v_cndmask_b32_e64 v109, v109, v117, s[10:11]
	v_cndmask_b32_e32 v117, 0, v212, vcc
	v_sub_f32_e32 v109, v109, v117
	v_sub_f32_e32 v109, v116, v109
	v_min_f32_e32 v116, 0, v114
	v_mul_f32_e64 v114, |v114|, s23
	v_exp_f32_e32 v114, v114
	v_mul_f32_e32 v109, 0x3d800000, v109
	v_add_f32_e32 v114, 1.0, v114
	v_cmp_gt_f32_e32 vcc, s68, v114
	s_nop 1
	v_cndmask_b32_e64 v117, 0, 32, vcc
	v_ldexp_f32 v114, v114, v117
	v_log_f32_e32 v114, v114
	s_nop 0
	v_mul_f32_e32 v117, 0x3f317217, v114
	v_fma_f32 v117, v114, s25, -v117
	v_fmac_f32_e32 v117, 0x3377d1cf, v114
	v_fmac_f32_e32 v117, 0x3f317217, v114
	v_cmp_lt_f32_e64 s[10:11], |v114|, s55
	s_nop 1
	v_cndmask_b32_e64 v114, v114, v117, s[10:11]
	v_cndmask_b32_e32 v117, 0, v212, vcc
	v_sub_f32_e32 v114, v114, v117
	v_sub_f32_e32 v114, v116, v114
	v_min_f32_e32 v116, 0, v110
	v_mul_f32_e64 v110, |v110|, s23
	v_exp_f32_e32 v110, v110
	v_mul_f32_e32 v114, 0x3d800000, v114
	v_add_f32_e32 v110, 1.0, v110
	v_cmp_gt_f32_e32 vcc, s68, v110
	s_nop 1
	v_cndmask_b32_e64 v117, 0, 32, vcc
	v_ldexp_f32 v110, v110, v117
	v_log_f32_e32 v110, v110
	s_nop 0
	v_mul_f32_e32 v117, 0x3f317217, v110
	v_fma_f32 v117, v110, s25, -v117
	v_fmac_f32_e32 v117, 0x3377d1cf, v110
	v_fmac_f32_e32 v117, 0x3f317217, v110
	v_cmp_lt_f32_e64 s[10:11], |v110|, s55
	s_nop 1
	v_cndmask_b32_e64 v110, v110, v117, s[10:11]
	v_cndmask_b32_e32 v117, 0, v212, vcc
	v_sub_f32_e32 v110, v110, v117
	v_sub_f32_e32 v110, v116, v110
	v_mul_f32_e32 v116, 0x3d800000, v110
	v_add_f32_e32 v110, v107, v115
	v_min_f32_e32 v115, 0, v110
	v_mul_f32_e64 v110, |v110|, s23
	v_exp_f32_e32 v110, v110
	s_nop 0
	v_add_f32_e32 v110, 1.0, v110
	v_cmp_gt_f32_e32 vcc, s68, v110
	s_nop 1
	v_cndmask_b32_e64 v117, 0, 32, vcc
	v_ldexp_f32 v110, v110, v117
	v_log_f32_e32 v110, v110
	s_nop 0
	v_mul_f32_e32 v117, 0x3f317217, v110
	v_fma_f32 v117, v110, s25, -v117
	v_fmac_f32_e32 v117, 0x3377d1cf, v110
	v_fmac_f32_e32 v117, 0x3f317217, v110
	v_cmp_lt_f32_e64 s[10:11], |v110|, s55
	s_nop 1
	v_cndmask_b32_e64 v110, v110, v117, s[10:11]
	v_cndmask_b32_e32 v117, 0, v212, vcc
	v_sub_f32_e32 v110, v110, v117
	v_sub_f32_e32 v110, v115, v110
	v_mul_f32_e32 v115, 0x3d800000, v110
	v_add_f32_e32 v110, v103, v111
	v_min_f32_e32 v111, 0, v110
	v_mul_f32_e64 v110, |v110|, s23
	v_exp_f32_e32 v110, v110
	s_nop 0
	v_add_f32_e32 v110, 1.0, v110
	v_cmp_gt_f32_e32 vcc, s68, v110
	s_nop 1
	v_cndmask_b32_e64 v117, 0, 32, vcc
	v_ldexp_f32 v110, v110, v117
	v_log_f32_e32 v110, v110
	s_nop 0
	v_mul_f32_e32 v117, 0x3f317217, v110
	v_fma_f32 v117, v110, s25, -v117
	v_fmac_f32_e32 v117, 0x3377d1cf, v110
	v_fmac_f32_e32 v117, 0x3f317217, v110
	v_cmp_lt_f32_e64 s[10:11], |v110|, s55
	s_nop 1
	v_cndmask_b32_e64 v110, v110, v117, s[10:11]
	v_cndmask_b32_e32 v117, 0, v212, vcc
	v_sub_f32_e32 v110, v110, v117
	v_sub_f32_e32 v110, v111, v110
	v_mul_f32_e32 v117, 0x3d800000, v110
	v_cvt_pk_bf16_f32 v110, v112, v113
	v_cvt_pk_bf16_f32 v111, v114, v115
	v_cvt_pk_bf16_f32 v112, v108, v109
	v_lshl_add_u64 v[108:109], s[16:17], 0, v[124:125]
	v_lshl_add_u64 v[108:109], v[150:151], 1, v[108:109]
	v_cvt_pk_bf16_f32 v113, v116, v117
	global_store_dwordx4 v[108:109], v[110:113], off offset:256
	s_mov_b64 s[10:11], 0

.LBB0_204:
	ds_read_b32 v110, v176 offset:128
	v_add_u32_e32 v112, 32, v152
	v_ashrrev_i32_e32 v113, 31, v112
	v_lshlrev_b64 v[108:109], 9, v[112:113]
	s_mov_b64 s[36:37], -1
	s_waitcnt lgkmcnt(0)
	v_pk_mul_f32 v[98:99], v[98:99], v[110:111] op_sel_hi:[1,0]
	v_pk_mul_f32 v[96:97], v[96:97], v[110:111] op_sel_hi:[1,0]
	v_pk_mul_f32 v[94:95], v[94:95], v[110:111] op_sel_hi:[1,0]
	v_pk_mul_f32 v[92:93], v[92:93], v[110:111] op_sel_hi:[1,0]
	s_mov_b64 s[34:35], 0
	s_cmp_lt_i32 s54, 9
	s_mov_b64 s[10:11], 0
	s_cbranch_scc1 .LBB0_210
	s_cmp_eq_u32 s54, 9
	s_mov_b64 s[10:11], -1
	s_cbranch_scc0 .LBB0_207
	v_mov_b64_e32 v[100:101], v[184:185]
	v_mov_b64_e32 v[102:103], v[186:187]
	v_mov_b64_e32 v[104:105], v[180:181]
	v_mov_b64_e32 v[106:107], v[182:183]
	v_add_f32_e32 v100, v92, v100
	v_add_f32_e32 v104, v96, v104
	v_min_f32_e32 v111, 0, v104
	v_mul_f32_e64 v104, |v104|, s23
	v_exp_f32_e32 v104, v104
	v_add_f32_e32 v105, v97, v105
	v_add_f32_e32 v101, v93, v101
	v_add_f32_e32 v106, v98, v106
	v_add_f32_e32 v104, 1.0, v104
	v_cmp_gt_f32_e32 vcc, s68, v104
	v_add_f32_e32 v102, v94, v102
	s_nop 0
	v_cndmask_b32_e64 v113, 0, 32, vcc
	v_ldexp_f32 v104, v104, v113
	v_log_f32_e32 v104, v104
	s_nop 0
	v_mul_f32_e32 v113, 0x3f317217, v104
	v_fma_f32 v113, v104, s25, -v113
	v_fmac_f32_e32 v113, 0x3377d1cf, v104
	v_fmac_f32_e32 v113, 0x3f317217, v104
	v_cmp_lt_f32_e64 s[10:11], |v104|, s55
	s_nop 1
	v_cndmask_b32_e64 v104, v104, v113, s[10:11]
	v_cndmask_b32_e32 v113, 0, v212, vcc
	v_sub_f32_e32 v104, v104, v113
	v_sub_f32_e32 v104, v111, v104
	v_min_f32_e32 v111, 0, v100
	v_mul_f32_e64 v100, |v100|, s23
	v_exp_f32_e32 v100, v100
	v_mul_f32_e32 v104, 0x3d800000, v104
	v_add_f32_e32 v100, 1.0, v100
	v_cmp_gt_f32_e32 vcc, s68, v100
	s_nop 1
	v_cndmask_b32_e64 v113, 0, 32, vcc
	v_ldexp_f32 v100, v100, v113
	v_log_f32_e32 v100, v100
	s_nop 0
	v_mul_f32_e32 v113, 0x3f317217, v100
	v_fma_f32 v113, v100, s25, -v113
	v_fmac_f32_e32 v113, 0x3377d1cf, v100
	v_fmac_f32_e32 v113, 0x3f317217, v100
	v_cmp_lt_f32_e64 s[10:11], |v100|, s55
	s_nop 1
	v_cndmask_b32_e64 v100, v100, v113, s[10:11]
	v_cndmask_b32_e32 v113, 0, v212, vcc
	v_sub_f32_e32 v100, v100, v113
	v_sub_f32_e32 v100, v111, v100
	v_min_f32_e32 v111, 0, v105
	v_mul_f32_e64 v105, |v105|, s23
	v_exp_f32_e32 v105, v105
	v_mul_f32_e32 v100, 0x3d800000, v100
	v_add_f32_e32 v105, 1.0, v105
	v_cmp_gt_f32_e32 vcc, s68, v105
	s_nop 1
	v_cndmask_b32_e64 v113, 0, 32, vcc
	v_ldexp_f32 v105, v105, v113
	v_log_f32_e32 v105, v105
	s_nop 0
	v_mul_f32_e32 v113, 0x3f317217, v105
	v_fma_f32 v113, v105, s25, -v113
	v_fmac_f32_e32 v113, 0x3377d1cf, v105
	v_fmac_f32_e32 v113, 0x3f317217, v105
	v_cmp_lt_f32_e64 s[10:11], |v105|, s55
	s_nop 1
	v_cndmask_b32_e64 v105, v105, v113, s[10:11]
	v_cndmask_b32_e32 v113, 0, v212, vcc
	v_sub_f32_e32 v105, v105, v113
	v_sub_f32_e32 v105, v111, v105
	v_min_f32_e32 v111, 0, v101
	v_mul_f32_e64 v101, |v101|, s23
	v_exp_f32_e32 v101, v101
	v_mul_f32_e32 v105, 0x3d800000, v105
	v_add_f32_e32 v101, 1.0, v101
	v_cmp_gt_f32_e32 vcc, s68, v101
	s_nop 1
	v_cndmask_b32_e64 v113, 0, 32, vcc
	v_ldexp_f32 v101, v101, v113
	v_log_f32_e32 v101, v101
	s_nop 0
	v_mul_f32_e32 v113, 0x3f317217, v101
	v_fma_f32 v113, v101, s25, -v113
	v_fmac_f32_e32 v113, 0x3377d1cf, v101
	v_fmac_f32_e32 v113, 0x3f317217, v101
	v_cmp_lt_f32_e64 s[10:11], |v101|, s55
	s_nop 1
	v_cndmask_b32_e64 v101, v101, v113, s[10:11]
	v_cndmask_b32_e32 v113, 0, v212, vcc
	v_sub_f32_e32 v101, v101, v113
	v_sub_f32_e32 v101, v111, v101
	v_min_f32_e32 v111, 0, v106
	v_mul_f32_e64 v106, |v106|, s23
	v_exp_f32_e32 v106, v106
	v_mul_f32_e32 v101, 0x3d800000, v101
	v_add_f32_e32 v106, 1.0, v106
	v_cmp_gt_f32_e32 vcc, s68, v106
	s_nop 1
	v_cndmask_b32_e64 v113, 0, 32, vcc
	v_ldexp_f32 v106, v106, v113
	v_log_f32_e32 v106, v106
	s_nop 0
	v_mul_f32_e32 v113, 0x3f317217, v106
	v_fma_f32 v113, v106, s25, -v113
	v_fmac_f32_e32 v113, 0x3377d1cf, v106
	v_fmac_f32_e32 v113, 0x3f317217, v106
	v_cmp_lt_f32_e64 s[10:11], |v106|, s55
	s_nop 1
	v_cndmask_b32_e64 v106, v106, v113, s[10:11]
	v_cndmask_b32_e32 v113, 0, v212, vcc
	v_sub_f32_e32 v106, v106, v113
	v_sub_f32_e32 v106, v111, v106
	v_min_f32_e32 v111, 0, v102
	v_mul_f32_e64 v102, |v102|, s23
	v_exp_f32_e32 v102, v102
	v_mul_f32_e32 v106, 0x3d800000, v106
	v_add_f32_e32 v102, 1.0, v102
	v_cmp_gt_f32_e32 vcc, s68, v102
	s_nop 1
	v_cndmask_b32_e64 v113, 0, 32, vcc
	v_ldexp_f32 v102, v102, v113
	v_log_f32_e32 v102, v102
	s_nop 0
	v_mul_f32_e32 v113, 0x3f317217, v102
	v_fma_f32 v113, v102, s25, -v113
	v_fmac_f32_e32 v113, 0x3377d1cf, v102
	v_fmac_f32_e32 v113, 0x3f317217, v102
	v_cmp_lt_f32_e64 s[10:11], |v102|, s55
	s_nop 1
	v_cndmask_b32_e64 v102, v102, v113, s[10:11]
	v_cndmask_b32_e32 v113, 0, v212, vcc
	v_sub_f32_e32 v102, v102, v113
	v_sub_f32_e32 v102, v111, v102
	v_mul_f32_e32 v111, 0x3d800000, v102
	v_add_f32_e32 v102, v99, v107
	v_min_f32_e32 v107, 0, v102
	v_mul_f32_e64 v102, |v102|, s23
	v_exp_f32_e32 v102, v102
	s_nop 0
	v_add_f32_e32 v102, 1.0, v102
	v_cmp_gt_f32_e32 vcc, s68, v102
	s_nop 1
	v_cndmask_b32_e64 v113, 0, 32, vcc
	v_ldexp_f32 v102, v102, v113
	v_log_f32_e32 v102, v102
	s_nop 0
	v_mul_f32_e32 v113, 0x3f317217, v102
	v_fma_f32 v113, v102, s25, -v113
	v_fmac_f32_e32 v113, 0x3377d1cf, v102
	v_fmac_f32_e32 v113, 0x3f317217, v102
	v_cmp_lt_f32_e64 s[10:11], |v102|, s55
	s_nop 1
	v_cndmask_b32_e64 v102, v102, v113, s[10:11]
	v_cndmask_b32_e32 v113, 0, v212, vcc
	v_sub_f32_e32 v102, v102, v113
	v_sub_f32_e32 v102, v107, v102
	v_mul_f32_e32 v107, 0x3d800000, v102
	v_add_f32_e32 v102, v95, v103
	v_min_f32_e32 v103, 0, v102
	v_mul_f32_e64 v102, |v102|, s23
	v_exp_f32_e32 v102, v102
	s_nop 0
	v_add_f32_e32 v102, 1.0, v102
	v_cmp_gt_f32_e32 vcc, s68, v102
	s_nop 1
	v_cndmask_b32_e64 v113, 0, 32, vcc
	v_ldexp_f32 v102, v102, v113
	v_log_f32_e32 v102, v102
	s_nop 0
	v_mul_f32_e32 v113, 0x3f317217, v102
	v_fma_f32 v113, v102, s25, -v113
	v_fmac_f32_e32 v113, 0x3377d1cf, v102
	v_fmac_f32_e32 v113, 0x3f317217, v102
	v_cmp_lt_f32_e64 s[10:11], |v102|, s55
	s_nop 1
	v_cndmask_b32_e64 v102, v102, v113, s[10:11]
	v_cndmask_b32_e32 v113, 0, v212, vcc
	v_sub_f32_e32 v102, v102, v113
	v_sub_f32_e32 v102, v103, v102
	v_mul_f32_e32 v113, 0x3d800000, v102
	v_cvt_pk_bf16_f32 v102, v104, v105
	v_cvt_pk_bf16_f32 v103, v106, v107
	v_cvt_pk_bf16_f32 v104, v100, v101
	v_lshl_add_u64 v[100:101], s[16:17], 0, v[108:109]
	v_lshl_add_u64 v[100:101], v[150:151], 1, v[100:101]
	v_cvt_pk_bf16_f32 v105, v111, v113
	global_store_dwordx4 v[100:101], v[102:105], off
	s_mov_b64 s[10:11], 0

.LBB0_220:
	v_mov_b32_e32 v111, v110
	s_nop 0
	v_mov_b32_e32 v92, v110
	v_mov_b32_e32 v93, v110
	v_pk_mul_f32 v[90:91], v[90:91], v[92:93]
	v_pk_mul_f32 v[88:89], v[88:89], v[110:111]
	v_pk_mul_f32 v[86:87], v[86:87], v[92:93]
	v_pk_mul_f32 v[84:85], v[84:85], v[110:111]
	s_mov_b64 s[36:37], -1
	s_mov_b64 s[34:35], 0
	s_cmp_lt_i32 s54, 9
	s_mov_b64 s[10:11], 0
	s_cbranch_scc1 .LBB0_224
	s_cmp_eq_u32 s54, 9
	s_mov_b64 s[10:11], -1
	s_cbranch_scc0 .LBB0_223
	v_mov_b64_e32 v[92:93], v[192:193]
	v_mov_b64_e32 v[94:95], v[194:195]
	v_mov_b64_e32 v[96:97], v[188:189]
	v_mov_b64_e32 v[98:99], v[190:191]
	v_add_f32_e32 v92, v84, v92
	v_add_f32_e32 v96, v88, v96
	v_min_f32_e32 v100, 0, v96
	v_mul_f32_e64 v96, |v96|, s23
	v_exp_f32_e32 v96, v96
	v_add_f32_e32 v97, v89, v97
	v_add_f32_e32 v93, v85, v93
	v_add_f32_e32 v98, v90, v98
	v_add_f32_e32 v96, 1.0, v96
	v_cmp_gt_f32_e32 vcc, s68, v96
	v_add_f32_e32 v94, v86, v94
	s_nop 0
	v_cndmask_b32_e64 v101, 0, 32, vcc
	v_ldexp_f32 v96, v96, v101
	v_log_f32_e32 v96, v96
	s_nop 0
	v_mul_f32_e32 v101, 0x3f317217, v96
	v_fma_f32 v101, v96, s25, -v101
	v_fmac_f32_e32 v101, 0x3377d1cf, v96
	v_fmac_f32_e32 v101, 0x3f317217, v96
	v_cmp_lt_f32_e64 s[10:11], |v96|, s55
	s_nop 1
	v_cndmask_b32_e64 v96, v96, v101, s[10:11]
	v_cndmask_b32_e32 v101, 0, v212, vcc
	v_sub_f32_e32 v96, v96, v101
	v_sub_f32_e32 v96, v100, v96
	v_min_f32_e32 v100, 0, v92
	v_mul_f32_e64 v92, |v92|, s23
	v_exp_f32_e32 v92, v92
	v_mul_f32_e32 v96, 0x3d800000, v96
	v_add_f32_e32 v92, 1.0, v92
	v_cmp_gt_f32_e32 vcc, s68, v92
	s_nop 1
	v_cndmask_b32_e64 v101, 0, 32, vcc
	v_ldexp_f32 v92, v92, v101
	v_log_f32_e32 v92, v92
	s_nop 0
	v_mul_f32_e32 v101, 0x3f317217, v92
	v_fma_f32 v101, v92, s25, -v101
	v_fmac_f32_e32 v101, 0x3377d1cf, v92
	v_fmac_f32_e32 v101, 0x3f317217, v92
	v_cmp_lt_f32_e64 s[10:11], |v92|, s55
	s_nop 1
	v_cndmask_b32_e64 v92, v92, v101, s[10:11]
	v_cndmask_b32_e32 v101, 0, v212, vcc
	v_sub_f32_e32 v92, v92, v101
	v_sub_f32_e32 v92, v100, v92
	v_min_f32_e32 v100, 0, v97
	v_mul_f32_e64 v97, |v97|, s23
	v_exp_f32_e32 v97, v97
	v_mul_f32_e32 v92, 0x3d800000, v92
	v_add_f32_e32 v97, 1.0, v97
	v_cmp_gt_f32_e32 vcc, s68, v97
	s_nop 1
	v_cndmask_b32_e64 v101, 0, 32, vcc
	v_ldexp_f32 v97, v97, v101
	v_log_f32_e32 v97, v97
	s_nop 0
	v_mul_f32_e32 v101, 0x3f317217, v97
	v_fma_f32 v101, v97, s25, -v101
	v_fmac_f32_e32 v101, 0x3377d1cf, v97
	v_fmac_f32_e32 v101, 0x3f317217, v97
	v_cmp_lt_f32_e64 s[10:11], |v97|, s55
	s_nop 1
	v_cndmask_b32_e64 v97, v97, v101, s[10:11]
	v_cndmask_b32_e32 v101, 0, v212, vcc
	v_sub_f32_e32 v97, v97, v101
	v_sub_f32_e32 v97, v100, v97
	v_min_f32_e32 v100, 0, v93
	v_mul_f32_e64 v93, |v93|, s23
	v_exp_f32_e32 v93, v93
	v_mul_f32_e32 v97, 0x3d800000, v97
	v_add_f32_e32 v93, 1.0, v93
	v_cmp_gt_f32_e32 vcc, s68, v93
	s_nop 1
	v_cndmask_b32_e64 v101, 0, 32, vcc
	v_ldexp_f32 v93, v93, v101
	v_log_f32_e32 v93, v93
	s_nop 0
	v_mul_f32_e32 v101, 0x3f317217, v93
	v_fma_f32 v101, v93, s25, -v101
	v_fmac_f32_e32 v101, 0x3377d1cf, v93
	v_fmac_f32_e32 v101, 0x3f317217, v93
	v_cmp_lt_f32_e64 s[10:11], |v93|, s55
	s_nop 1
	v_cndmask_b32_e64 v93, v93, v101, s[10:11]
	v_cndmask_b32_e32 v101, 0, v212, vcc
	v_sub_f32_e32 v93, v93, v101
	v_sub_f32_e32 v93, v100, v93
	v_min_f32_e32 v100, 0, v98
	v_mul_f32_e64 v98, |v98|, s23
	v_exp_f32_e32 v98, v98
	v_mul_f32_e32 v93, 0x3d800000, v93
	v_add_f32_e32 v98, 1.0, v98
	v_cmp_gt_f32_e32 vcc, s68, v98
	s_nop 1
	v_cndmask_b32_e64 v101, 0, 32, vcc
	v_ldexp_f32 v98, v98, v101
	v_log_f32_e32 v98, v98
	s_nop 0
	v_mul_f32_e32 v101, 0x3f317217, v98
	v_fma_f32 v101, v98, s25, -v101
	v_fmac_f32_e32 v101, 0x3377d1cf, v98
	v_fmac_f32_e32 v101, 0x3f317217, v98
	v_cmp_lt_f32_e64 s[10:11], |v98|, s55
	s_nop 1
	v_cndmask_b32_e64 v98, v98, v101, s[10:11]
	v_cndmask_b32_e32 v101, 0, v212, vcc
	v_sub_f32_e32 v98, v98, v101
	v_sub_f32_e32 v98, v100, v98
	v_min_f32_e32 v100, 0, v94
	v_mul_f32_e64 v94, |v94|, s23
	v_exp_f32_e32 v94, v94
	v_mul_f32_e32 v98, 0x3d800000, v98
	v_add_f32_e32 v94, 1.0, v94
	v_cmp_gt_f32_e32 vcc, s68, v94
	s_nop 1
	v_cndmask_b32_e64 v101, 0, 32, vcc
	v_ldexp_f32 v94, v94, v101
	v_log_f32_e32 v94, v94
	s_nop 0
	v_mul_f32_e32 v101, 0x3f317217, v94
	v_fma_f32 v101, v94, s25, -v101
	v_fmac_f32_e32 v101, 0x3377d1cf, v94
	v_fmac_f32_e32 v101, 0x3f317217, v94
	v_cmp_lt_f32_e64 s[10:11], |v94|, s55
	s_nop 1
	v_cndmask_b32_e64 v94, v94, v101, s[10:11]
	v_cndmask_b32_e32 v101, 0, v212, vcc
	v_sub_f32_e32 v94, v94, v101
	v_sub_f32_e32 v94, v100, v94
	v_mul_f32_e32 v100, 0x3d800000, v94
	v_add_f32_e32 v94, v91, v99
	v_min_f32_e32 v99, 0, v94
	v_mul_f32_e64 v94, |v94|, s23
	v_exp_f32_e32 v94, v94
	s_nop 0
	v_add_f32_e32 v94, 1.0, v94
	v_cmp_gt_f32_e32 vcc, s68, v94
	s_nop 1
	v_cndmask_b32_e64 v101, 0, 32, vcc
	v_ldexp_f32 v94, v94, v101
	v_log_f32_e32 v94, v94
	s_nop 0
	v_mul_f32_e32 v101, 0x3f317217, v94
	v_fma_f32 v101, v94, s25, -v101
	v_fmac_f32_e32 v101, 0x3377d1cf, v94
	v_fmac_f32_e32 v101, 0x3f317217, v94
	v_cmp_lt_f32_e64 s[10:11], |v94|, s55
	s_nop 1
	v_cndmask_b32_e64 v94, v94, v101, s[10:11]
	v_cndmask_b32_e32 v101, 0, v212, vcc
	v_sub_f32_e32 v94, v94, v101
	v_sub_f32_e32 v94, v99, v94
	v_mul_f32_e32 v99, 0x3d800000, v94
	v_add_f32_e32 v94, v87, v95
	v_min_f32_e32 v95, 0, v94
	v_mul_f32_e64 v94, |v94|, s23
	v_exp_f32_e32 v94, v94
	s_nop 0
	v_add_f32_e32 v94, 1.0, v94
	v_cmp_gt_f32_e32 vcc, s68, v94
	s_nop 1
	v_cndmask_b32_e64 v101, 0, 32, vcc
	v_ldexp_f32 v94, v94, v101
	v_log_f32_e32 v94, v94
	s_nop 0
	v_mul_f32_e32 v101, 0x3f317217, v94
	v_fma_f32 v101, v94, s25, -v101
	v_fmac_f32_e32 v101, 0x3377d1cf, v94
	v_fmac_f32_e32 v101, 0x3f317217, v94
	v_cmp_lt_f32_e64 s[10:11], |v94|, s55
	s_nop 1
	v_cndmask_b32_e64 v94, v94, v101, s[10:11]
	v_cndmask_b32_e32 v101, 0, v212, vcc
	v_sub_f32_e32 v94, v94, v101
	v_sub_f32_e32 v94, v95, v94
	v_mul_f32_e32 v101, 0x3d800000, v94
	v_cvt_pk_bf16_f32 v94, v96, v97
	v_cvt_pk_bf16_f32 v95, v98, v99
	v_cvt_pk_bf16_f32 v96, v92, v93
	v_lshl_add_u64 v[92:93], s[16:17], 0, v[108:109]
	v_lshl_add_u64 v[92:93], v[150:151], 1, v[92:93]
	v_cvt_pk_bf16_f32 v97, v100, v101
	global_store_dwordx4 v[92:93], v[94:97], off offset:256
	s_mov_b64 s[10:11], 0

.LBB0_232:
	ds_read_b32 v94, v176 offset:192
	v_add_u32_e32 v96, 48, v152
	v_ashrrev_i32_e32 v97, 31, v96
	v_lshlrev_b64 v[92:93], 9, v[96:97]
	s_mov_b64 s[36:37], -1
	s_waitcnt lgkmcnt(0)
	v_pk_mul_f32 v[82:83], v[82:83], v[94:95] op_sel_hi:[1,0]
	v_pk_mul_f32 v[80:81], v[80:81], v[94:95] op_sel_hi:[1,0]
	v_pk_mul_f32 v[78:79], v[78:79], v[94:95] op_sel_hi:[1,0]
	v_pk_mul_f32 v[76:77], v[76:77], v[94:95] op_sel_hi:[1,0]
	s_mov_b64 s[34:35], 0
	s_cmp_lt_i32 s54, 9
	s_mov_b64 s[10:11], 0
	s_cbranch_scc1 .LBB0_238
	s_cmp_eq_u32 s54, 9
	s_mov_b64 s[10:11], -1
	s_cbranch_scc0 .LBB0_235
	v_mov_b64_e32 v[84:85], v[184:185]
	v_mov_b64_e32 v[86:87], v[186:187]
	v_mov_b64_e32 v[88:89], v[180:181]
	v_mov_b64_e32 v[90:91], v[182:183]
	v_add_f32_e32 v84, v76, v84
	v_add_f32_e32 v88, v80, v88
	v_min_f32_e32 v95, 0, v88
	v_mul_f32_e64 v88, |v88|, s23
	v_exp_f32_e32 v88, v88
	v_add_f32_e32 v89, v81, v89
	v_add_f32_e32 v85, v77, v85
	v_add_f32_e32 v90, v82, v90
	v_add_f32_e32 v88, 1.0, v88
	v_cmp_gt_f32_e32 vcc, s68, v88
	v_add_f32_e32 v86, v78, v86
	s_nop 0
	v_cndmask_b32_e64 v97, 0, 32, vcc
	v_ldexp_f32 v88, v88, v97
	v_log_f32_e32 v88, v88
	s_nop 0
	v_mul_f32_e32 v97, 0x3f317217, v88
	v_fma_f32 v97, v88, s25, -v97
	v_fmac_f32_e32 v97, 0x3377d1cf, v88
	v_fmac_f32_e32 v97, 0x3f317217, v88
	v_cmp_lt_f32_e64 s[10:11], |v88|, s55
	s_nop 1
	v_cndmask_b32_e64 v88, v88, v97, s[10:11]
	v_cndmask_b32_e32 v97, 0, v212, vcc
	v_sub_f32_e32 v88, v88, v97
	v_sub_f32_e32 v88, v95, v88
	v_min_f32_e32 v95, 0, v84
	v_mul_f32_e64 v84, |v84|, s23
	v_exp_f32_e32 v84, v84
	v_mul_f32_e32 v88, 0x3d800000, v88
	v_add_f32_e32 v84, 1.0, v84
	v_cmp_gt_f32_e32 vcc, s68, v84
	s_nop 1
	v_cndmask_b32_e64 v97, 0, 32, vcc
	v_ldexp_f32 v84, v84, v97
	v_log_f32_e32 v84, v84
	s_nop 0
	v_mul_f32_e32 v97, 0x3f317217, v84
	v_fma_f32 v97, v84, s25, -v97
	v_fmac_f32_e32 v97, 0x3377d1cf, v84
	v_fmac_f32_e32 v97, 0x3f317217, v84
	v_cmp_lt_f32_e64 s[10:11], |v84|, s55
	s_nop 1
	v_cndmask_b32_e64 v84, v84, v97, s[10:11]
	v_cndmask_b32_e32 v97, 0, v212, vcc
	v_sub_f32_e32 v84, v84, v97
	v_sub_f32_e32 v84, v95, v84
	v_min_f32_e32 v95, 0, v89
	v_mul_f32_e64 v89, |v89|, s23
	v_exp_f32_e32 v89, v89
	v_mul_f32_e32 v84, 0x3d800000, v84
	v_add_f32_e32 v89, 1.0, v89
	v_cmp_gt_f32_e32 vcc, s68, v89
	s_nop 1
	v_cndmask_b32_e64 v97, 0, 32, vcc
	v_ldexp_f32 v89, v89, v97
	v_log_f32_e32 v89, v89
	s_nop 0
	v_mul_f32_e32 v97, 0x3f317217, v89
	v_fma_f32 v97, v89, s25, -v97
	v_fmac_f32_e32 v97, 0x3377d1cf, v89
	v_fmac_f32_e32 v97, 0x3f317217, v89
	v_cmp_lt_f32_e64 s[10:11], |v89|, s55
	s_nop 1
	v_cndmask_b32_e64 v89, v89, v97, s[10:11]
	v_cndmask_b32_e32 v97, 0, v212, vcc
	v_sub_f32_e32 v89, v89, v97
	v_sub_f32_e32 v89, v95, v89
	v_min_f32_e32 v95, 0, v85
	v_mul_f32_e64 v85, |v85|, s23
	v_exp_f32_e32 v85, v85
	v_mul_f32_e32 v89, 0x3d800000, v89
	v_add_f32_e32 v85, 1.0, v85
	v_cmp_gt_f32_e32 vcc, s68, v85
	s_nop 1
	v_cndmask_b32_e64 v97, 0, 32, vcc
	v_ldexp_f32 v85, v85, v97
	v_log_f32_e32 v85, v85
	s_nop 0
	v_mul_f32_e32 v97, 0x3f317217, v85
	v_fma_f32 v97, v85, s25, -v97
	v_fmac_f32_e32 v97, 0x3377d1cf, v85
	v_fmac_f32_e32 v97, 0x3f317217, v85
	v_cmp_lt_f32_e64 s[10:11], |v85|, s55
	s_nop 1
	v_cndmask_b32_e64 v85, v85, v97, s[10:11]
	v_cndmask_b32_e32 v97, 0, v212, vcc
	v_sub_f32_e32 v85, v85, v97
	v_sub_f32_e32 v85, v95, v85
	v_min_f32_e32 v95, 0, v90
	v_mul_f32_e64 v90, |v90|, s23
	v_exp_f32_e32 v90, v90
	v_mul_f32_e32 v85, 0x3d800000, v85
	v_add_f32_e32 v90, 1.0, v90
	v_cmp_gt_f32_e32 vcc, s68, v90
	s_nop 1
	v_cndmask_b32_e64 v97, 0, 32, vcc
	v_ldexp_f32 v90, v90, v97
	v_log_f32_e32 v90, v90
	s_nop 0
	v_mul_f32_e32 v97, 0x3f317217, v90
	v_fma_f32 v97, v90, s25, -v97
	v_fmac_f32_e32 v97, 0x3377d1cf, v90
	v_fmac_f32_e32 v97, 0x3f317217, v90
	v_cmp_lt_f32_e64 s[10:11], |v90|, s55
	s_nop 1
	v_cndmask_b32_e64 v90, v90, v97, s[10:11]
	v_cndmask_b32_e32 v97, 0, v212, vcc
	v_sub_f32_e32 v90, v90, v97
	v_sub_f32_e32 v90, v95, v90
	v_min_f32_e32 v95, 0, v86
	v_mul_f32_e64 v86, |v86|, s23
	v_exp_f32_e32 v86, v86
	v_mul_f32_e32 v90, 0x3d800000, v90
	v_add_f32_e32 v86, 1.0, v86
	v_cmp_gt_f32_e32 vcc, s68, v86
	s_nop 1
	v_cndmask_b32_e64 v97, 0, 32, vcc
	v_ldexp_f32 v86, v86, v97
	v_log_f32_e32 v86, v86
	s_nop 0
	v_mul_f32_e32 v97, 0x3f317217, v86
	v_fma_f32 v97, v86, s25, -v97
	v_fmac_f32_e32 v97, 0x3377d1cf, v86
	v_fmac_f32_e32 v97, 0x3f317217, v86
	v_cmp_lt_f32_e64 s[10:11], |v86|, s55
	s_nop 1
	v_cndmask_b32_e64 v86, v86, v97, s[10:11]
	v_cndmask_b32_e32 v97, 0, v212, vcc
	v_sub_f32_e32 v86, v86, v97
	v_sub_f32_e32 v86, v95, v86
	v_mul_f32_e32 v95, 0x3d800000, v86
	v_add_f32_e32 v86, v83, v91
	v_min_f32_e32 v91, 0, v86
	v_mul_f32_e64 v86, |v86|, s23
	v_exp_f32_e32 v86, v86
	s_nop 0
	v_add_f32_e32 v86, 1.0, v86
	v_cmp_gt_f32_e32 vcc, s68, v86
	s_nop 1
	v_cndmask_b32_e64 v97, 0, 32, vcc
	v_ldexp_f32 v86, v86, v97
	v_log_f32_e32 v86, v86
	s_nop 0
	v_mul_f32_e32 v97, 0x3f317217, v86
	v_fma_f32 v97, v86, s25, -v97
	v_fmac_f32_e32 v97, 0x3377d1cf, v86
	v_fmac_f32_e32 v97, 0x3f317217, v86
	v_cmp_lt_f32_e64 s[10:11], |v86|, s55
	s_nop 1
	v_cndmask_b32_e64 v86, v86, v97, s[10:11]
	v_cndmask_b32_e32 v97, 0, v212, vcc
	v_sub_f32_e32 v86, v86, v97
	v_sub_f32_e32 v86, v91, v86
	v_mul_f32_e32 v91, 0x3d800000, v86
	v_add_f32_e32 v86, v79, v87
	v_min_f32_e32 v87, 0, v86
	v_mul_f32_e64 v86, |v86|, s23
	v_exp_f32_e32 v86, v86
	s_nop 0
	v_add_f32_e32 v86, 1.0, v86
	v_cmp_gt_f32_e32 vcc, s68, v86
	s_nop 1
	v_cndmask_b32_e64 v97, 0, 32, vcc
	v_ldexp_f32 v86, v86, v97
	v_log_f32_e32 v86, v86
	s_nop 0
	v_mul_f32_e32 v97, 0x3f317217, v86
	v_fma_f32 v97, v86, s25, -v97
	v_fmac_f32_e32 v97, 0x3377d1cf, v86
	v_fmac_f32_e32 v97, 0x3f317217, v86
	v_cmp_lt_f32_e64 s[10:11], |v86|, s55
	s_nop 1
	v_cndmask_b32_e64 v86, v86, v97, s[10:11]
	v_cndmask_b32_e32 v97, 0, v212, vcc
	v_sub_f32_e32 v86, v86, v97
	v_sub_f32_e32 v86, v87, v86
	v_mul_f32_e32 v97, 0x3d800000, v86
	v_cvt_pk_bf16_f32 v86, v88, v89
	v_cvt_pk_bf16_f32 v87, v90, v91
	v_cvt_pk_bf16_f32 v88, v84, v85
	v_lshl_add_u64 v[84:85], s[16:17], 0, v[92:93]
	v_lshl_add_u64 v[84:85], v[150:151], 1, v[84:85]
	v_cvt_pk_bf16_f32 v89, v95, v97
	global_store_dwordx4 v[84:85], v[86:89], off
	s_mov_b64 s[10:11], 0

.LBB0_248:
	v_mov_b32_e32 v95, v94
	s_nop 0
	v_mov_b32_e32 v76, v94
	v_mov_b32_e32 v77, v94
	v_pk_mul_f32 v[74:75], v[74:75], v[76:77]
	v_pk_mul_f32 v[72:73], v[72:73], v[94:95]
	v_pk_mul_f32 v[70:71], v[70:71], v[76:77]
	v_pk_mul_f32 v[68:69], v[68:69], v[94:95]
	s_mov_b64 s[36:37], -1
	s_mov_b64 s[34:35], 0
	s_cmp_lt_i32 s54, 9
	s_mov_b64 s[10:11], 0
	s_cbranch_scc1 .LBB0_252
	s_cmp_eq_u32 s54, 9
	s_mov_b64 s[10:11], -1
	s_cbranch_scc0 .LBB0_251
	v_mov_b64_e32 v[76:77], v[192:193]
	v_mov_b64_e32 v[78:79], v[194:195]
	v_mov_b64_e32 v[80:81], v[188:189]
	v_mov_b64_e32 v[82:83], v[190:191]
	v_add_f32_e32 v76, v68, v76
	v_add_f32_e32 v80, v72, v80
	v_min_f32_e32 v84, 0, v80
	v_mul_f32_e64 v80, |v80|, s23
	v_exp_f32_e32 v80, v80
	v_add_f32_e32 v81, v73, v81
	v_add_f32_e32 v77, v69, v77
	v_add_f32_e32 v82, v74, v82
	v_add_f32_e32 v80, 1.0, v80
	v_cmp_gt_f32_e32 vcc, s68, v80
	v_add_f32_e32 v78, v70, v78
	s_nop 0
	v_cndmask_b32_e64 v85, 0, 32, vcc
	v_ldexp_f32 v80, v80, v85
	v_log_f32_e32 v80, v80
	s_nop 0
	v_mul_f32_e32 v85, 0x3f317217, v80
	v_fma_f32 v85, v80, s25, -v85
	v_fmac_f32_e32 v85, 0x3377d1cf, v80
	v_fmac_f32_e32 v85, 0x3f317217, v80
	v_cmp_lt_f32_e64 s[10:11], |v80|, s55
	s_nop 1
	v_cndmask_b32_e64 v80, v80, v85, s[10:11]
	v_cndmask_b32_e32 v85, 0, v212, vcc
	v_sub_f32_e32 v80, v80, v85
	v_sub_f32_e32 v80, v84, v80
	v_min_f32_e32 v84, 0, v76
	v_mul_f32_e64 v76, |v76|, s23
	v_exp_f32_e32 v76, v76
	v_mul_f32_e32 v80, 0x3d800000, v80
	v_add_f32_e32 v76, 1.0, v76
	v_cmp_gt_f32_e32 vcc, s68, v76
	s_nop 1
	v_cndmask_b32_e64 v85, 0, 32, vcc
	v_ldexp_f32 v76, v76, v85
	v_log_f32_e32 v76, v76
	s_nop 0
	v_mul_f32_e32 v85, 0x3f317217, v76
	v_fma_f32 v85, v76, s25, -v85
	v_fmac_f32_e32 v85, 0x3377d1cf, v76
	v_fmac_f32_e32 v85, 0x3f317217, v76
	v_cmp_lt_f32_e64 s[10:11], |v76|, s55
	s_nop 1
	v_cndmask_b32_e64 v76, v76, v85, s[10:11]
	v_cndmask_b32_e32 v85, 0, v212, vcc
	v_sub_f32_e32 v76, v76, v85
	v_sub_f32_e32 v76, v84, v76
	v_min_f32_e32 v84, 0, v81
	v_mul_f32_e64 v81, |v81|, s23
	v_exp_f32_e32 v81, v81
	v_mul_f32_e32 v76, 0x3d800000, v76
	v_add_f32_e32 v81, 1.0, v81
	v_cmp_gt_f32_e32 vcc, s68, v81
	s_nop 1
	v_cndmask_b32_e64 v85, 0, 32, vcc
	v_ldexp_f32 v81, v81, v85
	v_log_f32_e32 v81, v81
	s_nop 0
	v_mul_f32_e32 v85, 0x3f317217, v81
	v_fma_f32 v85, v81, s25, -v85
	v_fmac_f32_e32 v85, 0x3377d1cf, v81
	v_fmac_f32_e32 v85, 0x3f317217, v81
	v_cmp_lt_f32_e64 s[10:11], |v81|, s55
	s_nop 1
	v_cndmask_b32_e64 v81, v81, v85, s[10:11]
	v_cndmask_b32_e32 v85, 0, v212, vcc
	v_sub_f32_e32 v81, v81, v85
	v_sub_f32_e32 v81, v84, v81
	v_min_f32_e32 v84, 0, v77
	v_mul_f32_e64 v77, |v77|, s23
	v_exp_f32_e32 v77, v77
	v_mul_f32_e32 v81, 0x3d800000, v81
	v_add_f32_e32 v77, 1.0, v77
	v_cmp_gt_f32_e32 vcc, s68, v77
	s_nop 1
	v_cndmask_b32_e64 v85, 0, 32, vcc
	v_ldexp_f32 v77, v77, v85
	v_log_f32_e32 v77, v77
	s_nop 0
	v_mul_f32_e32 v85, 0x3f317217, v77
	v_fma_f32 v85, v77, s25, -v85
	v_fmac_f32_e32 v85, 0x3377d1cf, v77
	v_fmac_f32_e32 v85, 0x3f317217, v77
	v_cmp_lt_f32_e64 s[10:11], |v77|, s55
	s_nop 1
	v_cndmask_b32_e64 v77, v77, v85, s[10:11]
	v_cndmask_b32_e32 v85, 0, v212, vcc
	v_sub_f32_e32 v77, v77, v85
	v_sub_f32_e32 v77, v84, v77
	v_min_f32_e32 v84, 0, v82
	v_mul_f32_e64 v82, |v82|, s23
	v_exp_f32_e32 v82, v82
	v_mul_f32_e32 v77, 0x3d800000, v77
	v_add_f32_e32 v82, 1.0, v82
	v_cmp_gt_f32_e32 vcc, s68, v82
	s_nop 1
	v_cndmask_b32_e64 v85, 0, 32, vcc
	v_ldexp_f32 v82, v82, v85
	v_log_f32_e32 v82, v82
	s_nop 0
	v_mul_f32_e32 v85, 0x3f317217, v82
	v_fma_f32 v85, v82, s25, -v85
	v_fmac_f32_e32 v85, 0x3377d1cf, v82
	v_fmac_f32_e32 v85, 0x3f317217, v82
	v_cmp_lt_f32_e64 s[10:11], |v82|, s55
	s_nop 1
	v_cndmask_b32_e64 v82, v82, v85, s[10:11]
	v_cndmask_b32_e32 v85, 0, v212, vcc
	v_sub_f32_e32 v82, v82, v85
	v_sub_f32_e32 v82, v84, v82
	v_min_f32_e32 v84, 0, v78
	v_mul_f32_e64 v78, |v78|, s23
	v_exp_f32_e32 v78, v78
	v_mul_f32_e32 v82, 0x3d800000, v82
	v_add_f32_e32 v78, 1.0, v78
	v_cmp_gt_f32_e32 vcc, s68, v78
	s_nop 1
	v_cndmask_b32_e64 v85, 0, 32, vcc
	v_ldexp_f32 v78, v78, v85
	v_log_f32_e32 v78, v78
	s_nop 0
	v_mul_f32_e32 v85, 0x3f317217, v78
	v_fma_f32 v85, v78, s25, -v85
	v_fmac_f32_e32 v85, 0x3377d1cf, v78
	v_fmac_f32_e32 v85, 0x3f317217, v78
	v_cmp_lt_f32_e64 s[10:11], |v78|, s55
	s_nop 1
	v_cndmask_b32_e64 v78, v78, v85, s[10:11]
	v_cndmask_b32_e32 v85, 0, v212, vcc
	v_sub_f32_e32 v78, v78, v85
	v_sub_f32_e32 v78, v84, v78
	v_mul_f32_e32 v84, 0x3d800000, v78
	v_add_f32_e32 v78, v75, v83
	v_min_f32_e32 v83, 0, v78
	v_mul_f32_e64 v78, |v78|, s23
	v_exp_f32_e32 v78, v78
	s_nop 0
	v_add_f32_e32 v78, 1.0, v78
	v_cmp_gt_f32_e32 vcc, s68, v78
	s_nop 1
	v_cndmask_b32_e64 v85, 0, 32, vcc
	v_ldexp_f32 v78, v78, v85
	v_log_f32_e32 v78, v78
	s_nop 0
	v_mul_f32_e32 v85, 0x3f317217, v78
	v_fma_f32 v85, v78, s25, -v85
	v_fmac_f32_e32 v85, 0x3377d1cf, v78
	v_fmac_f32_e32 v85, 0x3f317217, v78
	v_cmp_lt_f32_e64 s[10:11], |v78|, s55
	s_nop 1
	v_cndmask_b32_e64 v78, v78, v85, s[10:11]
	v_cndmask_b32_e32 v85, 0, v212, vcc
	v_sub_f32_e32 v78, v78, v85
	v_sub_f32_e32 v78, v83, v78
	v_mul_f32_e32 v83, 0x3d800000, v78
	v_add_f32_e32 v78, v71, v79
	v_min_f32_e32 v79, 0, v78
	v_mul_f32_e64 v78, |v78|, s23
	v_exp_f32_e32 v78, v78
	s_nop 0
	v_add_f32_e32 v78, 1.0, v78
	v_cmp_gt_f32_e32 vcc, s68, v78
	s_nop 1
	v_cndmask_b32_e64 v85, 0, 32, vcc
	v_ldexp_f32 v78, v78, v85
	v_log_f32_e32 v78, v78
	s_nop 0
	v_mul_f32_e32 v85, 0x3f317217, v78
	v_fma_f32 v85, v78, s25, -v85
	v_fmac_f32_e32 v85, 0x3377d1cf, v78
	v_fmac_f32_e32 v85, 0x3f317217, v78
	v_cmp_lt_f32_e64 s[10:11], |v78|, s55
	s_nop 1
	v_cndmask_b32_e64 v78, v78, v85, s[10:11]
	v_cndmask_b32_e32 v85, 0, v212, vcc
	v_sub_f32_e32 v78, v78, v85
	v_sub_f32_e32 v78, v79, v78
	v_mul_f32_e32 v85, 0x3d800000, v78
	v_cvt_pk_bf16_f32 v78, v80, v81
	v_cvt_pk_bf16_f32 v79, v82, v83
	v_cvt_pk_bf16_f32 v80, v76, v77
	v_lshl_add_u64 v[76:77], s[16:17], 0, v[92:93]
	v_lshl_add_u64 v[76:77], v[150:151], 1, v[76:77]
	v_cvt_pk_bf16_f32 v81, v84, v85
	global_store_dwordx4 v[76:77], v[78:81], off offset:256
	s_mov_b64 s[10:11], 0

.LBB0_260:
	ds_read_b32 v78, v176 offset:512
	v_add_u32_e32 v80, 0x80, v152
	v_ashrrev_i32_e32 v81, 31, v80
	v_lshlrev_b64 v[76:77], 9, v[80:81]
	s_mov_b64 s[36:37], -1
	s_waitcnt lgkmcnt(0)
	v_pk_mul_f32 v[66:67], v[66:67], v[78:79] op_sel_hi:[1,0]
	v_pk_mul_f32 v[64:65], v[64:65], v[78:79] op_sel_hi:[1,0]
	v_pk_mul_f32 v[62:63], v[62:63], v[78:79] op_sel_hi:[1,0]
	v_pk_mul_f32 v[60:61], v[60:61], v[78:79] op_sel_hi:[1,0]
	s_mov_b64 s[34:35], 0
	s_cmp_lt_i32 s54, 9
	s_mov_b64 s[10:11], 0
	s_cbranch_scc1 .LBB0_266
	s_cmp_eq_u32 s54, 9
	s_mov_b64 s[10:11], -1
	s_cbranch_scc0 .LBB0_263
	v_mov_b64_e32 v[68:69], v[184:185]
	v_mov_b64_e32 v[70:71], v[186:187]
	v_mov_b64_e32 v[72:73], v[180:181]
	v_mov_b64_e32 v[74:75], v[182:183]
	v_add_f32_e32 v68, v60, v68
	v_add_f32_e32 v72, v64, v72
	v_min_f32_e32 v79, 0, v72
	v_mul_f32_e64 v72, |v72|, s23
	v_exp_f32_e32 v72, v72
	v_add_f32_e32 v73, v65, v73
	v_add_f32_e32 v69, v61, v69
	v_add_f32_e32 v74, v66, v74
	v_add_f32_e32 v72, 1.0, v72
	v_cmp_gt_f32_e32 vcc, s68, v72
	v_add_f32_e32 v70, v62, v70
	s_nop 0
	v_cndmask_b32_e64 v81, 0, 32, vcc
	v_ldexp_f32 v72, v72, v81
	v_log_f32_e32 v72, v72
	s_nop 0
	v_mul_f32_e32 v81, 0x3f317217, v72
	v_fma_f32 v81, v72, s25, -v81
	v_fmac_f32_e32 v81, 0x3377d1cf, v72
	v_fmac_f32_e32 v81, 0x3f317217, v72
	v_cmp_lt_f32_e64 s[10:11], |v72|, s55
	s_nop 1
	v_cndmask_b32_e64 v72, v72, v81, s[10:11]
	v_cndmask_b32_e32 v81, 0, v212, vcc
	v_sub_f32_e32 v72, v72, v81
	v_sub_f32_e32 v72, v79, v72
	v_min_f32_e32 v79, 0, v68
	v_mul_f32_e64 v68, |v68|, s23
	v_exp_f32_e32 v68, v68
	v_mul_f32_e32 v72, 0x3d800000, v72
	v_add_f32_e32 v68, 1.0, v68
	v_cmp_gt_f32_e32 vcc, s68, v68
	s_nop 1
	v_cndmask_b32_e64 v81, 0, 32, vcc
	v_ldexp_f32 v68, v68, v81
	v_log_f32_e32 v68, v68
	s_nop 0
	v_mul_f32_e32 v81, 0x3f317217, v68
	v_fma_f32 v81, v68, s25, -v81
	v_fmac_f32_e32 v81, 0x3377d1cf, v68
	v_fmac_f32_e32 v81, 0x3f317217, v68
	v_cmp_lt_f32_e64 s[10:11], |v68|, s55
	s_nop 1
	v_cndmask_b32_e64 v68, v68, v81, s[10:11]
	v_cndmask_b32_e32 v81, 0, v212, vcc
	v_sub_f32_e32 v68, v68, v81
	v_sub_f32_e32 v68, v79, v68
	v_min_f32_e32 v79, 0, v73
	v_mul_f32_e64 v73, |v73|, s23
	v_exp_f32_e32 v73, v73
	v_mul_f32_e32 v68, 0x3d800000, v68
	v_add_f32_e32 v73, 1.0, v73
	v_cmp_gt_f32_e32 vcc, s68, v73
	s_nop 1
	v_cndmask_b32_e64 v81, 0, 32, vcc
	v_ldexp_f32 v73, v73, v81
	v_log_f32_e32 v73, v73
	s_nop 0
	v_mul_f32_e32 v81, 0x3f317217, v73
	v_fma_f32 v81, v73, s25, -v81
	v_fmac_f32_e32 v81, 0x3377d1cf, v73
	v_fmac_f32_e32 v81, 0x3f317217, v73
	v_cmp_lt_f32_e64 s[10:11], |v73|, s55
	s_nop 1
	v_cndmask_b32_e64 v73, v73, v81, s[10:11]
	v_cndmask_b32_e32 v81, 0, v212, vcc
	v_sub_f32_e32 v73, v73, v81
	v_sub_f32_e32 v73, v79, v73
	v_min_f32_e32 v79, 0, v69
	v_mul_f32_e64 v69, |v69|, s23
	v_exp_f32_e32 v69, v69
	v_mul_f32_e32 v73, 0x3d800000, v73
	v_add_f32_e32 v69, 1.0, v69
	v_cmp_gt_f32_e32 vcc, s68, v69
	s_nop 1
	v_cndmask_b32_e64 v81, 0, 32, vcc
	v_ldexp_f32 v69, v69, v81
	v_log_f32_e32 v69, v69
	s_nop 0
	v_mul_f32_e32 v81, 0x3f317217, v69
	v_fma_f32 v81, v69, s25, -v81
	v_fmac_f32_e32 v81, 0x3377d1cf, v69
	v_fmac_f32_e32 v81, 0x3f317217, v69
	v_cmp_lt_f32_e64 s[10:11], |v69|, s55
	s_nop 1
	v_cndmask_b32_e64 v69, v69, v81, s[10:11]
	v_cndmask_b32_e32 v81, 0, v212, vcc
	v_sub_f32_e32 v69, v69, v81
	v_sub_f32_e32 v69, v79, v69
	v_min_f32_e32 v79, 0, v74
	v_mul_f32_e64 v74, |v74|, s23
	v_exp_f32_e32 v74, v74
	v_mul_f32_e32 v69, 0x3d800000, v69
	v_add_f32_e32 v74, 1.0, v74
	v_cmp_gt_f32_e32 vcc, s68, v74
	s_nop 1
	v_cndmask_b32_e64 v81, 0, 32, vcc
	v_ldexp_f32 v74, v74, v81
	v_log_f32_e32 v74, v74
	s_nop 0
	v_mul_f32_e32 v81, 0x3f317217, v74
	v_fma_f32 v81, v74, s25, -v81
	v_fmac_f32_e32 v81, 0x3377d1cf, v74
	v_fmac_f32_e32 v81, 0x3f317217, v74
	v_cmp_lt_f32_e64 s[10:11], |v74|, s55
	s_nop 1
	v_cndmask_b32_e64 v74, v74, v81, s[10:11]
	v_cndmask_b32_e32 v81, 0, v212, vcc
	v_sub_f32_e32 v74, v74, v81
	v_sub_f32_e32 v74, v79, v74
	v_min_f32_e32 v79, 0, v70
	v_mul_f32_e64 v70, |v70|, s23
	v_exp_f32_e32 v70, v70
	v_mul_f32_e32 v74, 0x3d800000, v74
	v_add_f32_e32 v70, 1.0, v70
	v_cmp_gt_f32_e32 vcc, s68, v70
	s_nop 1
	v_cndmask_b32_e64 v81, 0, 32, vcc
	v_ldexp_f32 v70, v70, v81
	v_log_f32_e32 v70, v70
	s_nop 0
	v_mul_f32_e32 v81, 0x3f317217, v70
	v_fma_f32 v81, v70, s25, -v81
	v_fmac_f32_e32 v81, 0x3377d1cf, v70
	v_fmac_f32_e32 v81, 0x3f317217, v70
	v_cmp_lt_f32_e64 s[10:11], |v70|, s55
	s_nop 1
	v_cndmask_b32_e64 v70, v70, v81, s[10:11]
	v_cndmask_b32_e32 v81, 0, v212, vcc
	v_sub_f32_e32 v70, v70, v81
	v_sub_f32_e32 v70, v79, v70
	v_mul_f32_e32 v79, 0x3d800000, v70
	v_add_f32_e32 v70, v67, v75
	v_min_f32_e32 v75, 0, v70
	v_mul_f32_e64 v70, |v70|, s23
	v_exp_f32_e32 v70, v70
	s_nop 0
	v_add_f32_e32 v70, 1.0, v70
	v_cmp_gt_f32_e32 vcc, s68, v70
	s_nop 1
	v_cndmask_b32_e64 v81, 0, 32, vcc
	v_ldexp_f32 v70, v70, v81
	v_log_f32_e32 v70, v70
	s_nop 0
	v_mul_f32_e32 v81, 0x3f317217, v70
	v_fma_f32 v81, v70, s25, -v81
	v_fmac_f32_e32 v81, 0x3377d1cf, v70
	v_fmac_f32_e32 v81, 0x3f317217, v70
	v_cmp_lt_f32_e64 s[10:11], |v70|, s55
	s_nop 1
	v_cndmask_b32_e64 v70, v70, v81, s[10:11]
	v_cndmask_b32_e32 v81, 0, v212, vcc
	v_sub_f32_e32 v70, v70, v81
	v_sub_f32_e32 v70, v75, v70
	v_mul_f32_e32 v75, 0x3d800000, v70
	v_add_f32_e32 v70, v63, v71
	v_min_f32_e32 v71, 0, v70
	v_mul_f32_e64 v70, |v70|, s23
	v_exp_f32_e32 v70, v70
	s_nop 0
	v_add_f32_e32 v70, 1.0, v70
	v_cmp_gt_f32_e32 vcc, s68, v70
	s_nop 1
	v_cndmask_b32_e64 v81, 0, 32, vcc
	v_ldexp_f32 v70, v70, v81
	v_log_f32_e32 v70, v70
	s_nop 0
	v_mul_f32_e32 v81, 0x3f317217, v70
	v_fma_f32 v81, v70, s25, -v81
	v_fmac_f32_e32 v81, 0x3377d1cf, v70
	v_fmac_f32_e32 v81, 0x3f317217, v70
	v_cmp_lt_f32_e64 s[10:11], |v70|, s55
	s_nop 1
	v_cndmask_b32_e64 v70, v70, v81, s[10:11]
	v_cndmask_b32_e32 v81, 0, v212, vcc
	v_sub_f32_e32 v70, v70, v81
	v_sub_f32_e32 v70, v71, v70
	v_mul_f32_e32 v81, 0x3d800000, v70
	v_cvt_pk_bf16_f32 v70, v72, v73
	v_cvt_pk_bf16_f32 v71, v74, v75
	v_cvt_pk_bf16_f32 v72, v68, v69
	v_lshl_add_u64 v[68:69], s[16:17], 0, v[76:77]
	v_lshl_add_u64 v[68:69], v[150:151], 1, v[68:69]
	v_cvt_pk_bf16_f32 v73, v79, v81
	global_store_dwordx4 v[68:69], v[70:73], off
	s_mov_b64 s[10:11], 0

.LBB0_276:
	v_mov_b32_e32 v79, v78
	s_nop 0
	v_mov_b32_e32 v60, v78
	v_mov_b32_e32 v61, v78
	v_pk_mul_f32 v[58:59], v[58:59], v[60:61]
	v_pk_mul_f32 v[56:57], v[56:57], v[78:79]
	v_pk_mul_f32 v[54:55], v[54:55], v[60:61]
	v_pk_mul_f32 v[52:53], v[52:53], v[78:79]
	s_mov_b64 s[36:37], -1
	s_mov_b64 s[34:35], 0
	s_cmp_lt_i32 s54, 9
	s_mov_b64 s[10:11], 0
	s_cbranch_scc1 .LBB0_280
	s_cmp_eq_u32 s54, 9
	s_mov_b64 s[10:11], -1
	s_cbranch_scc0 .LBB0_279
	v_mov_b64_e32 v[60:61], v[192:193]
	v_mov_b64_e32 v[62:63], v[194:195]
	v_mov_b64_e32 v[64:65], v[188:189]
	v_mov_b64_e32 v[66:67], v[190:191]
	v_add_f32_e32 v60, v52, v60
	v_add_f32_e32 v64, v56, v64
	v_min_f32_e32 v68, 0, v64
	v_mul_f32_e64 v64, |v64|, s23
	v_exp_f32_e32 v64, v64
	v_add_f32_e32 v65, v57, v65
	v_add_f32_e32 v61, v53, v61
	v_add_f32_e32 v66, v58, v66
	v_add_f32_e32 v64, 1.0, v64
	v_cmp_gt_f32_e32 vcc, s68, v64
	v_add_f32_e32 v62, v54, v62
	s_nop 0
	v_cndmask_b32_e64 v69, 0, 32, vcc
	v_ldexp_f32 v64, v64, v69
	v_log_f32_e32 v64, v64
	s_nop 0
	v_mul_f32_e32 v69, 0x3f317217, v64
	v_fma_f32 v69, v64, s25, -v69
	v_fmac_f32_e32 v69, 0x3377d1cf, v64
	v_fmac_f32_e32 v69, 0x3f317217, v64
	v_cmp_lt_f32_e64 s[10:11], |v64|, s55
	s_nop 1
	v_cndmask_b32_e64 v64, v64, v69, s[10:11]
	v_cndmask_b32_e32 v69, 0, v212, vcc
	v_sub_f32_e32 v64, v64, v69
	v_sub_f32_e32 v64, v68, v64
	v_min_f32_e32 v68, 0, v60
	v_mul_f32_e64 v60, |v60|, s23
	v_exp_f32_e32 v60, v60
	v_mul_f32_e32 v64, 0x3d800000, v64
	v_add_f32_e32 v60, 1.0, v60
	v_cmp_gt_f32_e32 vcc, s68, v60
	s_nop 1
	v_cndmask_b32_e64 v69, 0, 32, vcc
	v_ldexp_f32 v60, v60, v69
	v_log_f32_e32 v60, v60
	s_nop 0
	v_mul_f32_e32 v69, 0x3f317217, v60
	v_fma_f32 v69, v60, s25, -v69
	v_fmac_f32_e32 v69, 0x3377d1cf, v60
	v_fmac_f32_e32 v69, 0x3f317217, v60
	v_cmp_lt_f32_e64 s[10:11], |v60|, s55
	s_nop 1
	v_cndmask_b32_e64 v60, v60, v69, s[10:11]
	v_cndmask_b32_e32 v69, 0, v212, vcc
	v_sub_f32_e32 v60, v60, v69
	v_sub_f32_e32 v60, v68, v60
	v_min_f32_e32 v68, 0, v65
	v_mul_f32_e64 v65, |v65|, s23
	v_exp_f32_e32 v65, v65
	v_mul_f32_e32 v60, 0x3d800000, v60
	v_add_f32_e32 v65, 1.0, v65
	v_cmp_gt_f32_e32 vcc, s68, v65
	s_nop 1
	v_cndmask_b32_e64 v69, 0, 32, vcc
	v_ldexp_f32 v65, v65, v69
	v_log_f32_e32 v65, v65
	s_nop 0
	v_mul_f32_e32 v69, 0x3f317217, v65
	v_fma_f32 v69, v65, s25, -v69
	v_fmac_f32_e32 v69, 0x3377d1cf, v65
	v_fmac_f32_e32 v69, 0x3f317217, v65
	v_cmp_lt_f32_e64 s[10:11], |v65|, s55
	s_nop 1
	v_cndmask_b32_e64 v65, v65, v69, s[10:11]
	v_cndmask_b32_e32 v69, 0, v212, vcc
	v_sub_f32_e32 v65, v65, v69
	v_sub_f32_e32 v65, v68, v65
	v_min_f32_e32 v68, 0, v61
	v_mul_f32_e64 v61, |v61|, s23
	v_exp_f32_e32 v61, v61
	v_mul_f32_e32 v65, 0x3d800000, v65
	v_add_f32_e32 v61, 1.0, v61
	v_cmp_gt_f32_e32 vcc, s68, v61
	s_nop 1
	v_cndmask_b32_e64 v69, 0, 32, vcc
	v_ldexp_f32 v61, v61, v69
	v_log_f32_e32 v61, v61
	s_nop 0
	v_mul_f32_e32 v69, 0x3f317217, v61
	v_fma_f32 v69, v61, s25, -v69
	v_fmac_f32_e32 v69, 0x3377d1cf, v61
	v_fmac_f32_e32 v69, 0x3f317217, v61
	v_cmp_lt_f32_e64 s[10:11], |v61|, s55
	s_nop 1
	v_cndmask_b32_e64 v61, v61, v69, s[10:11]
	v_cndmask_b32_e32 v69, 0, v212, vcc
	v_sub_f32_e32 v61, v61, v69
	v_sub_f32_e32 v61, v68, v61
	v_min_f32_e32 v68, 0, v66
	v_mul_f32_e64 v66, |v66|, s23
	v_exp_f32_e32 v66, v66
	v_mul_f32_e32 v61, 0x3d800000, v61
	v_add_f32_e32 v66, 1.0, v66
	v_cmp_gt_f32_e32 vcc, s68, v66
	s_nop 1
	v_cndmask_b32_e64 v69, 0, 32, vcc
	v_ldexp_f32 v66, v66, v69
	v_log_f32_e32 v66, v66
	s_nop 0
	v_mul_f32_e32 v69, 0x3f317217, v66
	v_fma_f32 v69, v66, s25, -v69
	v_fmac_f32_e32 v69, 0x3377d1cf, v66
	v_fmac_f32_e32 v69, 0x3f317217, v66
	v_cmp_lt_f32_e64 s[10:11], |v66|, s55
	s_nop 1
	v_cndmask_b32_e64 v66, v66, v69, s[10:11]
	v_cndmask_b32_e32 v69, 0, v212, vcc
	v_sub_f32_e32 v66, v66, v69
	v_sub_f32_e32 v66, v68, v66
	v_min_f32_e32 v68, 0, v62
	v_mul_f32_e64 v62, |v62|, s23
	v_exp_f32_e32 v62, v62
	v_mul_f32_e32 v66, 0x3d800000, v66
	v_add_f32_e32 v62, 1.0, v62
	v_cmp_gt_f32_e32 vcc, s68, v62
	s_nop 1
	v_cndmask_b32_e64 v69, 0, 32, vcc
	v_ldexp_f32 v62, v62, v69
	v_log_f32_e32 v62, v62
	s_nop 0
	v_mul_f32_e32 v69, 0x3f317217, v62
	v_fma_f32 v69, v62, s25, -v69
	v_fmac_f32_e32 v69, 0x3377d1cf, v62
	v_fmac_f32_e32 v69, 0x3f317217, v62
	v_cmp_lt_f32_e64 s[10:11], |v62|, s55
	s_nop 1
	v_cndmask_b32_e64 v62, v62, v69, s[10:11]
	v_cndmask_b32_e32 v69, 0, v212, vcc
	v_sub_f32_e32 v62, v62, v69
	v_sub_f32_e32 v62, v68, v62
	v_mul_f32_e32 v68, 0x3d800000, v62
	v_add_f32_e32 v62, v59, v67
	v_min_f32_e32 v67, 0, v62
	v_mul_f32_e64 v62, |v62|, s23
	v_exp_f32_e32 v62, v62
	s_nop 0
	v_add_f32_e32 v62, 1.0, v62
	v_cmp_gt_f32_e32 vcc, s68, v62
	s_nop 1
	v_cndmask_b32_e64 v69, 0, 32, vcc
	v_ldexp_f32 v62, v62, v69
	v_log_f32_e32 v62, v62
	s_nop 0
	v_mul_f32_e32 v69, 0x3f317217, v62
	v_fma_f32 v69, v62, s25, -v69
	v_fmac_f32_e32 v69, 0x3377d1cf, v62
	v_fmac_f32_e32 v69, 0x3f317217, v62
	v_cmp_lt_f32_e64 s[10:11], |v62|, s55
	s_nop 1
	v_cndmask_b32_e64 v62, v62, v69, s[10:11]
	v_cndmask_b32_e32 v69, 0, v212, vcc
	v_sub_f32_e32 v62, v62, v69
	v_sub_f32_e32 v62, v67, v62
	v_mul_f32_e32 v67, 0x3d800000, v62
	v_add_f32_e32 v62, v55, v63
	v_min_f32_e32 v63, 0, v62
	v_mul_f32_e64 v62, |v62|, s23
	v_exp_f32_e32 v62, v62
	s_nop 0
	v_add_f32_e32 v62, 1.0, v62
	v_cmp_gt_f32_e32 vcc, s68, v62
	s_nop 1
	v_cndmask_b32_e64 v69, 0, 32, vcc
	v_ldexp_f32 v62, v62, v69
	v_log_f32_e32 v62, v62
	s_nop 0
	v_mul_f32_e32 v69, 0x3f317217, v62
	v_fma_f32 v69, v62, s25, -v69
	v_fmac_f32_e32 v69, 0x3377d1cf, v62
	v_fmac_f32_e32 v69, 0x3f317217, v62
	v_cmp_lt_f32_e64 s[10:11], |v62|, s55
	s_nop 1
	v_cndmask_b32_e64 v62, v62, v69, s[10:11]
	v_cndmask_b32_e32 v69, 0, v212, vcc
	v_sub_f32_e32 v62, v62, v69
	v_sub_f32_e32 v62, v63, v62
	v_mul_f32_e32 v69, 0x3d800000, v62
	v_cvt_pk_bf16_f32 v62, v64, v65
	v_cvt_pk_bf16_f32 v63, v66, v67
	v_cvt_pk_bf16_f32 v64, v60, v61
	v_lshl_add_u64 v[60:61], s[16:17], 0, v[76:77]
	v_lshl_add_u64 v[60:61], v[150:151], 1, v[60:61]
	v_cvt_pk_bf16_f32 v65, v68, v69
	global_store_dwordx4 v[60:61], v[62:65], off offset:256
	s_mov_b64 s[10:11], 0

.LBB0_288:
	ds_read_b32 v62, v176 offset:576
	v_add_u32_e32 v64, 0x90, v152
	v_ashrrev_i32_e32 v65, 31, v64
	v_lshlrev_b64 v[60:61], 9, v[64:65]
	s_mov_b64 s[36:37], -1
	s_waitcnt lgkmcnt(0)
	v_pk_mul_f32 v[50:51], v[50:51], v[62:63] op_sel_hi:[1,0]
	v_pk_mul_f32 v[48:49], v[48:49], v[62:63] op_sel_hi:[1,0]
	v_pk_mul_f32 v[46:47], v[46:47], v[62:63] op_sel_hi:[1,0]
	v_pk_mul_f32 v[44:45], v[44:45], v[62:63] op_sel_hi:[1,0]
	s_mov_b64 s[34:35], 0
	s_cmp_lt_i32 s54, 9
	s_mov_b64 s[10:11], 0
	s_cbranch_scc1 .LBB0_294
	s_cmp_eq_u32 s54, 9
	s_mov_b64 s[10:11], -1
	s_cbranch_scc0 .LBB0_291
	v_mov_b64_e32 v[52:53], v[184:185]
	v_mov_b64_e32 v[54:55], v[186:187]
	v_mov_b64_e32 v[56:57], v[180:181]
	v_mov_b64_e32 v[58:59], v[182:183]
	v_add_f32_e32 v52, v44, v52
	v_add_f32_e32 v56, v48, v56
	v_min_f32_e32 v63, 0, v56
	v_mul_f32_e64 v56, |v56|, s23
	v_exp_f32_e32 v56, v56
	v_add_f32_e32 v57, v49, v57
	v_add_f32_e32 v53, v45, v53
	v_add_f32_e32 v58, v50, v58
	v_add_f32_e32 v56, 1.0, v56
	v_cmp_gt_f32_e32 vcc, s68, v56
	v_add_f32_e32 v54, v46, v54
	s_nop 0
	v_cndmask_b32_e64 v65, 0, 32, vcc
	v_ldexp_f32 v56, v56, v65
	v_log_f32_e32 v56, v56
	s_nop 0
	v_mul_f32_e32 v65, 0x3f317217, v56
	v_fma_f32 v65, v56, s25, -v65
	v_fmac_f32_e32 v65, 0x3377d1cf, v56
	v_fmac_f32_e32 v65, 0x3f317217, v56
	v_cmp_lt_f32_e64 s[10:11], |v56|, s55
	s_nop 1
	v_cndmask_b32_e64 v56, v56, v65, s[10:11]
	v_cndmask_b32_e32 v65, 0, v212, vcc
	v_sub_f32_e32 v56, v56, v65
	v_sub_f32_e32 v56, v63, v56
	v_min_f32_e32 v63, 0, v52
	v_mul_f32_e64 v52, |v52|, s23
	v_exp_f32_e32 v52, v52
	v_mul_f32_e32 v56, 0x3d800000, v56
	v_add_f32_e32 v52, 1.0, v52
	v_cmp_gt_f32_e32 vcc, s68, v52
	s_nop 1
	v_cndmask_b32_e64 v65, 0, 32, vcc
	v_ldexp_f32 v52, v52, v65
	v_log_f32_e32 v52, v52
	s_nop 0
	v_mul_f32_e32 v65, 0x3f317217, v52
	v_fma_f32 v65, v52, s25, -v65
	v_fmac_f32_e32 v65, 0x3377d1cf, v52
	v_fmac_f32_e32 v65, 0x3f317217, v52
	v_cmp_lt_f32_e64 s[10:11], |v52|, s55
	s_nop 1
	v_cndmask_b32_e64 v52, v52, v65, s[10:11]
	v_cndmask_b32_e32 v65, 0, v212, vcc
	v_sub_f32_e32 v52, v52, v65
	v_sub_f32_e32 v52, v63, v52
	v_min_f32_e32 v63, 0, v57
	v_mul_f32_e64 v57, |v57|, s23
	v_exp_f32_e32 v57, v57
	v_mul_f32_e32 v52, 0x3d800000, v52
	v_add_f32_e32 v57, 1.0, v57
	v_cmp_gt_f32_e32 vcc, s68, v57
	s_nop 1
	v_cndmask_b32_e64 v65, 0, 32, vcc
	v_ldexp_f32 v57, v57, v65
	v_log_f32_e32 v57, v57
	s_nop 0
	v_mul_f32_e32 v65, 0x3f317217, v57
	v_fma_f32 v65, v57, s25, -v65
	v_fmac_f32_e32 v65, 0x3377d1cf, v57
	v_fmac_f32_e32 v65, 0x3f317217, v57
	v_cmp_lt_f32_e64 s[10:11], |v57|, s55
	s_nop 1
	v_cndmask_b32_e64 v57, v57, v65, s[10:11]
	v_cndmask_b32_e32 v65, 0, v212, vcc
	v_sub_f32_e32 v57, v57, v65
	v_sub_f32_e32 v57, v63, v57
	v_min_f32_e32 v63, 0, v53
	v_mul_f32_e64 v53, |v53|, s23
	v_exp_f32_e32 v53, v53
	v_mul_f32_e32 v57, 0x3d800000, v57
	v_add_f32_e32 v53, 1.0, v53
	v_cmp_gt_f32_e32 vcc, s68, v53
	s_nop 1
	v_cndmask_b32_e64 v65, 0, 32, vcc
	v_ldexp_f32 v53, v53, v65
	v_log_f32_e32 v53, v53
	s_nop 0
	v_mul_f32_e32 v65, 0x3f317217, v53
	v_fma_f32 v65, v53, s25, -v65
	v_fmac_f32_e32 v65, 0x3377d1cf, v53
	v_fmac_f32_e32 v65, 0x3f317217, v53
	v_cmp_lt_f32_e64 s[10:11], |v53|, s55
	s_nop 1
	v_cndmask_b32_e64 v53, v53, v65, s[10:11]
	v_cndmask_b32_e32 v65, 0, v212, vcc
	v_sub_f32_e32 v53, v53, v65
	v_sub_f32_e32 v53, v63, v53
	v_min_f32_e32 v63, 0, v58
	v_mul_f32_e64 v58, |v58|, s23
	v_exp_f32_e32 v58, v58
	v_mul_f32_e32 v53, 0x3d800000, v53
	v_add_f32_e32 v58, 1.0, v58
	v_cmp_gt_f32_e32 vcc, s68, v58
	s_nop 1
	v_cndmask_b32_e64 v65, 0, 32, vcc
	v_ldexp_f32 v58, v58, v65
	v_log_f32_e32 v58, v58
	s_nop 0
	v_mul_f32_e32 v65, 0x3f317217, v58
	v_fma_f32 v65, v58, s25, -v65
	v_fmac_f32_e32 v65, 0x3377d1cf, v58
	v_fmac_f32_e32 v65, 0x3f317217, v58
	v_cmp_lt_f32_e64 s[10:11], |v58|, s55
	s_nop 1
	v_cndmask_b32_e64 v58, v58, v65, s[10:11]
	v_cndmask_b32_e32 v65, 0, v212, vcc
	v_sub_f32_e32 v58, v58, v65
	v_sub_f32_e32 v58, v63, v58
	v_min_f32_e32 v63, 0, v54
	v_mul_f32_e64 v54, |v54|, s23
	v_exp_f32_e32 v54, v54
	v_mul_f32_e32 v58, 0x3d800000, v58
	v_add_f32_e32 v54, 1.0, v54
	v_cmp_gt_f32_e32 vcc, s68, v54
	s_nop 1
	v_cndmask_b32_e64 v65, 0, 32, vcc
	v_ldexp_f32 v54, v54, v65
	v_log_f32_e32 v54, v54
	s_nop 0
	v_mul_f32_e32 v65, 0x3f317217, v54
	v_fma_f32 v65, v54, s25, -v65
	v_fmac_f32_e32 v65, 0x3377d1cf, v54
	v_fmac_f32_e32 v65, 0x3f317217, v54
	v_cmp_lt_f32_e64 s[10:11], |v54|, s55
	s_nop 1
	v_cndmask_b32_e64 v54, v54, v65, s[10:11]
	v_cndmask_b32_e32 v65, 0, v212, vcc
	v_sub_f32_e32 v54, v54, v65
	v_sub_f32_e32 v54, v63, v54
	v_mul_f32_e32 v63, 0x3d800000, v54
	v_add_f32_e32 v54, v51, v59
	v_min_f32_e32 v59, 0, v54
	v_mul_f32_e64 v54, |v54|, s23
	v_exp_f32_e32 v54, v54
	s_nop 0
	v_add_f32_e32 v54, 1.0, v54
	v_cmp_gt_f32_e32 vcc, s68, v54
	s_nop 1
	v_cndmask_b32_e64 v65, 0, 32, vcc
	v_ldexp_f32 v54, v54, v65
	v_log_f32_e32 v54, v54
	s_nop 0
	v_mul_f32_e32 v65, 0x3f317217, v54
	v_fma_f32 v65, v54, s25, -v65
	v_fmac_f32_e32 v65, 0x3377d1cf, v54
	v_fmac_f32_e32 v65, 0x3f317217, v54
	v_cmp_lt_f32_e64 s[10:11], |v54|, s55
	s_nop 1
	v_cndmask_b32_e64 v54, v54, v65, s[10:11]
	v_cndmask_b32_e32 v65, 0, v212, vcc
	v_sub_f32_e32 v54, v54, v65
	v_sub_f32_e32 v54, v59, v54
	v_mul_f32_e32 v59, 0x3d800000, v54
	v_add_f32_e32 v54, v47, v55
	v_min_f32_e32 v55, 0, v54
	v_mul_f32_e64 v54, |v54|, s23
	v_exp_f32_e32 v54, v54
	s_nop 0
	v_add_f32_e32 v54, 1.0, v54
	v_cmp_gt_f32_e32 vcc, s68, v54
	s_nop 1
	v_cndmask_b32_e64 v65, 0, 32, vcc
	v_ldexp_f32 v54, v54, v65
	v_log_f32_e32 v54, v54
	s_nop 0
	v_mul_f32_e32 v65, 0x3f317217, v54
	v_fma_f32 v65, v54, s25, -v65
	v_fmac_f32_e32 v65, 0x3377d1cf, v54
	v_fmac_f32_e32 v65, 0x3f317217, v54
	v_cmp_lt_f32_e64 s[10:11], |v54|, s55
	s_nop 1
	v_cndmask_b32_e64 v54, v54, v65, s[10:11]
	v_cndmask_b32_e32 v65, 0, v212, vcc
	v_sub_f32_e32 v54, v54, v65
	v_sub_f32_e32 v54, v55, v54
	v_mul_f32_e32 v65, 0x3d800000, v54
	v_cvt_pk_bf16_f32 v54, v56, v57
	v_cvt_pk_bf16_f32 v55, v58, v59
	v_cvt_pk_bf16_f32 v56, v52, v53
	v_lshl_add_u64 v[52:53], s[16:17], 0, v[60:61]
	v_lshl_add_u64 v[52:53], v[150:151], 1, v[52:53]
	v_cvt_pk_bf16_f32 v57, v63, v65
	global_store_dwordx4 v[52:53], v[54:57], off
	s_mov_b64 s[10:11], 0

.LBB0_304:
	v_mov_b32_e32 v63, v62
	s_nop 0
	v_mov_b32_e32 v44, v62
	v_mov_b32_e32 v45, v62
	v_pk_mul_f32 v[42:43], v[42:43], v[44:45]
	v_pk_mul_f32 v[40:41], v[40:41], v[62:63]
	v_pk_mul_f32 v[38:39], v[38:39], v[44:45]
	v_pk_mul_f32 v[36:37], v[36:37], v[62:63]
	s_mov_b64 s[36:37], -1
	s_mov_b64 s[34:35], 0
	s_cmp_lt_i32 s54, 9
	s_mov_b64 s[10:11], 0
	s_cbranch_scc1 .LBB0_308
	s_cmp_eq_u32 s54, 9
	s_mov_b64 s[10:11], -1
	s_cbranch_scc0 .LBB0_307
	v_mov_b64_e32 v[44:45], v[192:193]
	v_mov_b64_e32 v[46:47], v[194:195]
	v_mov_b64_e32 v[48:49], v[188:189]
	v_mov_b64_e32 v[50:51], v[190:191]
	v_add_f32_e32 v44, v36, v44
	v_add_f32_e32 v48, v40, v48
	v_min_f32_e32 v52, 0, v48
	v_mul_f32_e64 v48, |v48|, s23
	v_exp_f32_e32 v48, v48
	v_add_f32_e32 v49, v41, v49
	v_add_f32_e32 v45, v37, v45
	v_add_f32_e32 v50, v42, v50
	v_add_f32_e32 v48, 1.0, v48
	v_cmp_gt_f32_e32 vcc, s68, v48
	v_add_f32_e32 v46, v38, v46
	s_nop 0
	v_cndmask_b32_e64 v53, 0, 32, vcc
	v_ldexp_f32 v48, v48, v53
	v_log_f32_e32 v48, v48
	s_nop 0
	v_mul_f32_e32 v53, 0x3f317217, v48
	v_fma_f32 v53, v48, s25, -v53
	v_fmac_f32_e32 v53, 0x3377d1cf, v48
	v_fmac_f32_e32 v53, 0x3f317217, v48
	v_cmp_lt_f32_e64 s[10:11], |v48|, s55
	s_nop 1
	v_cndmask_b32_e64 v48, v48, v53, s[10:11]
	v_cndmask_b32_e32 v53, 0, v212, vcc
	v_sub_f32_e32 v48, v48, v53
	v_sub_f32_e32 v48, v52, v48
	v_min_f32_e32 v52, 0, v44
	v_mul_f32_e64 v44, |v44|, s23
	v_exp_f32_e32 v44, v44
	v_mul_f32_e32 v48, 0x3d800000, v48
	v_add_f32_e32 v44, 1.0, v44
	v_cmp_gt_f32_e32 vcc, s68, v44
	s_nop 1
	v_cndmask_b32_e64 v53, 0, 32, vcc
	v_ldexp_f32 v44, v44, v53
	v_log_f32_e32 v44, v44
	s_nop 0
	v_mul_f32_e32 v53, 0x3f317217, v44
	v_fma_f32 v53, v44, s25, -v53
	v_fmac_f32_e32 v53, 0x3377d1cf, v44
	v_fmac_f32_e32 v53, 0x3f317217, v44
	v_cmp_lt_f32_e64 s[10:11], |v44|, s55
	s_nop 1
	v_cndmask_b32_e64 v44, v44, v53, s[10:11]
	v_cndmask_b32_e32 v53, 0, v212, vcc
	v_sub_f32_e32 v44, v44, v53
	v_sub_f32_e32 v44, v52, v44
	v_min_f32_e32 v52, 0, v49
	v_mul_f32_e64 v49, |v49|, s23
	v_exp_f32_e32 v49, v49
	v_mul_f32_e32 v44, 0x3d800000, v44
	v_add_f32_e32 v49, 1.0, v49
	v_cmp_gt_f32_e32 vcc, s68, v49
	s_nop 1
	v_cndmask_b32_e64 v53, 0, 32, vcc
	v_ldexp_f32 v49, v49, v53
	v_log_f32_e32 v49, v49
	s_nop 0
	v_mul_f32_e32 v53, 0x3f317217, v49
	v_fma_f32 v53, v49, s25, -v53
	v_fmac_f32_e32 v53, 0x3377d1cf, v49
	v_fmac_f32_e32 v53, 0x3f317217, v49
	v_cmp_lt_f32_e64 s[10:11], |v49|, s55
	s_nop 1
	v_cndmask_b32_e64 v49, v49, v53, s[10:11]
	v_cndmask_b32_e32 v53, 0, v212, vcc
	v_sub_f32_e32 v49, v49, v53
	v_sub_f32_e32 v49, v52, v49
	v_min_f32_e32 v52, 0, v45
	v_mul_f32_e64 v45, |v45|, s23
	v_exp_f32_e32 v45, v45
	v_mul_f32_e32 v49, 0x3d800000, v49
	v_add_f32_e32 v45, 1.0, v45
	v_cmp_gt_f32_e32 vcc, s68, v45
	s_nop 1
	v_cndmask_b32_e64 v53, 0, 32, vcc
	v_ldexp_f32 v45, v45, v53
	v_log_f32_e32 v45, v45
	s_nop 0
	v_mul_f32_e32 v53, 0x3f317217, v45
	v_fma_f32 v53, v45, s25, -v53
	v_fmac_f32_e32 v53, 0x3377d1cf, v45
	v_fmac_f32_e32 v53, 0x3f317217, v45
	v_cmp_lt_f32_e64 s[10:11], |v45|, s55
	s_nop 1
	v_cndmask_b32_e64 v45, v45, v53, s[10:11]
	v_cndmask_b32_e32 v53, 0, v212, vcc
	v_sub_f32_e32 v45, v45, v53
	v_sub_f32_e32 v45, v52, v45
	v_min_f32_e32 v52, 0, v50
	v_mul_f32_e64 v50, |v50|, s23
	v_exp_f32_e32 v50, v50
	v_mul_f32_e32 v45, 0x3d800000, v45
	v_add_f32_e32 v50, 1.0, v50
	v_cmp_gt_f32_e32 vcc, s68, v50
	s_nop 1
	v_cndmask_b32_e64 v53, 0, 32, vcc
	v_ldexp_f32 v50, v50, v53
	v_log_f32_e32 v50, v50
	s_nop 0
	v_mul_f32_e32 v53, 0x3f317217, v50
	v_fma_f32 v53, v50, s25, -v53
	v_fmac_f32_e32 v53, 0x3377d1cf, v50
	v_fmac_f32_e32 v53, 0x3f317217, v50
	v_cmp_lt_f32_e64 s[10:11], |v50|, s55
	s_nop 1
	v_cndmask_b32_e64 v50, v50, v53, s[10:11]
	v_cndmask_b32_e32 v53, 0, v212, vcc
	v_sub_f32_e32 v50, v50, v53
	v_sub_f32_e32 v50, v52, v50
	v_min_f32_e32 v52, 0, v46
	v_mul_f32_e64 v46, |v46|, s23
	v_exp_f32_e32 v46, v46
	v_mul_f32_e32 v50, 0x3d800000, v50
	v_add_f32_e32 v46, 1.0, v46
	v_cmp_gt_f32_e32 vcc, s68, v46
	s_nop 1
	v_cndmask_b32_e64 v53, 0, 32, vcc
	v_ldexp_f32 v46, v46, v53
	v_log_f32_e32 v46, v46
	s_nop 0
	v_mul_f32_e32 v53, 0x3f317217, v46
	v_fma_f32 v53, v46, s25, -v53
	v_fmac_f32_e32 v53, 0x3377d1cf, v46
	v_fmac_f32_e32 v53, 0x3f317217, v46
	v_cmp_lt_f32_e64 s[10:11], |v46|, s55
	s_nop 1
	v_cndmask_b32_e64 v46, v46, v53, s[10:11]
	v_cndmask_b32_e32 v53, 0, v212, vcc
	v_sub_f32_e32 v46, v46, v53
	v_sub_f32_e32 v46, v52, v46
	v_mul_f32_e32 v52, 0x3d800000, v46
	v_add_f32_e32 v46, v43, v51
	v_min_f32_e32 v51, 0, v46
	v_mul_f32_e64 v46, |v46|, s23
	v_exp_f32_e32 v46, v46
	s_nop 0
	v_add_f32_e32 v46, 1.0, v46
	v_cmp_gt_f32_e32 vcc, s68, v46
	s_nop 1
	v_cndmask_b32_e64 v53, 0, 32, vcc
	v_ldexp_f32 v46, v46, v53
	v_log_f32_e32 v46, v46
	s_nop 0
	v_mul_f32_e32 v53, 0x3f317217, v46
	v_fma_f32 v53, v46, s25, -v53
	v_fmac_f32_e32 v53, 0x3377d1cf, v46
	v_fmac_f32_e32 v53, 0x3f317217, v46
	v_cmp_lt_f32_e64 s[10:11], |v46|, s55
	s_nop 1
	v_cndmask_b32_e64 v46, v46, v53, s[10:11]
	v_cndmask_b32_e32 v53, 0, v212, vcc
	v_sub_f32_e32 v46, v46, v53
	v_sub_f32_e32 v46, v51, v46
	v_mul_f32_e32 v51, 0x3d800000, v46
	v_add_f32_e32 v46, v39, v47
	v_min_f32_e32 v47, 0, v46
	v_mul_f32_e64 v46, |v46|, s23
	v_exp_f32_e32 v46, v46
	s_nop 0
	v_add_f32_e32 v46, 1.0, v46
	v_cmp_gt_f32_e32 vcc, s68, v46
	s_nop 1
	v_cndmask_b32_e64 v53, 0, 32, vcc
	v_ldexp_f32 v46, v46, v53
	v_log_f32_e32 v46, v46
	s_nop 0
	v_mul_f32_e32 v53, 0x3f317217, v46
	v_fma_f32 v53, v46, s25, -v53
	v_fmac_f32_e32 v53, 0x3377d1cf, v46
	v_fmac_f32_e32 v53, 0x3f317217, v46
	v_cmp_lt_f32_e64 s[10:11], |v46|, s55
	s_nop 1
	v_cndmask_b32_e64 v46, v46, v53, s[10:11]
	v_cndmask_b32_e32 v53, 0, v212, vcc
	v_sub_f32_e32 v46, v46, v53
	v_sub_f32_e32 v46, v47, v46
	v_mul_f32_e32 v53, 0x3d800000, v46
	v_cvt_pk_bf16_f32 v46, v48, v49
	v_cvt_pk_bf16_f32 v47, v50, v51
	v_cvt_pk_bf16_f32 v48, v44, v45
	v_lshl_add_u64 v[44:45], s[16:17], 0, v[60:61]
	v_lshl_add_u64 v[44:45], v[150:151], 1, v[44:45]
	v_cvt_pk_bf16_f32 v49, v52, v53
	global_store_dwordx4 v[44:45], v[46:49], off offset:256
	s_mov_b64 s[10:11], 0

.LBB0_316:
	ds_read_b32 v46, v176 offset:640
	v_add_u32_e32 v48, 0xa0, v152
	v_ashrrev_i32_e32 v49, 31, v48
	v_lshlrev_b64 v[44:45], 9, v[48:49]
	s_mov_b64 s[36:37], -1
	s_waitcnt lgkmcnt(0)
	v_pk_mul_f32 v[34:35], v[34:35], v[46:47] op_sel_hi:[1,0]
	v_pk_mul_f32 v[32:33], v[32:33], v[46:47] op_sel_hi:[1,0]
	v_pk_mul_f32 v[30:31], v[30:31], v[46:47] op_sel_hi:[1,0]
	v_pk_mul_f32 v[28:29], v[28:29], v[46:47] op_sel_hi:[1,0]
	s_mov_b64 s[34:35], 0
	s_cmp_lt_i32 s54, 9
	s_mov_b64 s[10:11], 0
	s_cbranch_scc1 .LBB0_322
	s_cmp_eq_u32 s54, 9
	s_mov_b64 s[10:11], -1
	s_cbranch_scc0 .LBB0_319
	v_mov_b64_e32 v[36:37], v[184:185]
	v_mov_b64_e32 v[38:39], v[186:187]
	v_mov_b64_e32 v[40:41], v[180:181]
	v_mov_b64_e32 v[42:43], v[182:183]
	v_add_f32_e32 v36, v28, v36
	v_add_f32_e32 v40, v32, v40
	v_min_f32_e32 v47, 0, v40
	v_mul_f32_e64 v40, |v40|, s23
	v_exp_f32_e32 v40, v40
	v_add_f32_e32 v41, v33, v41
	v_add_f32_e32 v37, v29, v37
	v_add_f32_e32 v42, v34, v42
	v_add_f32_e32 v40, 1.0, v40
	v_cmp_gt_f32_e32 vcc, s68, v40
	v_add_f32_e32 v38, v30, v38
	s_nop 0
	v_cndmask_b32_e64 v49, 0, 32, vcc
	v_ldexp_f32 v40, v40, v49
	v_log_f32_e32 v40, v40
	s_nop 0
	v_mul_f32_e32 v49, 0x3f317217, v40
	v_fma_f32 v49, v40, s25, -v49
	v_fmac_f32_e32 v49, 0x3377d1cf, v40
	v_fmac_f32_e32 v49, 0x3f317217, v40
	v_cmp_lt_f32_e64 s[10:11], |v40|, s55
	s_nop 1
	v_cndmask_b32_e64 v40, v40, v49, s[10:11]
	v_cndmask_b32_e32 v49, 0, v212, vcc
	v_sub_f32_e32 v40, v40, v49
	v_sub_f32_e32 v40, v47, v40
	v_min_f32_e32 v47, 0, v36
	v_mul_f32_e64 v36, |v36|, s23
	v_exp_f32_e32 v36, v36
	v_mul_f32_e32 v40, 0x3d800000, v40
	v_add_f32_e32 v36, 1.0, v36
	v_cmp_gt_f32_e32 vcc, s68, v36
	s_nop 1
	v_cndmask_b32_e64 v49, 0, 32, vcc
	v_ldexp_f32 v36, v36, v49
	v_log_f32_e32 v36, v36
	s_nop 0
	v_mul_f32_e32 v49, 0x3f317217, v36
	v_fma_f32 v49, v36, s25, -v49
	v_fmac_f32_e32 v49, 0x3377d1cf, v36
	v_fmac_f32_e32 v49, 0x3f317217, v36
	v_cmp_lt_f32_e64 s[10:11], |v36|, s55
	s_nop 1
	v_cndmask_b32_e64 v36, v36, v49, s[10:11]
	v_cndmask_b32_e32 v49, 0, v212, vcc
	v_sub_f32_e32 v36, v36, v49
	v_sub_f32_e32 v36, v47, v36
	v_min_f32_e32 v47, 0, v41
	v_mul_f32_e64 v41, |v41|, s23
	v_exp_f32_e32 v41, v41
	v_mul_f32_e32 v36, 0x3d800000, v36
	v_add_f32_e32 v41, 1.0, v41
	v_cmp_gt_f32_e32 vcc, s68, v41
	s_nop 1
	v_cndmask_b32_e64 v49, 0, 32, vcc
	v_ldexp_f32 v41, v41, v49
	v_log_f32_e32 v41, v41
	s_nop 0
	v_mul_f32_e32 v49, 0x3f317217, v41
	v_fma_f32 v49, v41, s25, -v49
	v_fmac_f32_e32 v49, 0x3377d1cf, v41
	v_fmac_f32_e32 v49, 0x3f317217, v41
	v_cmp_lt_f32_e64 s[10:11], |v41|, s55
	s_nop 1
	v_cndmask_b32_e64 v41, v41, v49, s[10:11]
	v_cndmask_b32_e32 v49, 0, v212, vcc
	v_sub_f32_e32 v41, v41, v49
	v_sub_f32_e32 v41, v47, v41
	v_min_f32_e32 v47, 0, v37
	v_mul_f32_e64 v37, |v37|, s23
	v_exp_f32_e32 v37, v37
	v_mul_f32_e32 v41, 0x3d800000, v41
	v_add_f32_e32 v37, 1.0, v37
	v_cmp_gt_f32_e32 vcc, s68, v37
	s_nop 1
	v_cndmask_b32_e64 v49, 0, 32, vcc
	v_ldexp_f32 v37, v37, v49
	v_log_f32_e32 v37, v37
	s_nop 0
	v_mul_f32_e32 v49, 0x3f317217, v37
	v_fma_f32 v49, v37, s25, -v49
	v_fmac_f32_e32 v49, 0x3377d1cf, v37
	v_fmac_f32_e32 v49, 0x3f317217, v37
	v_cmp_lt_f32_e64 s[10:11], |v37|, s55
	s_nop 1
	v_cndmask_b32_e64 v37, v37, v49, s[10:11]
	v_cndmask_b32_e32 v49, 0, v212, vcc
	v_sub_f32_e32 v37, v37, v49
	v_sub_f32_e32 v37, v47, v37
	v_min_f32_e32 v47, 0, v42
	v_mul_f32_e64 v42, |v42|, s23
	v_exp_f32_e32 v42, v42
	v_mul_f32_e32 v37, 0x3d800000, v37
	v_add_f32_e32 v42, 1.0, v42
	v_cmp_gt_f32_e32 vcc, s68, v42
	s_nop 1
	v_cndmask_b32_e64 v49, 0, 32, vcc
	v_ldexp_f32 v42, v42, v49
	v_log_f32_e32 v42, v42
	s_nop 0
	v_mul_f32_e32 v49, 0x3f317217, v42
	v_fma_f32 v49, v42, s25, -v49
	v_fmac_f32_e32 v49, 0x3377d1cf, v42
	v_fmac_f32_e32 v49, 0x3f317217, v42
	v_cmp_lt_f32_e64 s[10:11], |v42|, s55
	s_nop 1
	v_cndmask_b32_e64 v42, v42, v49, s[10:11]
	v_cndmask_b32_e32 v49, 0, v212, vcc
	v_sub_f32_e32 v42, v42, v49
	v_sub_f32_e32 v42, v47, v42
	v_min_f32_e32 v47, 0, v38
	v_mul_f32_e64 v38, |v38|, s23
	v_exp_f32_e32 v38, v38
	v_mul_f32_e32 v42, 0x3d800000, v42
	v_add_f32_e32 v38, 1.0, v38
	v_cmp_gt_f32_e32 vcc, s68, v38
	s_nop 1
	v_cndmask_b32_e64 v49, 0, 32, vcc
	v_ldexp_f32 v38, v38, v49
	v_log_f32_e32 v38, v38
	s_nop 0
	v_mul_f32_e32 v49, 0x3f317217, v38
	v_fma_f32 v49, v38, s25, -v49
	v_fmac_f32_e32 v49, 0x3377d1cf, v38
	v_fmac_f32_e32 v49, 0x3f317217, v38
	v_cmp_lt_f32_e64 s[10:11], |v38|, s55
	s_nop 1
	v_cndmask_b32_e64 v38, v38, v49, s[10:11]
	v_cndmask_b32_e32 v49, 0, v212, vcc
	v_sub_f32_e32 v38, v38, v49
	v_sub_f32_e32 v38, v47, v38
	v_mul_f32_e32 v47, 0x3d800000, v38
	v_add_f32_e32 v38, v35, v43
	v_min_f32_e32 v43, 0, v38
	v_mul_f32_e64 v38, |v38|, s23
	v_exp_f32_e32 v38, v38
	s_nop 0
	v_add_f32_e32 v38, 1.0, v38
	v_cmp_gt_f32_e32 vcc, s68, v38
	s_nop 1
	v_cndmask_b32_e64 v49, 0, 32, vcc
	v_ldexp_f32 v38, v38, v49
	v_log_f32_e32 v38, v38
	s_nop 0
	v_mul_f32_e32 v49, 0x3f317217, v38
	v_fma_f32 v49, v38, s25, -v49
	v_fmac_f32_e32 v49, 0x3377d1cf, v38
	v_fmac_f32_e32 v49, 0x3f317217, v38
	v_cmp_lt_f32_e64 s[10:11], |v38|, s55
	s_nop 1
	v_cndmask_b32_e64 v38, v38, v49, s[10:11]
	v_cndmask_b32_e32 v49, 0, v212, vcc
	v_sub_f32_e32 v38, v38, v49
	v_sub_f32_e32 v38, v43, v38
	v_mul_f32_e32 v43, 0x3d800000, v38
	v_add_f32_e32 v38, v31, v39
	v_min_f32_e32 v39, 0, v38
	v_mul_f32_e64 v38, |v38|, s23
	v_exp_f32_e32 v38, v38
	s_nop 0
	v_add_f32_e32 v38, 1.0, v38
	v_cmp_gt_f32_e32 vcc, s68, v38
	s_nop 1
	v_cndmask_b32_e64 v49, 0, 32, vcc
	v_ldexp_f32 v38, v38, v49
	v_log_f32_e32 v38, v38
	s_nop 0
	v_mul_f32_e32 v49, 0x3f317217, v38
	v_fma_f32 v49, v38, s25, -v49
	v_fmac_f32_e32 v49, 0x3377d1cf, v38
	v_fmac_f32_e32 v49, 0x3f317217, v38
	v_cmp_lt_f32_e64 s[10:11], |v38|, s55
	s_nop 1
	v_cndmask_b32_e64 v38, v38, v49, s[10:11]
	v_cndmask_b32_e32 v49, 0, v212, vcc
	v_sub_f32_e32 v38, v38, v49
	v_sub_f32_e32 v38, v39, v38
	v_mul_f32_e32 v49, 0x3d800000, v38
	v_cvt_pk_bf16_f32 v38, v40, v41
	v_cvt_pk_bf16_f32 v39, v42, v43
	v_cvt_pk_bf16_f32 v40, v36, v37
	v_lshl_add_u64 v[36:37], s[16:17], 0, v[44:45]
	v_lshl_add_u64 v[36:37], v[150:151], 1, v[36:37]
	v_cvt_pk_bf16_f32 v41, v47, v49
	global_store_dwordx4 v[36:37], v[38:41], off
	s_mov_b64 s[10:11], 0

.LBB0_332:
	v_mov_b32_e32 v47, v46
	s_nop 0
	v_mov_b32_e32 v28, v46
	v_mov_b32_e32 v29, v46
	v_pk_mul_f32 v[26:27], v[26:27], v[28:29]
	v_pk_mul_f32 v[24:25], v[24:25], v[46:47]
	v_pk_mul_f32 v[22:23], v[22:23], v[28:29]
	v_pk_mul_f32 v[20:21], v[20:21], v[46:47]
	s_mov_b64 s[36:37], -1
	s_mov_b64 s[34:35], 0
	s_cmp_lt_i32 s54, 9
	s_mov_b64 s[10:11], 0
	s_cbranch_scc1 .LBB0_336
	s_cmp_eq_u32 s54, 9
	s_mov_b64 s[10:11], -1
	s_cbranch_scc0 .LBB0_335
	v_mov_b64_e32 v[28:29], v[192:193]
	v_mov_b64_e32 v[30:31], v[194:195]
	v_mov_b64_e32 v[32:33], v[188:189]
	v_mov_b64_e32 v[34:35], v[190:191]
	v_add_f32_e32 v28, v20, v28
	v_add_f32_e32 v32, v24, v32
	v_min_f32_e32 v36, 0, v32
	v_mul_f32_e64 v32, |v32|, s23
	v_exp_f32_e32 v32, v32
	v_add_f32_e32 v33, v25, v33
	v_add_f32_e32 v29, v21, v29
	v_add_f32_e32 v34, v26, v34
	v_add_f32_e32 v32, 1.0, v32
	v_cmp_gt_f32_e32 vcc, s68, v32
	v_add_f32_e32 v30, v22, v30
	s_nop 0
	v_cndmask_b32_e64 v37, 0, 32, vcc
	v_ldexp_f32 v32, v32, v37
	v_log_f32_e32 v32, v32
	s_nop 0
	v_mul_f32_e32 v37, 0x3f317217, v32
	v_fma_f32 v37, v32, s25, -v37
	v_fmac_f32_e32 v37, 0x3377d1cf, v32
	v_fmac_f32_e32 v37, 0x3f317217, v32
	v_cmp_lt_f32_e64 s[10:11], |v32|, s55
	s_nop 1
	v_cndmask_b32_e64 v32, v32, v37, s[10:11]
	v_cndmask_b32_e32 v37, 0, v212, vcc
	v_sub_f32_e32 v32, v32, v37
	v_sub_f32_e32 v32, v36, v32
	v_min_f32_e32 v36, 0, v28
	v_mul_f32_e64 v28, |v28|, s23
	v_exp_f32_e32 v28, v28
	v_mul_f32_e32 v32, 0x3d800000, v32
	v_add_f32_e32 v28, 1.0, v28
	v_cmp_gt_f32_e32 vcc, s68, v28
	s_nop 1
	v_cndmask_b32_e64 v37, 0, 32, vcc
	v_ldexp_f32 v28, v28, v37
	v_log_f32_e32 v28, v28
	s_nop 0
	v_mul_f32_e32 v37, 0x3f317217, v28
	v_fma_f32 v37, v28, s25, -v37
	v_fmac_f32_e32 v37, 0x3377d1cf, v28
	v_fmac_f32_e32 v37, 0x3f317217, v28
	v_cmp_lt_f32_e64 s[10:11], |v28|, s55
	s_nop 1
	v_cndmask_b32_e64 v28, v28, v37, s[10:11]
	v_cndmask_b32_e32 v37, 0, v212, vcc
	v_sub_f32_e32 v28, v28, v37
	v_sub_f32_e32 v28, v36, v28
	v_min_f32_e32 v36, 0, v33
	v_mul_f32_e64 v33, |v33|, s23
	v_exp_f32_e32 v33, v33
	v_mul_f32_e32 v28, 0x3d800000, v28
	v_add_f32_e32 v33, 1.0, v33
	v_cmp_gt_f32_e32 vcc, s68, v33
	s_nop 1
	v_cndmask_b32_e64 v37, 0, 32, vcc
	v_ldexp_f32 v33, v33, v37
	v_log_f32_e32 v33, v33
	s_nop 0
	v_mul_f32_e32 v37, 0x3f317217, v33
	v_fma_f32 v37, v33, s25, -v37
	v_fmac_f32_e32 v37, 0x3377d1cf, v33
	v_fmac_f32_e32 v37, 0x3f317217, v33
	v_cmp_lt_f32_e64 s[10:11], |v33|, s55
	s_nop 1
	v_cndmask_b32_e64 v33, v33, v37, s[10:11]
	v_cndmask_b32_e32 v37, 0, v212, vcc
	v_sub_f32_e32 v33, v33, v37
	v_sub_f32_e32 v33, v36, v33
	v_min_f32_e32 v36, 0, v29
	v_mul_f32_e64 v29, |v29|, s23
	v_exp_f32_e32 v29, v29
	v_mul_f32_e32 v33, 0x3d800000, v33
	v_add_f32_e32 v29, 1.0, v29
	v_cmp_gt_f32_e32 vcc, s68, v29
	s_nop 1
	v_cndmask_b32_e64 v37, 0, 32, vcc
	v_ldexp_f32 v29, v29, v37
	v_log_f32_e32 v29, v29
	s_nop 0
	v_mul_f32_e32 v37, 0x3f317217, v29
	v_fma_f32 v37, v29, s25, -v37
	v_fmac_f32_e32 v37, 0x3377d1cf, v29
	v_fmac_f32_e32 v37, 0x3f317217, v29
	v_cmp_lt_f32_e64 s[10:11], |v29|, s55
	s_nop 1
	v_cndmask_b32_e64 v29, v29, v37, s[10:11]
	v_cndmask_b32_e32 v37, 0, v212, vcc
	v_sub_f32_e32 v29, v29, v37
	v_sub_f32_e32 v29, v36, v29
	v_min_f32_e32 v36, 0, v34
	v_mul_f32_e64 v34, |v34|, s23
	v_exp_f32_e32 v34, v34
	v_mul_f32_e32 v29, 0x3d800000, v29
	v_add_f32_e32 v34, 1.0, v34
	v_cmp_gt_f32_e32 vcc, s68, v34
	s_nop 1
	v_cndmask_b32_e64 v37, 0, 32, vcc
	v_ldexp_f32 v34, v34, v37
	v_log_f32_e32 v34, v34
	s_nop 0
	v_mul_f32_e32 v37, 0x3f317217, v34
	v_fma_f32 v37, v34, s25, -v37
	v_fmac_f32_e32 v37, 0x3377d1cf, v34
	v_fmac_f32_e32 v37, 0x3f317217, v34
	v_cmp_lt_f32_e64 s[10:11], |v34|, s55
	s_nop 1
	v_cndmask_b32_e64 v34, v34, v37, s[10:11]
	v_cndmask_b32_e32 v37, 0, v212, vcc
	v_sub_f32_e32 v34, v34, v37
	v_sub_f32_e32 v34, v36, v34
	v_min_f32_e32 v36, 0, v30
	v_mul_f32_e64 v30, |v30|, s23
	v_exp_f32_e32 v30, v30
	v_mul_f32_e32 v34, 0x3d800000, v34
	v_add_f32_e32 v30, 1.0, v30
	v_cmp_gt_f32_e32 vcc, s68, v30
	s_nop 1
	v_cndmask_b32_e64 v37, 0, 32, vcc
	v_ldexp_f32 v30, v30, v37
	v_log_f32_e32 v30, v30
	s_nop 0
	v_mul_f32_e32 v37, 0x3f317217, v30
	v_fma_f32 v37, v30, s25, -v37
	v_fmac_f32_e32 v37, 0x3377d1cf, v30
	v_fmac_f32_e32 v37, 0x3f317217, v30
	v_cmp_lt_f32_e64 s[10:11], |v30|, s55
	s_nop 1
	v_cndmask_b32_e64 v30, v30, v37, s[10:11]
	v_cndmask_b32_e32 v37, 0, v212, vcc
	v_sub_f32_e32 v30, v30, v37
	v_sub_f32_e32 v30, v36, v30
	v_mul_f32_e32 v36, 0x3d800000, v30
	v_add_f32_e32 v30, v27, v35
	v_min_f32_e32 v35, 0, v30
	v_mul_f32_e64 v30, |v30|, s23
	v_exp_f32_e32 v30, v30
	s_nop 0
	v_add_f32_e32 v30, 1.0, v30
	v_cmp_gt_f32_e32 vcc, s68, v30
	s_nop 1
	v_cndmask_b32_e64 v37, 0, 32, vcc
	v_ldexp_f32 v30, v30, v37
	v_log_f32_e32 v30, v30
	s_nop 0
	v_mul_f32_e32 v37, 0x3f317217, v30
	v_fma_f32 v37, v30, s25, -v37
	v_fmac_f32_e32 v37, 0x3377d1cf, v30
	v_fmac_f32_e32 v37, 0x3f317217, v30
	v_cmp_lt_f32_e64 s[10:11], |v30|, s55
	s_nop 1
	v_cndmask_b32_e64 v30, v30, v37, s[10:11]
	v_cndmask_b32_e32 v37, 0, v212, vcc
	v_sub_f32_e32 v30, v30, v37
	v_sub_f32_e32 v30, v35, v30
	v_mul_f32_e32 v35, 0x3d800000, v30
	v_add_f32_e32 v30, v23, v31
	v_min_f32_e32 v31, 0, v30
	v_mul_f32_e64 v30, |v30|, s23
	v_exp_f32_e32 v30, v30
	s_nop 0
	v_add_f32_e32 v30, 1.0, v30
	v_cmp_gt_f32_e32 vcc, s68, v30
	s_nop 1
	v_cndmask_b32_e64 v37, 0, 32, vcc
	v_ldexp_f32 v30, v30, v37
	v_log_f32_e32 v30, v30
	s_nop 0
	v_mul_f32_e32 v37, 0x3f317217, v30
	v_fma_f32 v37, v30, s25, -v37
	v_fmac_f32_e32 v37, 0x3377d1cf, v30
	v_fmac_f32_e32 v37, 0x3f317217, v30
	v_cmp_lt_f32_e64 s[10:11], |v30|, s55
	s_nop 1
	v_cndmask_b32_e64 v30, v30, v37, s[10:11]
	v_cndmask_b32_e32 v37, 0, v212, vcc
	v_sub_f32_e32 v30, v30, v37
	v_sub_f32_e32 v30, v31, v30
	v_mul_f32_e32 v37, 0x3d800000, v30
	v_cvt_pk_bf16_f32 v30, v32, v33
	v_cvt_pk_bf16_f32 v31, v34, v35
	v_cvt_pk_bf16_f32 v32, v28, v29
	v_lshl_add_u64 v[28:29], s[16:17], 0, v[44:45]
	v_lshl_add_u64 v[28:29], v[150:151], 1, v[28:29]
	v_cvt_pk_bf16_f32 v33, v36, v37
	global_store_dwordx4 v[28:29], v[30:33], off offset:256
	s_mov_b64 s[10:11], 0

.LBB0_344:
	ds_read_b32 v30, v176 offset:704
	v_add_u32_e32 v32, 0xb0, v152
	v_ashrrev_i32_e32 v33, 31, v32
	v_lshlrev_b64 v[28:29], 9, v[32:33]
	s_mov_b64 s[36:37], -1
	s_waitcnt lgkmcnt(0)
	v_pk_mul_f32 v[18:19], v[18:19], v[30:31] op_sel_hi:[1,0]
	v_pk_mul_f32 v[16:17], v[16:17], v[30:31] op_sel_hi:[1,0]
	v_pk_mul_f32 v[14:15], v[14:15], v[30:31] op_sel_hi:[1,0]
	v_pk_mul_f32 v[12:13], v[12:13], v[30:31] op_sel_hi:[1,0]
	s_mov_b64 s[34:35], 0
	s_cmp_lt_i32 s54, 9
	s_mov_b64 s[10:11], 0
	s_cbranch_scc1 .LBB0_350
	s_cmp_eq_u32 s54, 9
	s_mov_b64 s[10:11], -1
	s_cbranch_scc0 .LBB0_347
	v_mov_b64_e32 v[20:21], v[184:185]
	v_mov_b64_e32 v[22:23], v[186:187]
	v_mov_b64_e32 v[24:25], v[180:181]
	v_mov_b64_e32 v[26:27], v[182:183]
	v_add_f32_e32 v20, v12, v20
	v_add_f32_e32 v24, v16, v24
	v_min_f32_e32 v31, 0, v24
	v_mul_f32_e64 v24, |v24|, s23
	v_exp_f32_e32 v24, v24
	v_add_f32_e32 v25, v17, v25
	v_add_f32_e32 v21, v13, v21
	v_add_f32_e32 v26, v18, v26
	v_add_f32_e32 v24, 1.0, v24
	v_cmp_gt_f32_e32 vcc, s68, v24
	v_add_f32_e32 v22, v14, v22
	s_nop 0
	v_cndmask_b32_e64 v33, 0, 32, vcc
	v_ldexp_f32 v24, v24, v33
	v_log_f32_e32 v24, v24
	s_nop 0
	v_mul_f32_e32 v33, 0x3f317217, v24
	v_fma_f32 v33, v24, s25, -v33
	v_fmac_f32_e32 v33, 0x3377d1cf, v24
	v_fmac_f32_e32 v33, 0x3f317217, v24
	v_cmp_lt_f32_e64 s[10:11], |v24|, s55
	s_nop 1
	v_cndmask_b32_e64 v24, v24, v33, s[10:11]
	v_cndmask_b32_e32 v33, 0, v212, vcc
	v_sub_f32_e32 v24, v24, v33
	v_sub_f32_e32 v24, v31, v24
	v_min_f32_e32 v31, 0, v20
	v_mul_f32_e64 v20, |v20|, s23
	v_exp_f32_e32 v20, v20
	v_mul_f32_e32 v24, 0x3d800000, v24
	v_add_f32_e32 v20, 1.0, v20
	v_cmp_gt_f32_e32 vcc, s68, v20
	s_nop 1
	v_cndmask_b32_e64 v33, 0, 32, vcc
	v_ldexp_f32 v20, v20, v33
	v_log_f32_e32 v20, v20
	s_nop 0
	v_mul_f32_e32 v33, 0x3f317217, v20
	v_fma_f32 v33, v20, s25, -v33
	v_fmac_f32_e32 v33, 0x3377d1cf, v20
	v_fmac_f32_e32 v33, 0x3f317217, v20
	v_cmp_lt_f32_e64 s[10:11], |v20|, s55
	s_nop 1
	v_cndmask_b32_e64 v20, v20, v33, s[10:11]
	v_cndmask_b32_e32 v33, 0, v212, vcc
	v_sub_f32_e32 v20, v20, v33
	v_sub_f32_e32 v20, v31, v20
	v_min_f32_e32 v31, 0, v25
	v_mul_f32_e64 v25, |v25|, s23
	v_exp_f32_e32 v25, v25
	v_mul_f32_e32 v20, 0x3d800000, v20
	v_add_f32_e32 v25, 1.0, v25
	v_cmp_gt_f32_e32 vcc, s68, v25
	s_nop 1
	v_cndmask_b32_e64 v33, 0, 32, vcc
	v_ldexp_f32 v25, v25, v33
	v_log_f32_e32 v25, v25
	s_nop 0
	v_mul_f32_e32 v33, 0x3f317217, v25
	v_fma_f32 v33, v25, s25, -v33
	v_fmac_f32_e32 v33, 0x3377d1cf, v25
	v_fmac_f32_e32 v33, 0x3f317217, v25
	v_cmp_lt_f32_e64 s[10:11], |v25|, s55
	s_nop 1
	v_cndmask_b32_e64 v25, v25, v33, s[10:11]
	v_cndmask_b32_e32 v33, 0, v212, vcc
	v_sub_f32_e32 v25, v25, v33
	v_sub_f32_e32 v25, v31, v25
	v_min_f32_e32 v31, 0, v21
	v_mul_f32_e64 v21, |v21|, s23
	v_exp_f32_e32 v21, v21
	v_mul_f32_e32 v25, 0x3d800000, v25
	v_add_f32_e32 v21, 1.0, v21
	v_cmp_gt_f32_e32 vcc, s68, v21
	s_nop 1
	v_cndmask_b32_e64 v33, 0, 32, vcc
	v_ldexp_f32 v21, v21, v33
	v_log_f32_e32 v21, v21
	s_nop 0
	v_mul_f32_e32 v33, 0x3f317217, v21
	v_fma_f32 v33, v21, s25, -v33
	v_fmac_f32_e32 v33, 0x3377d1cf, v21
	v_fmac_f32_e32 v33, 0x3f317217, v21
	v_cmp_lt_f32_e64 s[10:11], |v21|, s55
	s_nop 1
	v_cndmask_b32_e64 v21, v21, v33, s[10:11]
	v_cndmask_b32_e32 v33, 0, v212, vcc
	v_sub_f32_e32 v21, v21, v33
	v_sub_f32_e32 v21, v31, v21
	v_min_f32_e32 v31, 0, v26
	v_mul_f32_e64 v26, |v26|, s23
	v_exp_f32_e32 v26, v26
	v_mul_f32_e32 v21, 0x3d800000, v21
	v_add_f32_e32 v26, 1.0, v26
	v_cmp_gt_f32_e32 vcc, s68, v26
	s_nop 1
	v_cndmask_b32_e64 v33, 0, 32, vcc
	v_ldexp_f32 v26, v26, v33
	v_log_f32_e32 v26, v26
	s_nop 0
	v_mul_f32_e32 v33, 0x3f317217, v26
	v_fma_f32 v33, v26, s25, -v33
	v_fmac_f32_e32 v33, 0x3377d1cf, v26
	v_fmac_f32_e32 v33, 0x3f317217, v26
	v_cmp_lt_f32_e64 s[10:11], |v26|, s55
	s_nop 1
	v_cndmask_b32_e64 v26, v26, v33, s[10:11]
	v_cndmask_b32_e32 v33, 0, v212, vcc
	v_sub_f32_e32 v26, v26, v33
	v_sub_f32_e32 v26, v31, v26
	v_min_f32_e32 v31, 0, v22
	v_mul_f32_e64 v22, |v22|, s23
	v_exp_f32_e32 v22, v22
	v_mul_f32_e32 v26, 0x3d800000, v26
	v_add_f32_e32 v22, 1.0, v22
	v_cmp_gt_f32_e32 vcc, s68, v22
	s_nop 1
	v_cndmask_b32_e64 v33, 0, 32, vcc
	v_ldexp_f32 v22, v22, v33
	v_log_f32_e32 v22, v22
	s_nop 0
	v_mul_f32_e32 v33, 0x3f317217, v22
	v_fma_f32 v33, v22, s25, -v33
	v_fmac_f32_e32 v33, 0x3377d1cf, v22
	v_fmac_f32_e32 v33, 0x3f317217, v22
	v_cmp_lt_f32_e64 s[10:11], |v22|, s55
	s_nop 1
	v_cndmask_b32_e64 v22, v22, v33, s[10:11]
	v_cndmask_b32_e32 v33, 0, v212, vcc
	v_sub_f32_e32 v22, v22, v33
	v_sub_f32_e32 v22, v31, v22
	v_mul_f32_e32 v31, 0x3d800000, v22
	v_add_f32_e32 v22, v19, v27
	v_min_f32_e32 v27, 0, v22
	v_mul_f32_e64 v22, |v22|, s23
	v_exp_f32_e32 v22, v22
	s_nop 0
	v_add_f32_e32 v22, 1.0, v22
	v_cmp_gt_f32_e32 vcc, s68, v22
	s_nop 1
	v_cndmask_b32_e64 v33, 0, 32, vcc
	v_ldexp_f32 v22, v22, v33
	v_log_f32_e32 v22, v22
	s_nop 0
	v_mul_f32_e32 v33, 0x3f317217, v22
	v_fma_f32 v33, v22, s25, -v33
	v_fmac_f32_e32 v33, 0x3377d1cf, v22
	v_fmac_f32_e32 v33, 0x3f317217, v22
	v_cmp_lt_f32_e64 s[10:11], |v22|, s55
	s_nop 1
	v_cndmask_b32_e64 v22, v22, v33, s[10:11]
	v_cndmask_b32_e32 v33, 0, v212, vcc
	v_sub_f32_e32 v22, v22, v33
	v_sub_f32_e32 v22, v27, v22
	v_mul_f32_e32 v27, 0x3d800000, v22
	v_add_f32_e32 v22, v15, v23
	v_min_f32_e32 v23, 0, v22
	v_mul_f32_e64 v22, |v22|, s23
	v_exp_f32_e32 v22, v22
	s_nop 0
	v_add_f32_e32 v22, 1.0, v22
	v_cmp_gt_f32_e32 vcc, s68, v22
	s_nop 1
	v_cndmask_b32_e64 v33, 0, 32, vcc
	v_ldexp_f32 v22, v22, v33
	v_log_f32_e32 v22, v22
	s_nop 0
	v_mul_f32_e32 v33, 0x3f317217, v22
	v_fma_f32 v33, v22, s25, -v33
	v_fmac_f32_e32 v33, 0x3377d1cf, v22
	v_fmac_f32_e32 v33, 0x3f317217, v22
	v_cmp_lt_f32_e64 s[10:11], |v22|, s55
	s_nop 1
	v_cndmask_b32_e64 v22, v22, v33, s[10:11]
	v_cndmask_b32_e32 v33, 0, v212, vcc
	v_sub_f32_e32 v22, v22, v33
	v_sub_f32_e32 v22, v23, v22
	v_mul_f32_e32 v33, 0x3d800000, v22
	v_cvt_pk_bf16_f32 v22, v24, v25
	v_cvt_pk_bf16_f32 v23, v26, v27
	v_cvt_pk_bf16_f32 v24, v20, v21
	v_lshl_add_u64 v[20:21], s[16:17], 0, v[28:29]
	v_lshl_add_u64 v[20:21], v[150:151], 1, v[20:21]
	v_cvt_pk_bf16_f32 v25, v31, v33
	global_store_dwordx4 v[20:21], v[22:25], off
	s_mov_b64 s[10:11], 0

.LBB0_360:
	v_mov_b32_e32 v31, v30
	s_nop 0
	v_mov_b32_e32 v12, v30
	v_mov_b32_e32 v13, v30
	v_pk_mul_f32 v[10:11], v[10:11], v[12:13]
	v_pk_mul_f32 v[8:9], v[8:9], v[30:31]
	v_pk_mul_f32 v[6:7], v[6:7], v[12:13]
	v_pk_mul_f32 v[4:5], v[4:5], v[30:31]
	s_mov_b64 s[34:35], -1
	s_mov_b64 s[30:31], 0
	s_cmp_lt_i32 s54, 9
	s_mov_b64 s[10:11], 0
	s_cbranch_scc1 .LBB0_364
	s_cmp_eq_u32 s54, 9
	s_mov_b64 s[10:11], -1
	s_cbranch_scc0 .LBB0_363
	v_mov_b64_e32 v[12:13], v[192:193]
	v_mov_b64_e32 v[14:15], v[194:195]
	v_mov_b64_e32 v[16:17], v[188:189]
	v_mov_b64_e32 v[18:19], v[190:191]
	v_add_f32_e32 v12, v4, v12
	v_add_f32_e32 v16, v8, v16
	v_min_f32_e32 v20, 0, v16
	v_mul_f32_e64 v16, |v16|, s23
	v_exp_f32_e32 v16, v16
	v_add_f32_e32 v17, v9, v17
	v_add_f32_e32 v13, v5, v13
	v_add_f32_e32 v18, v10, v18
	v_add_f32_e32 v16, 1.0, v16
	v_cmp_gt_f32_e32 vcc, s68, v16
	v_add_f32_e32 v14, v6, v14
	s_nop 0
	v_cndmask_b32_e64 v21, 0, 32, vcc
	v_ldexp_f32 v16, v16, v21
	v_log_f32_e32 v16, v16
	s_nop 0
	v_mul_f32_e32 v21, 0x3f317217, v16
	v_fma_f32 v21, v16, s25, -v21
	v_fmac_f32_e32 v21, 0x3377d1cf, v16
	v_fmac_f32_e32 v21, 0x3f317217, v16
	v_cmp_lt_f32_e64 s[10:11], |v16|, s55
	s_nop 1
	v_cndmask_b32_e64 v16, v16, v21, s[10:11]
	v_cndmask_b32_e32 v21, 0, v212, vcc
	v_sub_f32_e32 v16, v16, v21
	v_sub_f32_e32 v16, v20, v16
	v_min_f32_e32 v20, 0, v12
	v_mul_f32_e64 v12, |v12|, s23
	v_exp_f32_e32 v12, v12
	v_mul_f32_e32 v16, 0x3d800000, v16
	v_add_f32_e32 v12, 1.0, v12
	v_cmp_gt_f32_e32 vcc, s68, v12
	s_nop 1
	v_cndmask_b32_e64 v21, 0, 32, vcc
	v_ldexp_f32 v12, v12, v21
	v_log_f32_e32 v12, v12
	s_nop 0
	v_mul_f32_e32 v21, 0x3f317217, v12
	v_fma_f32 v21, v12, s25, -v21
	v_fmac_f32_e32 v21, 0x3377d1cf, v12
	v_fmac_f32_e32 v21, 0x3f317217, v12
	v_cmp_lt_f32_e64 s[10:11], |v12|, s55
	s_nop 1
	v_cndmask_b32_e64 v12, v12, v21, s[10:11]
	v_cndmask_b32_e32 v21, 0, v212, vcc
	v_sub_f32_e32 v12, v12, v21
	v_sub_f32_e32 v12, v20, v12
	v_min_f32_e32 v20, 0, v17
	v_mul_f32_e64 v17, |v17|, s23
	v_exp_f32_e32 v17, v17
	v_mul_f32_e32 v12, 0x3d800000, v12
	v_add_f32_e32 v17, 1.0, v17
	v_cmp_gt_f32_e32 vcc, s68, v17
	s_nop 1
	v_cndmask_b32_e64 v21, 0, 32, vcc
	v_ldexp_f32 v17, v17, v21
	v_log_f32_e32 v17, v17
	s_nop 0
	v_mul_f32_e32 v21, 0x3f317217, v17
	v_fma_f32 v21, v17, s25, -v21
	v_fmac_f32_e32 v21, 0x3377d1cf, v17
	v_fmac_f32_e32 v21, 0x3f317217, v17
	v_cmp_lt_f32_e64 s[10:11], |v17|, s55
	s_nop 1
	v_cndmask_b32_e64 v17, v17, v21, s[10:11]
	v_cndmask_b32_e32 v21, 0, v212, vcc
	v_sub_f32_e32 v17, v17, v21
	v_sub_f32_e32 v17, v20, v17
	v_min_f32_e32 v20, 0, v13
	v_mul_f32_e64 v13, |v13|, s23
	v_exp_f32_e32 v13, v13
	v_mul_f32_e32 v17, 0x3d800000, v17
	v_add_f32_e32 v13, 1.0, v13
	v_cmp_gt_f32_e32 vcc, s68, v13
	s_nop 1
	v_cndmask_b32_e64 v21, 0, 32, vcc
	v_ldexp_f32 v13, v13, v21
	v_log_f32_e32 v13, v13
	s_nop 0
	v_mul_f32_e32 v21, 0x3f317217, v13
	v_fma_f32 v21, v13, s25, -v21
	v_fmac_f32_e32 v21, 0x3377d1cf, v13
	v_fmac_f32_e32 v21, 0x3f317217, v13
	v_cmp_lt_f32_e64 s[10:11], |v13|, s55
	s_nop 1
	v_cndmask_b32_e64 v13, v13, v21, s[10:11]
	v_cndmask_b32_e32 v21, 0, v212, vcc
	v_sub_f32_e32 v13, v13, v21
	v_sub_f32_e32 v13, v20, v13
	v_min_f32_e32 v20, 0, v18
	v_mul_f32_e64 v18, |v18|, s23
	v_exp_f32_e32 v18, v18
	v_mul_f32_e32 v13, 0x3d800000, v13
	v_add_f32_e32 v18, 1.0, v18
	v_cmp_gt_f32_e32 vcc, s68, v18
	s_nop 1
	v_cndmask_b32_e64 v21, 0, 32, vcc
	v_ldexp_f32 v18, v18, v21
	v_log_f32_e32 v18, v18
	s_nop 0
	v_mul_f32_e32 v21, 0x3f317217, v18
	v_fma_f32 v21, v18, s25, -v21
	v_fmac_f32_e32 v21, 0x3377d1cf, v18
	v_fmac_f32_e32 v21, 0x3f317217, v18
	v_cmp_lt_f32_e64 s[10:11], |v18|, s55
	s_nop 1
	v_cndmask_b32_e64 v18, v18, v21, s[10:11]
	v_cndmask_b32_e32 v21, 0, v212, vcc
	v_sub_f32_e32 v18, v18, v21
	v_sub_f32_e32 v18, v20, v18
	v_min_f32_e32 v20, 0, v14
	v_mul_f32_e64 v14, |v14|, s23
	v_exp_f32_e32 v14, v14
	v_mul_f32_e32 v18, 0x3d800000, v18
	v_add_f32_e32 v14, 1.0, v14
	v_cmp_gt_f32_e32 vcc, s68, v14
	s_nop 1
	v_cndmask_b32_e64 v21, 0, 32, vcc
	v_ldexp_f32 v14, v14, v21
	v_log_f32_e32 v14, v14
	s_nop 0
	v_mul_f32_e32 v21, 0x3f317217, v14
	v_fma_f32 v21, v14, s25, -v21
	v_fmac_f32_e32 v21, 0x3377d1cf, v14
	v_fmac_f32_e32 v21, 0x3f317217, v14
	v_cmp_lt_f32_e64 s[10:11], |v14|, s55
	s_nop 1
	v_cndmask_b32_e64 v14, v14, v21, s[10:11]
	v_cndmask_b32_e32 v21, 0, v212, vcc
	v_sub_f32_e32 v14, v14, v21
	v_sub_f32_e32 v14, v20, v14
	v_mul_f32_e32 v20, 0x3d800000, v14
	v_add_f32_e32 v14, v11, v19
	v_min_f32_e32 v19, 0, v14
	v_mul_f32_e64 v14, |v14|, s23
	v_exp_f32_e32 v14, v14
	s_nop 0
	v_add_f32_e32 v14, 1.0, v14
	v_cmp_gt_f32_e32 vcc, s68, v14
	s_nop 1
	v_cndmask_b32_e64 v21, 0, 32, vcc
	v_ldexp_f32 v14, v14, v21
	v_log_f32_e32 v14, v14
	s_nop 0
	v_mul_f32_e32 v21, 0x3f317217, v14
	v_fma_f32 v21, v14, s25, -v21
	v_fmac_f32_e32 v21, 0x3377d1cf, v14
	v_fmac_f32_e32 v21, 0x3f317217, v14
	v_cmp_lt_f32_e64 s[10:11], |v14|, s55
	s_nop 1
	v_cndmask_b32_e64 v14, v14, v21, s[10:11]
	v_cndmask_b32_e32 v21, 0, v212, vcc
	v_sub_f32_e32 v14, v14, v21
	v_sub_f32_e32 v14, v19, v14
	v_mul_f32_e32 v19, 0x3d800000, v14
	v_add_f32_e32 v14, v7, v15
	v_min_f32_e32 v15, 0, v14
	v_mul_f32_e64 v14, |v14|, s23
	v_exp_f32_e32 v14, v14
	s_nop 0
	v_add_f32_e32 v14, 1.0, v14
	v_cmp_gt_f32_e32 vcc, s68, v14
	s_nop 1
	v_cndmask_b32_e64 v21, 0, 32, vcc
	v_ldexp_f32 v14, v14, v21
	v_log_f32_e32 v14, v14
	s_nop 0
	v_mul_f32_e32 v21, 0x3f317217, v14
	v_fma_f32 v21, v14, s25, -v21
	v_fmac_f32_e32 v21, 0x3377d1cf, v14
	v_fmac_f32_e32 v21, 0x3f317217, v14
	v_cmp_lt_f32_e64 s[10:11], |v14|, s55
	s_nop 1
	v_cndmask_b32_e64 v14, v14, v21, s[10:11]
	v_cndmask_b32_e32 v21, 0, v212, vcc
	v_sub_f32_e32 v14, v14, v21
	v_sub_f32_e32 v14, v15, v14
	v_mul_f32_e32 v21, 0x3d800000, v14
	v_cvt_pk_bf16_f32 v14, v16, v17
	v_cvt_pk_bf16_f32 v15, v18, v19
	v_cvt_pk_bf16_f32 v16, v12, v13
	v_lshl_add_u64 v[12:13], s[16:17], 0, v[28:29]
	v_lshl_add_u64 v[12:13], v[150:151], 1, v[12:13]
	v_cvt_pk_bf16_f32 v17, v20, v21
	global_store_dwordx4 v[12:13], v[14:17], off offset:256
	s_mov_b64 s[10:11], 0

.LBB0_605:
	s_add_u32 s26, s10, 0xfffc0080
	s_addc_u32 s27, s11, -1
	s_add_i32 s53, 0, 0x10000
	s_cmp_eq_u32 s52, 12
	s_cselect_b32 s29, s21, s27
	s_cselect_b32 s28, s48, s26
	v_add_u32_e32 v149, s53, v147
	s_cselect_b32 s27, s19, s51
	s_cselect_b32 s26, s49, s50
	s_add_i32 s56, 0, 0x14000
	ds_read_b128 v[142:145], v149
	ds_read_b128 v[150:153], v149 offset:1024
	ds_read_b128 v[170:173], v149 offset:2048
	ds_read_b128 v[174:177], v149 offset:3072
	v_add_u32_e32 v149, s56, v147
	ds_read_b128 v[178:181], v149
	ds_read_b128 v[182:185], v149 offset:1024
	ds_read_b128 v[186:189], v149 offset:2048
	ds_read_b128 v[190:193], v149 offset:3072
	v_lshl_add_u64 v[154:155], s[10:11], 0, v[138:139]
	s_add_i32 m0, s35, 0xc000
	ds_read_b128 v[194:197], v148
	ds_read_b128 v[198:201], v148 offset:1024
	ds_read_b128 v[202:205], v148 offset:2048
	ds_read_b128 v[220:223], v148 offset:3072
	ds_read_b128 v[224:227], v148 offset:4096
	ds_read_b128 v[228:231], v148 offset:5120
	ds_read_b128 v[232:235], v148 offset:6144
	ds_read_b128 v[236:239], v148 offset:7168
	global_load_lds_dwordx4 v[154:155], off
	v_lshl_add_u64 v[154:155], s[10:11], 0, v[140:141]
	s_add_i32 m0, s35, 0xe000
	s_nop 0
	global_load_lds_dwordx4 v[154:155], off
	s_waitcnt vmcnt(8)
	s_waitcnt lgkmcnt(0)
	s_barrier
	s_setprio 1
	s_waitcnt lgkmcnt(0)
	v_mfma_f32_16x16x32_bf16 v[128:131], v[142:145], v[194:197], v[128:131]
	v_mfma_f32_16x16x32_bf16 v[124:127], v[170:173], v[194:197], v[124:127]
	v_mfma_f32_16x16x32_bf16 v[112:115], v[142:145], v[202:205], v[112:115]
	v_mfma_f32_16x16x32_bf16 v[108:111], v[170:173], v[202:205], v[108:111]
	v_mfma_f32_16x16x32_bf16 v[96:99], v[142:145], v[224:227], v[96:99]
	v_mfma_f32_16x16x32_bf16 v[92:95], v[170:173], v[224:227], v[92:95]
	v_mfma_f32_16x16x32_bf16 v[80:83], v[142:145], v[232:235], v[80:83]
	v_mfma_f32_16x16x32_bf16 v[76:79], v[170:173], v[232:235], v[76:79]
	v_mfma_f32_16x16x32_bf16 v[128:131], v[150:153], v[198:201], v[128:131]
	v_mfma_f32_16x16x32_bf16 v[124:127], v[174:177], v[198:201], v[124:127]
	v_mfma_f32_16x16x32_bf16 v[112:115], v[150:153], v[220:223], v[112:115]
	v_mfma_f32_16x16x32_bf16 v[108:111], v[174:177], v[220:223], v[108:111]
	v_mfma_f32_16x16x32_bf16 v[96:99], v[150:153], v[228:231], v[96:99]
	v_mfma_f32_16x16x32_bf16 v[92:95], v[174:177], v[228:231], v[92:95]
	v_mfma_f32_16x16x32_bf16 v[80:83], v[150:153], v[236:239], v[80:83]
	v_mfma_f32_16x16x32_bf16 v[76:79], v[174:177], v[236:239], v[76:79]
	v_mfma_f32_16x16x32_bf16 v[120:123], v[178:181], v[194:197], v[120:123]
	v_mfma_f32_16x16x32_bf16 v[116:119], v[186:189], v[194:197], v[116:119]
	v_mfma_f32_16x16x32_bf16 v[104:107], v[178:181], v[202:205], v[104:107]
	v_mfma_f32_16x16x32_bf16 v[100:103], v[186:189], v[202:205], v[100:103]
	v_mfma_f32_16x16x32_bf16 v[88:91], v[178:181], v[224:227], v[88:91]
	v_mfma_f32_16x16x32_bf16 v[84:87], v[186:189], v[224:227], v[84:87]
	v_mfma_f32_16x16x32_bf16 v[72:75], v[178:181], v[232:235], v[72:75]
	v_mfma_f32_16x16x32_bf16 v[68:71], v[186:189], v[232:235], v[68:71]
	v_mfma_f32_16x16x32_bf16 v[120:123], v[182:185], v[198:201], v[120:123]
	v_mfma_f32_16x16x32_bf16 v[116:119], v[190:193], v[198:201], v[116:119]
	v_mfma_f32_16x16x32_bf16 v[104:107], v[182:185], v[220:223], v[104:107]
	v_mfma_f32_16x16x32_bf16 v[100:103], v[190:193], v[220:223], v[100:103]
	v_mfma_f32_16x16x32_bf16 v[88:91], v[182:185], v[228:231], v[88:91]
	v_mfma_f32_16x16x32_bf16 v[84:87], v[190:193], v[228:231], v[84:87]
	v_mfma_f32_16x16x32_bf16 v[72:75], v[182:185], v[236:239], v[72:75]
	v_mfma_f32_16x16x32_bf16 v[68:71], v[190:193], v[236:239], v[68:71]
	s_setprio 0
	s_barrier
	s_add_i32 s53, s53, s34
	v_lshl_add_u64 v[154:155], s[26:27], 0, v[134:135]
	s_mov_b32 m0, s53
	ds_read_b128 v[194:197], v148 offset:16384
	ds_read_b128 v[198:201], v148 offset:17408
	ds_read_b128 v[202:205], v148 offset:18432
	ds_read_b128 v[220:223], v148 offset:19456
	ds_read_b128 v[224:227], v148 offset:20480
	ds_read_b128 v[228:231], v148 offset:21504
	ds_read_b128 v[232:235], v148 offset:22528
	ds_read_b128 v[236:239], v148 offset:23552
	global_load_lds_dwordx4 v[154:155], off
	s_add_i32 m0, s53, 0x2000
	s_add_u32 s54, s26, 0x40000
	v_lshl_add_u64 v[158:159], s[26:27], 0, v[0:1]
	s_addc_u32 s55, s27, 0
	s_add_i32 s53, s56, s34
	global_load_lds_dwordx4 v[158:159], off
	v_lshl_add_u64 v[160:161], s[54:55], 0, v[134:135]
	s_mov_b32 m0, s53
	v_lshl_add_u64 v[206:207], s[28:29], 0, v[132:133]
	global_load_lds_dwordx4 v[160:161], off
	v_lshl_add_u64 v[160:161], s[54:55], 0, v[0:1]
	s_add_i32 m0, s53, 0x2000
	s_nop 0
	global_load_lds_dwordx4 v[160:161], off
	v_lshl_add_u64 v[160:161], s[28:29], 0, v[136:137]
	s_mov_b32 m0, s35
	s_nop 0
	global_load_lds_dwordx4 v[160:161], off
	s_mov_b32 m0, s36
	s_nop 0
	global_load_lds_dwordx4 v[206:207], off
	s_waitcnt vmcnt(8)
	s_waitcnt lgkmcnt(0)
	s_barrier
	s_setprio 1
	s_waitcnt lgkmcnt(0)
	v_mfma_f32_16x16x32_bf16 v[64:67], v[142:145], v[194:197], v[64:67]
	v_mfma_f32_16x16x32_bf16 v[60:63], v[170:173], v[194:197], v[60:63]
	v_mfma_f32_16x16x32_bf16 v[48:51], v[142:145], v[202:205], v[48:51]
	v_mfma_f32_16x16x32_bf16 v[44:47], v[170:173], v[202:205], v[44:47]
	v_mfma_f32_16x16x32_bf16 v[32:35], v[142:145], v[224:227], v[32:35]
	v_mfma_f32_16x16x32_bf16 v[28:31], v[170:173], v[224:227], v[28:31]
	v_mfma_f32_16x16x32_bf16 v[16:19], v[142:145], v[232:235], v[16:19]
	v_mfma_f32_16x16x32_bf16 v[12:15], v[170:173], v[232:235], v[12:15]
	v_mfma_f32_16x16x32_bf16 v[64:67], v[150:153], v[198:201], v[64:67]
	v_mfma_f32_16x16x32_bf16 v[60:63], v[174:177], v[198:201], v[60:63]
	v_mfma_f32_16x16x32_bf16 v[48:51], v[150:153], v[220:223], v[48:51]
	v_mfma_f32_16x16x32_bf16 v[44:47], v[174:177], v[220:223], v[44:47]
	v_mfma_f32_16x16x32_bf16 v[32:35], v[150:153], v[228:231], v[32:35]
	v_mfma_f32_16x16x32_bf16 v[28:31], v[174:177], v[228:231], v[28:31]
	v_mfma_f32_16x16x32_bf16 v[16:19], v[150:153], v[236:239], v[16:19]
	v_mfma_f32_16x16x32_bf16 v[12:15], v[174:177], v[236:239], v[12:15]
	v_mfma_f32_16x16x32_bf16 v[56:59], v[178:181], v[194:197], v[56:59]
	v_mfma_f32_16x16x32_bf16 v[52:55], v[186:189], v[194:197], v[52:55]
	v_mfma_f32_16x16x32_bf16 v[40:43], v[178:181], v[202:205], v[40:43]
	v_mfma_f32_16x16x32_bf16 v[36:39], v[186:189], v[202:205], v[36:39]
	v_mfma_f32_16x16x32_bf16 v[24:27], v[178:181], v[224:227], v[24:27]
	v_mfma_f32_16x16x32_bf16 v[20:23], v[186:189], v[224:227], v[20:23]
	v_mfma_f32_16x16x32_bf16 v[8:11], v[178:181], v[232:235], v[8:11]
	v_mfma_f32_16x16x32_bf16 v[4:7], v[186:189], v[232:235], v[4:7]
	v_mfma_f32_16x16x32_bf16 v[56:59], v[182:185], v[198:201], v[56:59]
	v_mfma_f32_16x16x32_bf16 v[52:55], v[190:193], v[198:201], v[52:55]
	v_mfma_f32_16x16x32_bf16 v[40:43], v[182:185], v[220:223], v[40:43]
	v_mfma_f32_16x16x32_bf16 v[36:39], v[190:193], v[220:223], v[36:39]
	v_mfma_f32_16x16x32_bf16 v[24:27], v[182:185], v[228:231], v[24:27]
	v_mfma_f32_16x16x32_bf16 v[20:23], v[190:193], v[228:231], v[20:23]
	v_mfma_f32_16x16x32_bf16 v[8:11], v[182:185], v[236:239], v[8:11]
	v_mfma_f32_16x16x32_bf16 v[4:7], v[190:193], v[236:239], v[4:7]
	s_setprio 0
	s_barrier
	s_add_i32 s53, 0, 0x18000
	v_add_u32_e32 v149, s53, v147
	s_add_i32 s54, 0, 0x1c000
	ds_read_b128 v[142:145], v149
	ds_read_b128 v[150:153], v149 offset:1024
	ds_read_b128 v[170:173], v149 offset:2048
	ds_read_b128 v[174:177], v149 offset:3072
	v_add_u32_e32 v149, s54, v147
	ds_read_b128 v[178:181], v149
	ds_read_b128 v[182:185], v149 offset:1024
	ds_read_b128 v[186:189], v149 offset:2048
	ds_read_b128 v[190:193], v149 offset:3072
	s_add_u32 s28, s28, 0x40000
	s_addc_u32 s29, s29, 0
	s_mov_b32 m0, s37
	v_lshl_add_u64 v[240:241], s[28:29], 0, v[136:137]
	ds_read_b128 v[194:197], v148 offset:32768
	ds_read_b128 v[198:201], v148 offset:33792
	ds_read_b128 v[202:205], v148 offset:34816
	ds_read_b128 v[220:223], v148 offset:35840
	ds_read_b128 v[224:227], v148 offset:36864
	ds_read_b128 v[228:231], v148 offset:37888
	ds_read_b128 v[232:235], v148 offset:38912
	ds_read_b128 v[236:239], v148 offset:39936
	global_load_lds_dwordx4 v[240:241], off
	v_lshl_add_u64 v[240:241], s[28:29], 0, v[132:133]
	s_mov_b32 m0, s38
	s_nop 0
	global_load_lds_dwordx4 v[240:241], off
	s_waitcnt vmcnt(8)
	s_waitcnt lgkmcnt(0)
	s_barrier
	s_setprio 1
	s_waitcnt lgkmcnt(0)
	v_mfma_f32_16x16x32_bf16 v[128:131], v[142:145], v[194:197], v[128:131]
	v_mfma_f32_16x16x32_bf16 v[124:127], v[170:173], v[194:197], v[124:127]
	v_mfma_f32_16x16x32_bf16 v[112:115], v[142:145], v[202:205], v[112:115]
	v_mfma_f32_16x16x32_bf16 v[108:111], v[170:173], v[202:205], v[108:111]
	v_mfma_f32_16x16x32_bf16 v[96:99], v[142:145], v[224:227], v[96:99]
	v_mfma_f32_16x16x32_bf16 v[92:95], v[170:173], v[224:227], v[92:95]
	v_mfma_f32_16x16x32_bf16 v[80:83], v[142:145], v[232:235], v[80:83]
	v_mfma_f32_16x16x32_bf16 v[76:79], v[170:173], v[232:235], v[76:79]
	v_mfma_f32_16x16x32_bf16 v[128:131], v[150:153], v[198:201], v[128:131]
	v_mfma_f32_16x16x32_bf16 v[124:127], v[174:177], v[198:201], v[124:127]
	v_mfma_f32_16x16x32_bf16 v[112:115], v[150:153], v[220:223], v[112:115]
	v_mfma_f32_16x16x32_bf16 v[108:111], v[174:177], v[220:223], v[108:111]
	v_mfma_f32_16x16x32_bf16 v[96:99], v[150:153], v[228:231], v[96:99]
	v_mfma_f32_16x16x32_bf16 v[92:95], v[174:177], v[228:231], v[92:95]
	v_mfma_f32_16x16x32_bf16 v[80:83], v[150:153], v[236:239], v[80:83]
	v_mfma_f32_16x16x32_bf16 v[76:79], v[174:177], v[236:239], v[76:79]
	v_mfma_f32_16x16x32_bf16 v[120:123], v[178:181], v[194:197], v[120:123]
	v_mfma_f32_16x16x32_bf16 v[116:119], v[186:189], v[194:197], v[116:119]
	v_mfma_f32_16x16x32_bf16 v[104:107], v[178:181], v[202:205], v[104:107]
	v_mfma_f32_16x16x32_bf16 v[100:103], v[186:189], v[202:205], v[100:103]
	v_mfma_f32_16x16x32_bf16 v[88:91], v[178:181], v[224:227], v[88:91]
	v_mfma_f32_16x16x32_bf16 v[84:87], v[186:189], v[224:227], v[84:87]
	v_mfma_f32_16x16x32_bf16 v[72:75], v[178:181], v[232:235], v[72:75]
	v_mfma_f32_16x16x32_bf16 v[68:71], v[186:189], v[232:235], v[68:71]
	v_mfma_f32_16x16x32_bf16 v[120:123], v[182:185], v[198:201], v[120:123]
	v_mfma_f32_16x16x32_bf16 v[116:119], v[190:193], v[198:201], v[116:119]
	v_mfma_f32_16x16x32_bf16 v[104:107], v[182:185], v[220:223], v[104:107]
	v_mfma_f32_16x16x32_bf16 v[100:103], v[190:193], v[220:223], v[100:103]
	v_mfma_f32_16x16x32_bf16 v[88:91], v[182:185], v[228:231], v[88:91]
	v_mfma_f32_16x16x32_bf16 v[84:87], v[190:193], v[228:231], v[84:87]
	v_mfma_f32_16x16x32_bf16 v[72:75], v[182:185], v[236:239], v[72:75]
	v_mfma_f32_16x16x32_bf16 v[68:71], v[190:193], v[236:239], v[68:71]
	s_setprio 0
	s_barrier
	s_add_i32 s28, s53, s34
	v_lshl_add_u64 v[154:155], v[154:155], 0, s[76:77]
	s_mov_b32 m0, s28
	ds_read_b128 v[194:197], v148 offset:49152
	ds_read_b128 v[198:201], v148 offset:50176
	ds_read_b128 v[202:205], v148 offset:51200
	ds_read_b128 v[220:223], v148 offset:52224
	ds_read_b128 v[224:227], v148 offset:53248
	ds_read_b128 v[228:231], v148 offset:54272
	ds_read_b128 v[232:235], v148 offset:55296
	ds_read_b128 v[236:239], v148 offset:56320
	global_load_lds_dwordx4 v[154:155], off
	s_add_i32 m0, s28, 0x2000
	s_add_u32 s26, s26, 0x40080
	v_lshl_add_u64 v[154:155], v[158:159], 0, s[76:77]
	s_addc_u32 s27, s27, 0
	s_add_i32 s28, s54, s34
	global_load_lds_dwordx4 v[154:155], off
	v_lshl_add_u64 v[154:155], s[26:27], 0, v[134:135]
	s_mov_b32 m0, s28
	s_nop 0
	global_load_lds_dwordx4 v[154:155], off
	v_lshl_add_u64 v[154:155], s[26:27], 0, v[0:1]
	s_add_i32 m0, s28, 0x2000
	s_nop 0
	global_load_lds_dwordx4 v[154:155], off
	v_lshl_add_u64 v[154:155], v[160:161], 0, s[76:77]
	s_mov_b32 m0, s41
	s_nop 0
	global_load_lds_dwordx4 v[154:155], off
	v_lshl_add_u64 v[154:155], v[206:207], 0, s[76:77]
	s_mov_b32 m0, s42
	s_nop 0
	global_load_lds_dwordx4 v[154:155], off
	s_waitcnt vmcnt(8)
	s_waitcnt lgkmcnt(0)
	s_barrier
	s_setprio 1
	s_waitcnt lgkmcnt(0)
	v_mfma_f32_16x16x32_bf16 v[64:67], v[142:145], v[194:197], v[64:67]
	v_mfma_f32_16x16x32_bf16 v[60:63], v[170:173], v[194:197], v[60:63]
	v_mfma_f32_16x16x32_bf16 v[48:51], v[142:145], v[202:205], v[48:51]
	v_mfma_f32_16x16x32_bf16 v[44:47], v[170:173], v[202:205], v[44:47]
	v_mfma_f32_16x16x32_bf16 v[32:35], v[142:145], v[224:227], v[32:35]
	v_mfma_f32_16x16x32_bf16 v[28:31], v[170:173], v[224:227], v[28:31]
	v_mfma_f32_16x16x32_bf16 v[16:19], v[142:145], v[232:235], v[16:19]
	v_mfma_f32_16x16x32_bf16 v[12:15], v[170:173], v[232:235], v[12:15]
	v_mfma_f32_16x16x32_bf16 v[64:67], v[150:153], v[198:201], v[64:67]
	v_mfma_f32_16x16x32_bf16 v[60:63], v[174:177], v[198:201], v[60:63]
	v_mfma_f32_16x16x32_bf16 v[48:51], v[150:153], v[220:223], v[48:51]
	v_mfma_f32_16x16x32_bf16 v[44:47], v[174:177], v[220:223], v[44:47]
	v_mfma_f32_16x16x32_bf16 v[32:35], v[150:153], v[228:231], v[32:35]
	v_mfma_f32_16x16x32_bf16 v[28:31], v[174:177], v[228:231], v[28:31]
	v_mfma_f32_16x16x32_bf16 v[16:19], v[150:153], v[236:239], v[16:19]
	v_mfma_f32_16x16x32_bf16 v[12:15], v[174:177], v[236:239], v[12:15]
	v_mfma_f32_16x16x32_bf16 v[56:59], v[178:181], v[194:197], v[56:59]
	v_mfma_f32_16x16x32_bf16 v[52:55], v[186:189], v[194:197], v[52:55]
	v_mfma_f32_16x16x32_bf16 v[40:43], v[178:181], v[202:205], v[40:43]
	v_mfma_f32_16x16x32_bf16 v[36:39], v[186:189], v[202:205], v[36:39]
	v_mfma_f32_16x16x32_bf16 v[24:27], v[178:181], v[224:227], v[24:27]
	v_mfma_f32_16x16x32_bf16 v[20:23], v[186:189], v[224:227], v[20:23]
	v_mfma_f32_16x16x32_bf16 v[8:11], v[178:181], v[232:235], v[8:11]
	v_mfma_f32_16x16x32_bf16 v[4:7], v[186:189], v[232:235], v[4:7]
	v_mfma_f32_16x16x32_bf16 v[56:59], v[182:185], v[198:201], v[56:59]
	v_mfma_f32_16x16x32_bf16 v[52:55], v[190:193], v[198:201], v[52:55]
	v_mfma_f32_16x16x32_bf16 v[40:43], v[182:185], v[220:223], v[40:43]
	v_mfma_f32_16x16x32_bf16 v[36:39], v[190:193], v[220:223], v[36:39]
	v_mfma_f32_16x16x32_bf16 v[24:27], v[182:185], v[228:231], v[24:27]
	v_mfma_f32_16x16x32_bf16 v[20:23], v[190:193], v[228:231], v[20:23]
	v_mfma_f32_16x16x32_bf16 v[8:11], v[182:185], v[236:239], v[8:11]
	v_mfma_f32_16x16x32_bf16 v[4:7], v[190:193], v[236:239], v[4:7]
	s_setprio 0
	s_barrier
	s_add_i32 s52, s52, 2
	s_add_u32 s10, s10, 0x100
	s_addc_u32 s11, s11, 0
	s_add_u32 s50, s50, 0x100
	s_addc_u32 s51, s51, 0
	s_cmp_gt_u32 s52, 13
	s_cbranch_scc0 .LBB0_605
	s_lshl_b32 s29, s47, 8
	s_add_i32 s29, s29, s39
	v_add_u32_e32 v155, s29, v3
	s_lshl_b32 s29, s46, 8
	s_or_b32 s29, s29, s40
	v_lshlrev_b32_e32 v149, 10, v155
	v_lshlrev_b32_e32 v154, 6, v155
	v_lshl_add_u32 v155, v146, 3, s29
	v_add_u32_e32 v149, v149, v155
	v_lshlrev_b32_e32 v149, 1, v149
	v_cmp_eq_u32_e64 s[50:51], 0, v146
	s_lshl_b32 s29, s46, 4
	s_add_u32 s26, s43, s29
	s_addc_u32 s27, s44, 0
	s_add_u32 s54, s26, 0x2000
	s_addc_u32 s55, s27, 0
	s_mov_b64 s[10:11], s[14:15]
	global_load_dwordx4 v[170:173], v149, s[10:11]
	global_load_dwordx4 v[174:177], v149, s[10:11] offset:256
	s_add_u32 s10, s10, 0x8000
	s_addc_u32 s11, s11, 0
	global_load_dwordx4 v[178:181], v149, s[10:11]
	global_load_dwordx4 v[182:185], v149, s[10:11] offset:256
	s_add_u32 s10, s10, 0x8000
	s_addc_u32 s11, s11, 0
	global_load_dwordx4 v[186:189], v149, s[10:11]
	global_load_dwordx4 v[190:193], v149, s[10:11] offset:256
	s_add_u32 s10, s10, 0x8000
	s_addc_u32 s11, s11, 0
	global_load_dwordx4 v[194:197], v149, s[10:11]
	global_load_dwordx4 v[198:201], v149, s[10:11] offset:256
	s_add_u32 s10, s10, 0x28000
	s_addc_u32 s11, s11, 0
	global_load_dwordx4 v[202:205], v149, s[10:11]
	global_load_dwordx4 v[220:223], v149, s[10:11] offset:256
	s_add_u32 s10, s10, 0x8000
	s_addc_u32 s11, s11, 0
	global_load_dwordx4 v[224:227], v149, s[10:11]
	global_load_dwordx4 v[228:231], v149, s[10:11] offset:256
	s_add_u32 s10, s10, 0x8000
	s_addc_u32 s11, s11, 0
	global_load_dwordx4 v[232:235], v149, s[10:11]
	global_load_dwordx4 v[236:239], v149, s[10:11] offset:256
	s_add_u32 s10, s10, 0x8000
	s_addc_u32 s11, s11, 0
	global_load_dwordx4 v[150:153], v149, s[10:11]
	global_load_dwordx4 v[142:145], v149, s[10:11] offset:256
	s_and_b64 vcc, exec, s[16:17]
	s_cbranch_vccz .Lres5_nobar
	s_barrier

.LBB0_679:
	s_add_u32 s14, s10, 0xfffc0080
	s_addc_u32 s15, s11, -1
	s_and_b64 s[12:13], s[12:13], exec
	s_cselect_b32 s15, s17, s15
	s_cselect_b32 s14, s43, s14
	s_cselect_b32 s13, s41, s51
	s_cselect_b32 s12, s49, s50
	s_add_i32 s53, 0, 0x10000
	v_add_u32_e32 v3, s53, v207
	s_add_i32 s56, 0, 0x14000
	ds_read_b128 v[134:137], v3
	ds_read_b128 v[138:141], v3 offset:1024
	ds_read_b128 v[142:145], v3 offset:2048
	ds_read_b128 v[146:149], v3 offset:3072
	v_add_u32_e32 v3, s56, v207
	ds_read_b128 v[150:153], v3
	ds_read_b128 v[158:161], v3 offset:1024
	ds_read_b128 v[184:187], v3 offset:2048
	ds_read_b128 v[188:191], v3 offset:3072
	v_lshl_add_u64 v[154:155], s[10:11], 0, v[178:179]
	s_add_i32 m0, s71, 0xc000
	ds_read_b128 v[192:195], v220
	ds_read_b128 v[196:199], v220 offset:1024
	ds_read_b128 v[200:203], v220 offset:2048
	ds_read_b128 v[222:225], v220 offset:3072
	ds_read_b128 v[226:229], v220 offset:4096
	ds_read_b128 v[230:233], v220 offset:5120
	ds_read_b128 v[234:237], v220 offset:6144
	ds_read_b128 v[238:241], v220 offset:7168
	global_load_lds_dwordx4 v[154:155], off
	v_lshl_add_u64 v[154:155], s[10:11], 0, v[180:181]
	s_add_i32 m0, s71, 0xe000
	s_nop 0
	global_load_lds_dwordx4 v[154:155], off
	s_waitcnt vmcnt(8)
	s_waitcnt lgkmcnt(0)
	s_barrier
	s_setprio 1
	s_waitcnt lgkmcnt(0)
	v_mfma_f32_16x16x32_bf16 v[128:131], v[134:137], v[192:195], v[128:131]
	v_mfma_f32_16x16x32_bf16 v[96:99], v[142:145], v[192:195], v[96:99]
	v_mfma_f32_16x16x32_bf16 v[124:127], v[134:137], v[200:203], v[124:127]
	v_mfma_f32_16x16x32_bf16 v[92:95], v[142:145], v[200:203], v[92:95]
	v_mfma_f32_16x16x32_bf16 v[120:123], v[134:137], v[226:229], v[120:123]
	v_mfma_f32_16x16x32_bf16 v[88:91], v[142:145], v[226:229], v[88:91]
	v_mfma_f32_16x16x32_bf16 v[116:119], v[134:137], v[234:237], v[116:119]
	v_mfma_f32_16x16x32_bf16 v[84:87], v[142:145], v[234:237], v[84:87]
	v_mfma_f32_16x16x32_bf16 v[128:131], v[138:141], v[196:199], v[128:131]
	v_mfma_f32_16x16x32_bf16 v[96:99], v[146:149], v[196:199], v[96:99]
	v_mfma_f32_16x16x32_bf16 v[124:127], v[138:141], v[222:225], v[124:127]
	v_mfma_f32_16x16x32_bf16 v[92:95], v[146:149], v[222:225], v[92:95]
	v_mfma_f32_16x16x32_bf16 v[120:123], v[138:141], v[230:233], v[120:123]
	v_mfma_f32_16x16x32_bf16 v[88:91], v[146:149], v[230:233], v[88:91]
	v_mfma_f32_16x16x32_bf16 v[116:119], v[138:141], v[238:241], v[116:119]
	v_mfma_f32_16x16x32_bf16 v[84:87], v[146:149], v[238:241], v[84:87]
	v_mfma_f32_16x16x32_bf16 v[112:115], v[150:153], v[192:195], v[112:115]
	v_mfma_f32_16x16x32_bf16 v[80:83], v[184:187], v[192:195], v[80:83]
	v_mfma_f32_16x16x32_bf16 v[108:111], v[150:153], v[200:203], v[108:111]
	v_mfma_f32_16x16x32_bf16 v[76:79], v[184:187], v[200:203], v[76:79]
	v_mfma_f32_16x16x32_bf16 v[104:107], v[150:153], v[226:229], v[104:107]
	v_mfma_f32_16x16x32_bf16 v[72:75], v[184:187], v[226:229], v[72:75]
	v_mfma_f32_16x16x32_bf16 v[100:103], v[150:153], v[234:237], v[100:103]
	v_mfma_f32_16x16x32_bf16 v[68:71], v[184:187], v[234:237], v[68:71]
	v_mfma_f32_16x16x32_bf16 v[112:115], v[158:161], v[196:199], v[112:115]
	v_mfma_f32_16x16x32_bf16 v[80:83], v[188:191], v[196:199], v[80:83]
	v_mfma_f32_16x16x32_bf16 v[108:111], v[158:161], v[222:225], v[108:111]
	v_mfma_f32_16x16x32_bf16 v[76:79], v[188:191], v[222:225], v[76:79]
	v_mfma_f32_16x16x32_bf16 v[104:107], v[158:161], v[230:233], v[104:107]
	v_mfma_f32_16x16x32_bf16 v[72:75], v[188:191], v[230:233], v[72:75]
	v_mfma_f32_16x16x32_bf16 v[100:103], v[158:161], v[238:241], v[100:103]
	v_mfma_f32_16x16x32_bf16 v[68:71], v[188:191], v[238:241], v[68:71]
	s_setprio 0
	s_barrier
	s_add_i32 s53, s53, s54
	v_lshl_add_u64 v[154:155], s[12:13], 0, v[172:173]
	s_mov_b32 m0, s53
	ds_read_b128 v[192:195], v220 offset:16384
	ds_read_b128 v[196:199], v220 offset:17408
	ds_read_b128 v[200:203], v220 offset:18432
	ds_read_b128 v[222:225], v220 offset:19456
	ds_read_b128 v[226:229], v220 offset:20480
	ds_read_b128 v[230:233], v220 offset:21504
	ds_read_b128 v[234:237], v220 offset:22528
	ds_read_b128 v[238:241], v220 offset:23552
	global_load_lds_dwordx4 v[154:155], off
	s_add_i32 m0, s53, 0x2000
	s_add_u32 vcc_lo, s12, 0x40000
	v_lshl_add_u64 v[204:205], s[12:13], 0, v[0:1]
	s_addc_u32 vcc_hi, s13, 0
	s_add_i32 s53, s56, s54
	global_load_lds_dwordx4 v[204:205], off
	v_lshl_add_u64 v[242:243], vcc, 0, v[172:173]
	s_mov_b32 m0, s53
	v_lshl_add_u64 v[244:245], s[14:15], 0, v[170:171]
	global_load_lds_dwordx4 v[242:243], off
	v_lshl_add_u64 v[242:243], vcc, 0, v[0:1]
	s_add_i32 m0, s53, 0x2000
	s_nop 0
	global_load_lds_dwordx4 v[242:243], off
	v_lshl_add_u64 v[242:243], s[14:15], 0, v[174:175]
	s_mov_b32 m0, s71
	s_nop 0
	global_load_lds_dwordx4 v[242:243], off
	s_mov_b32 m0, s72
	s_nop 0
	global_load_lds_dwordx4 v[244:245], off
	s_waitcnt vmcnt(8)
	s_waitcnt lgkmcnt(0)
	s_barrier
	s_setprio 1
	s_waitcnt lgkmcnt(0)
	v_mfma_f32_16x16x32_bf16 v[64:67], v[134:137], v[192:195], v[64:67]
	v_mfma_f32_16x16x32_bf16 v[32:35], v[142:145], v[192:195], v[32:35]
	v_mfma_f32_16x16x32_bf16 v[60:63], v[134:137], v[200:203], v[60:63]
	v_mfma_f32_16x16x32_bf16 v[28:31], v[142:145], v[200:203], v[28:31]
	v_mfma_f32_16x16x32_bf16 v[56:59], v[134:137], v[226:229], v[56:59]
	v_mfma_f32_16x16x32_bf16 v[24:27], v[142:145], v[226:229], v[24:27]
	v_mfma_f32_16x16x32_bf16 v[52:55], v[134:137], v[234:237], v[52:55]
	v_mfma_f32_16x16x32_bf16 v[20:23], v[142:145], v[234:237], v[20:23]
	v_mfma_f32_16x16x32_bf16 v[64:67], v[138:141], v[196:199], v[64:67]
	v_mfma_f32_16x16x32_bf16 v[32:35], v[146:149], v[196:199], v[32:35]
	v_mfma_f32_16x16x32_bf16 v[60:63], v[138:141], v[222:225], v[60:63]
	v_mfma_f32_16x16x32_bf16 v[28:31], v[146:149], v[222:225], v[28:31]
	v_mfma_f32_16x16x32_bf16 v[56:59], v[138:141], v[230:233], v[56:59]
	v_mfma_f32_16x16x32_bf16 v[24:27], v[146:149], v[230:233], v[24:27]
	v_mfma_f32_16x16x32_bf16 v[52:55], v[138:141], v[238:241], v[52:55]
	v_mfma_f32_16x16x32_bf16 v[20:23], v[146:149], v[238:241], v[20:23]
	v_mfma_f32_16x16x32_bf16 v[48:51], v[150:153], v[192:195], v[48:51]
	v_mfma_f32_16x16x32_bf16 v[16:19], v[184:187], v[192:195], v[16:19]
	v_mfma_f32_16x16x32_bf16 v[44:47], v[150:153], v[200:203], v[44:47]
	v_mfma_f32_16x16x32_bf16 v[12:15], v[184:187], v[200:203], v[12:15]
	v_mfma_f32_16x16x32_bf16 v[40:43], v[150:153], v[226:229], v[40:43]
	v_mfma_f32_16x16x32_bf16 v[8:11], v[184:187], v[226:229], v[8:11]
	v_mfma_f32_16x16x32_bf16 v[36:39], v[150:153], v[234:237], v[36:39]
	v_mfma_f32_16x16x32_bf16 v[4:7], v[184:187], v[234:237], v[4:7]
	v_mfma_f32_16x16x32_bf16 v[48:51], v[158:161], v[196:199], v[48:51]
	v_mfma_f32_16x16x32_bf16 v[16:19], v[188:191], v[196:199], v[16:19]
	v_mfma_f32_16x16x32_bf16 v[44:47], v[158:161], v[222:225], v[44:47]
	v_mfma_f32_16x16x32_bf16 v[12:15], v[188:191], v[222:225], v[12:15]
	v_mfma_f32_16x16x32_bf16 v[40:43], v[158:161], v[230:233], v[40:43]
	v_mfma_f32_16x16x32_bf16 v[8:11], v[188:191], v[230:233], v[8:11]
	v_mfma_f32_16x16x32_bf16 v[36:39], v[158:161], v[238:241], v[36:39]
	v_mfma_f32_16x16x32_bf16 v[4:7], v[188:191], v[238:241], v[4:7]
	s_setprio 0
	s_barrier
	s_add_i32 s53, 0, 0x18000
	v_add_u32_e32 v3, s53, v207
	s_add_i32 s56, 0, 0x1c000
	ds_read_b128 v[134:137], v3
	ds_read_b128 v[138:141], v3 offset:1024
	ds_read_b128 v[142:145], v3 offset:2048
	ds_read_b128 v[146:149], v3 offset:3072
	v_add_u32_e32 v3, s56, v207
	ds_read_b128 v[150:153], v3
	ds_read_b128 v[158:161], v3 offset:1024
	ds_read_b128 v[184:187], v3 offset:2048
	ds_read_b128 v[188:191], v3 offset:3072
	s_add_u32 s14, s14, 0x40000
	s_addc_u32 s15, s15, 0
	s_mov_b32 m0, s73
	v_lshl_add_u64 v[246:247], s[14:15], 0, v[174:175]
	ds_read_b128 v[192:195], v220 offset:32768
	ds_read_b128 v[196:199], v220 offset:33792
	ds_read_b128 v[200:203], v220 offset:34816
	ds_read_b128 v[222:225], v220 offset:35840
	ds_read_b128 v[226:229], v220 offset:36864
	ds_read_b128 v[230:233], v220 offset:37888
	ds_read_b128 v[234:237], v220 offset:38912
	ds_read_b128 v[238:241], v220 offset:39936
	global_load_lds_dwordx4 v[246:247], off
	v_lshl_add_u64 v[246:247], s[14:15], 0, v[170:171]
	s_mov_b32 m0, s78
	s_nop 0
	global_load_lds_dwordx4 v[246:247], off
	s_waitcnt vmcnt(8)
	s_waitcnt lgkmcnt(0)
	s_barrier
	s_setprio 1
	s_waitcnt lgkmcnt(0)
	v_mfma_f32_16x16x32_bf16 v[128:131], v[134:137], v[192:195], v[128:131]
	v_mfma_f32_16x16x32_bf16 v[96:99], v[142:145], v[192:195], v[96:99]
	v_mfma_f32_16x16x32_bf16 v[124:127], v[134:137], v[200:203], v[124:127]
	v_mfma_f32_16x16x32_bf16 v[92:95], v[142:145], v[200:203], v[92:95]
	v_mfma_f32_16x16x32_bf16 v[120:123], v[134:137], v[226:229], v[120:123]
	v_mfma_f32_16x16x32_bf16 v[88:91], v[142:145], v[226:229], v[88:91]
	v_mfma_f32_16x16x32_bf16 v[116:119], v[134:137], v[234:237], v[116:119]
	v_mfma_f32_16x16x32_bf16 v[84:87], v[142:145], v[234:237], v[84:87]
	v_mfma_f32_16x16x32_bf16 v[128:131], v[138:141], v[196:199], v[128:131]
	v_mfma_f32_16x16x32_bf16 v[96:99], v[146:149], v[196:199], v[96:99]
	v_mfma_f32_16x16x32_bf16 v[124:127], v[138:141], v[222:225], v[124:127]
	v_mfma_f32_16x16x32_bf16 v[92:95], v[146:149], v[222:225], v[92:95]
	v_mfma_f32_16x16x32_bf16 v[120:123], v[138:141], v[230:233], v[120:123]
	v_mfma_f32_16x16x32_bf16 v[88:91], v[146:149], v[230:233], v[88:91]
	v_mfma_f32_16x16x32_bf16 v[116:119], v[138:141], v[238:241], v[116:119]
	v_mfma_f32_16x16x32_bf16 v[84:87], v[146:149], v[238:241], v[84:87]
	v_mfma_f32_16x16x32_bf16 v[112:115], v[150:153], v[192:195], v[112:115]
	v_mfma_f32_16x16x32_bf16 v[80:83], v[184:187], v[192:195], v[80:83]
	v_mfma_f32_16x16x32_bf16 v[108:111], v[150:153], v[200:203], v[108:111]
	v_mfma_f32_16x16x32_bf16 v[76:79], v[184:187], v[200:203], v[76:79]
	v_mfma_f32_16x16x32_bf16 v[104:107], v[150:153], v[226:229], v[104:107]
	v_mfma_f32_16x16x32_bf16 v[72:75], v[184:187], v[226:229], v[72:75]
	v_mfma_f32_16x16x32_bf16 v[100:103], v[150:153], v[234:237], v[100:103]
	v_mfma_f32_16x16x32_bf16 v[68:71], v[184:187], v[234:237], v[68:71]
	v_mfma_f32_16x16x32_bf16 v[112:115], v[158:161], v[196:199], v[112:115]
	v_mfma_f32_16x16x32_bf16 v[80:83], v[188:191], v[196:199], v[80:83]
	v_mfma_f32_16x16x32_bf16 v[108:111], v[158:161], v[222:225], v[108:111]
	v_mfma_f32_16x16x32_bf16 v[76:79], v[188:191], v[222:225], v[76:79]
	v_mfma_f32_16x16x32_bf16 v[104:107], v[158:161], v[230:233], v[104:107]
	v_mfma_f32_16x16x32_bf16 v[72:75], v[188:191], v[230:233], v[72:75]
	v_mfma_f32_16x16x32_bf16 v[100:103], v[158:161], v[238:241], v[100:103]
	v_mfma_f32_16x16x32_bf16 v[68:71], v[188:191], v[238:241], v[68:71]
	s_setprio 0
	s_barrier
	s_add_i32 s14, s53, s54
	v_lshl_add_u64 v[154:155], v[154:155], 0, s[76:77]
	s_mov_b32 m0, s14
	ds_read_b128 v[192:195], v220 offset:49152
	ds_read_b128 v[196:199], v220 offset:50176
	ds_read_b128 v[200:203], v220 offset:51200
	ds_read_b128 v[222:225], v220 offset:52224
	ds_read_b128 v[226:229], v220 offset:53248
	ds_read_b128 v[230:233], v220 offset:54272
	ds_read_b128 v[234:237], v220 offset:55296
	ds_read_b128 v[238:241], v220 offset:56320
	global_load_lds_dwordx4 v[154:155], off
	s_add_i32 m0, s14, 0x2000
	s_add_u32 s12, s12, 0x40080
	v_lshl_add_u64 v[154:155], v[204:205], 0, s[76:77]
	s_addc_u32 s13, s13, 0
	s_add_i32 s14, s56, s54
	global_load_lds_dwordx4 v[154:155], off
	v_lshl_add_u64 v[154:155], s[12:13], 0, v[172:173]
	s_mov_b32 m0, s14
	s_nop 0
	global_load_lds_dwordx4 v[154:155], off
	v_lshl_add_u64 v[154:155], s[12:13], 0, v[0:1]
	s_add_i32 m0, s14, 0x2000
	s_nop 0
	global_load_lds_dwordx4 v[154:155], off
	v_lshl_add_u64 v[154:155], v[242:243], 0, s[76:77]
	s_mov_b32 m0, s85
	s_nop 0
	global_load_lds_dwordx4 v[154:155], off
	v_lshl_add_u64 v[154:155], v[244:245], 0, s[76:77]
	s_mov_b32 m0, s86
	s_nop 0
	global_load_lds_dwordx4 v[154:155], off
	s_waitcnt vmcnt(8)
	s_waitcnt lgkmcnt(0)
	s_barrier
	s_setprio 1
	s_waitcnt lgkmcnt(0)
	v_mfma_f32_16x16x32_bf16 v[64:67], v[134:137], v[192:195], v[64:67]
	v_mfma_f32_16x16x32_bf16 v[32:35], v[142:145], v[192:195], v[32:35]
	v_mfma_f32_16x16x32_bf16 v[60:63], v[134:137], v[200:203], v[60:63]
	v_mfma_f32_16x16x32_bf16 v[28:31], v[142:145], v[200:203], v[28:31]
	v_mfma_f32_16x16x32_bf16 v[56:59], v[134:137], v[226:229], v[56:59]
	v_mfma_f32_16x16x32_bf16 v[24:27], v[142:145], v[226:229], v[24:27]
	v_mfma_f32_16x16x32_bf16 v[52:55], v[134:137], v[234:237], v[52:55]
	v_mfma_f32_16x16x32_bf16 v[20:23], v[142:145], v[234:237], v[20:23]
	v_mfma_f32_16x16x32_bf16 v[64:67], v[138:141], v[196:199], v[64:67]
	v_mfma_f32_16x16x32_bf16 v[32:35], v[146:149], v[196:199], v[32:35]
	v_mfma_f32_16x16x32_bf16 v[60:63], v[138:141], v[222:225], v[60:63]
	v_mfma_f32_16x16x32_bf16 v[28:31], v[146:149], v[222:225], v[28:31]
	v_mfma_f32_16x16x32_bf16 v[56:59], v[138:141], v[230:233], v[56:59]
	v_mfma_f32_16x16x32_bf16 v[24:27], v[146:149], v[230:233], v[24:27]
	v_mfma_f32_16x16x32_bf16 v[52:55], v[138:141], v[238:241], v[52:55]
	v_mfma_f32_16x16x32_bf16 v[20:23], v[146:149], v[238:241], v[20:23]
	v_mfma_f32_16x16x32_bf16 v[48:51], v[150:153], v[192:195], v[48:51]
	v_mfma_f32_16x16x32_bf16 v[16:19], v[184:187], v[192:195], v[16:19]
	v_mfma_f32_16x16x32_bf16 v[44:47], v[150:153], v[200:203], v[44:47]
	v_mfma_f32_16x16x32_bf16 v[12:15], v[184:187], v[200:203], v[12:15]
	v_mfma_f32_16x16x32_bf16 v[40:43], v[150:153], v[226:229], v[40:43]
	v_mfma_f32_16x16x32_bf16 v[8:11], v[184:187], v[226:229], v[8:11]
	v_mfma_f32_16x16x32_bf16 v[36:39], v[150:153], v[234:237], v[36:39]
	v_mfma_f32_16x16x32_bf16 v[4:7], v[184:187], v[234:237], v[4:7]
	v_mfma_f32_16x16x32_bf16 v[48:51], v[158:161], v[196:199], v[48:51]
	v_mfma_f32_16x16x32_bf16 v[16:19], v[188:191], v[196:199], v[16:19]
	v_mfma_f32_16x16x32_bf16 v[44:47], v[158:161], v[222:225], v[44:47]
	v_mfma_f32_16x16x32_bf16 v[12:15], v[188:191], v[222:225], v[12:15]
	v_mfma_f32_16x16x32_bf16 v[40:43], v[158:161], v[230:233], v[40:43]
	v_mfma_f32_16x16x32_bf16 v[8:11], v[188:191], v[230:233], v[8:11]
	v_mfma_f32_16x16x32_bf16 v[36:39], v[158:161], v[238:241], v[36:39]
	v_mfma_f32_16x16x32_bf16 v[4:7], v[188:191], v[238:241], v[4:7]
	s_setprio 0
	s_barrier
	s_add_i32 s52, s52, 2
	s_add_u32 s10, s10, 0x100
	s_addc_u32 s11, s11, 0
	s_add_u32 s50, s50, 0x100
	s_addc_u32 s51, s51, 0
	s_cmp_gt_u32 s52, 13
	s_cbranch_scc1 .LBB0_682

.LBB0_700:
	s_or_b64 exec, exec, s[52:53]
	v_mul_f32_e32 v113, 0xbfb8aa3b, v132
	v_exp_f32_e32 v113, v113
	v_ashrrev_i32_e32 v138, 6, v197
	v_ashrrev_i32_e32 v139, 31, v138
	v_ashrrev_i32_e32 v197, 31, v196
	v_add_f32_e32 v113, 1.0, v113
	v_rcp_f32_e32 v113, v113
	v_and_b32_e32 v148, 56, v229
	v_mov_b32_e32 v191, v190
	v_pk_mul_f32 v[108:109], v[108:109], v[190:191]
	v_mul_f32_e32 v113, v132, v113
	v_mul_f32_e32 v112, v113, v112
	v_mul_f32_e32 v113, 0xbfb8aa3b, v205
	v_exp_f32_e32 v113, v113
	v_mov_b32_e32 v189, v188
	s_movk_i32 s19, 0x1000
	v_mov_b32_e32 v187, v186
	v_add_f32_e32 v113, 1.0, v113
	v_rcp_f32_e32 v113, v113
	s_mov_b32 s57, 0x42fc0000
	v_mul_f32_e32 v113, v205, v113
	v_mul_f32_e32 v113, v113, v149
	v_cvt_pk_bf16_f32 v112, v112, v113
	v_mul_f32_e32 v113, 0xbfb8aa3b, v134
	v_exp_f32_e32 v113, v113
	s_nop 0
	v_add_f32_e32 v113, 1.0, v113
	v_rcp_f32_e32 v113, v113
	s_nop 0
	v_mul_f32_e32 v113, v134, v113
	v_mul_f32_e32 v113, v113, v114
	v_mul_f32_e32 v114, 0xbfb8aa3b, v203
	v_exp_f32_e32 v114, v114
	s_nop 0
	v_add_f32_e32 v114, 1.0, v114
	v_rcp_f32_e32 v114, v114
	s_nop 0
	v_mul_f32_e32 v114, v203, v114
	v_mul_f32_e32 v114, v114, v133
	v_cvt_pk_bf16_f32 v113, v113, v114
	v_mad_u64_u32 v[114:115], s[48:49], v136, 44, v[138:139]
	v_mov_b32_e32 v132, v115
	v_mad_u64_u32 v[132:133], s[48:49], v137, 44, v[132:133]
	v_mov_b32_e32 v115, v132
	v_lshlrev_b64 v[114:115], 15, v[114:115]
	v_lshlrev_b64 v[132:133], 7, v[196:197]
	v_lshl_add_u64 v[114:115], s[20:21], 0, v[114:115]
	v_lshl_add_u64 v[134:135], v[114:115], 0, v[132:133]
	v_lshlrev_b32_e32 v138, 1, v148
	v_mov_b32_e32 v139, v2
	v_lshl_add_u64 v[132:133], v[134:135], 0, v[138:139]
	v_mul_f32_e32 v139, 0xbfb8aa3b, v200
	v_exp_f32_e32 v139, v139
	v_mov_b32_e32 v232, v112
	v_mov_b32_e32 v233, v113
	v_mov_b32_e32 v112, v190
	v_mov_b32_e32 v113, v190
	v_add_f32_e32 v139, 1.0, v139
	v_rcp_f32_e32 v139, v139
	v_pk_mul_f32 v[110:111], v[110:111], v[112:113]
	v_pk_fma_f32 v[114:115], v[108:109], v[124:125], v[128:129]
	v_pk_fma_f32 v[112:113], v[110:111], v[126:127], v[130:131]
	v_mul_f32_e32 v139, v200, v139
	s_nop 1
	v_fmac_f32_dpp v114, v108, v120 row_shr:1 row_mask:0xf bank_mask:0xf bound_ctrl:0
	v_fmac_f32_dpp v115, v109, v121 row_shr:1 row_mask:0xf bank_mask:0xf bound_ctrl:0
	v_fmac_f32_dpp v112, v110, v122 row_shr:1 row_mask:0xf bank_mask:0xf bound_ctrl:0
	v_fmac_f32_dpp v113, v111, v123 row_shr:1 row_mask:0xf bank_mask:0xf bound_ctrl:0
	v_fmac_f32_dpp v114, v108, v116 row_shr:2 row_mask:0xf bank_mask:0xf bound_ctrl:0
	v_fmac_f32_dpp v115, v109, v117 row_shr:2 row_mask:0xf bank_mask:0xf bound_ctrl:0
	v_fmac_f32_dpp v112, v110, v118 row_shr:2 row_mask:0xf bank_mask:0xf bound_ctrl:0
	v_fmac_f32_dpp v113, v111, v119 row_shr:2 row_mask:0xf bank_mask:0xf bound_ctrl:0
	v_fmac_f32_dpp v114, v142, v120 row_shl:15 row_mask:0xf bank_mask:0xf bound_ctrl:0
	v_fmac_f32_dpp v115, v143, v121 row_shl:15 row_mask:0xf bank_mask:0xf bound_ctrl:0
	v_fmac_f32_dpp v112, v140, v122 row_shl:15 row_mask:0xf bank_mask:0xf bound_ctrl:0
	v_fmac_f32_dpp v113, v141, v123 row_shl:15 row_mask:0xf bank_mask:0xf bound_ctrl:0
	v_fmac_f32_dpp v114, v142, v116 row_shl:14 row_mask:0xf bank_mask:0xf bound_ctrl:0
	v_fmac_f32_dpp v115, v143, v117 row_shl:14 row_mask:0xf bank_mask:0xf bound_ctrl:0
	v_fmac_f32_dpp v112, v140, v118 row_shl:14 row_mask:0xf bank_mask:0xf bound_ctrl:0
	v_fmac_f32_dpp v113, v141, v119 row_shl:14 row_mask:0xf bank_mask:0xf bound_ctrl:0
	v_add_co_u32_e32 v140, vcc, s19, v132
	v_mul_f32_e32 v114, v139, v114
	v_mul_f32_e32 v139, 0xbfb8aa3b, v201
	v_exp_f32_e32 v139, v139
	v_addc_co_u32_e32 v141, vcc, 0, v133, vcc
	s_and_b64 vcc, exec, s[14:15]
	v_add_f32_e32 v139, 1.0, v139
	v_rcp_f32_e32 v139, v139
	s_nop 0
	v_mul_f32_e32 v139, v201, v139
	v_mul_f32_e32 v115, v139, v115
	v_cvt_pk_bf16_f32 v114, v114, v115
	v_mul_f32_e32 v115, 0xbfb8aa3b, v198
	v_exp_f32_e32 v115, v115
	s_nop 0
	v_add_f32_e32 v115, 1.0, v115
	v_rcp_f32_e32 v115, v115
	s_nop 0
	v_mul_f32_e32 v115, v198, v115
	v_mul_f32_e32 v112, v115, v112
	v_mul_f32_e32 v115, 0xbfb8aa3b, v199
	v_exp_f32_e32 v115, v115
	s_nop 0
	v_add_f32_e32 v115, 1.0, v115
	v_rcp_f32_e32 v115, v115
	s_nop 0
	v_mul_f32_e32 v115, v199, v115
	v_mul_f32_e32 v113, v115, v113
	v_cvt_pk_bf16_f32 v115, v112, v113
	v_mov_b32_e32 v112, v188
	v_mov_b32_e32 v113, v188
	v_mov_b32_e32 v236, v114
	v_mov_b32_e32 v237, v115
	v_pk_mul_f32 v[112:113], v[106:107], v[112:113]
	v_pk_mul_f32 v[114:115], v[104:105], v[188:189]
	v_pk_fma_f32 v[104:105], v[112:113], v[126:127], v[130:131]
	v_pk_fma_f32 v[106:107], v[114:115], v[124:125], v[128:129]
	v_mov_b32_e32 v139, v104
	v_mov_b32_e32 v104, v107
	v_mul_f32_e32 v107, 0xbfb8aa3b, v154
	v_exp_f32_e32 v107, v107
	s_nop 1
	v_fmac_f32_dpp v106, v114, v120 row_shr:1 row_mask:0xf bank_mask:0xf bound_ctrl:0
	v_fmac_f32_dpp v104, v115, v121 row_shr:1 row_mask:0xf bank_mask:0xf bound_ctrl:0
	v_fmac_f32_dpp v139, v112, v122 row_shr:1 row_mask:0xf bank_mask:0xf bound_ctrl:0
	v_fmac_f32_dpp v105, v113, v123 row_shr:1 row_mask:0xf bank_mask:0xf bound_ctrl:0
	v_fmac_f32_dpp v106, v114, v116 row_shr:2 row_mask:0xf bank_mask:0xf bound_ctrl:0
	v_fmac_f32_dpp v104, v115, v117 row_shr:2 row_mask:0xf bank_mask:0xf bound_ctrl:0
	v_fmac_f32_dpp v139, v112, v118 row_shr:2 row_mask:0xf bank_mask:0xf bound_ctrl:0
	v_fmac_f32_dpp v105, v113, v119 row_shr:2 row_mask:0xf bank_mask:0xf bound_ctrl:0
	v_fmac_f32_dpp v106, v108, v120 row_shl:15 row_mask:0xf bank_mask:0xf bound_ctrl:0
	v_fmac_f32_dpp v104, v109, v121 row_shl:15 row_mask:0xf bank_mask:0xf bound_ctrl:0
	v_fmac_f32_dpp v139, v110, v122 row_shl:15 row_mask:0xf bank_mask:0xf bound_ctrl:0
	v_fmac_f32_dpp v105, v111, v123 row_shl:15 row_mask:0xf bank_mask:0xf bound_ctrl:0
	v_fmac_f32_dpp v106, v108, v116 row_shl:14 row_mask:0xf bank_mask:0xf bound_ctrl:0
	v_fmac_f32_dpp v104, v109, v117 row_shl:14 row_mask:0xf bank_mask:0xf bound_ctrl:0
	v_fmac_f32_dpp v139, v110, v118 row_shl:14 row_mask:0xf bank_mask:0xf bound_ctrl:0
	v_fmac_f32_dpp v105, v111, v119 row_shl:14 row_mask:0xf bank_mask:0xf bound_ctrl:0
	s_nop 0
	v_add_f32_e32 v107, 1.0, v107
	v_rcp_f32_e32 v107, v107
	s_nop 0
	v_mul_f32_e32 v107, v154, v107
	v_mul_f32_e32 v106, v107, v106
	v_mul_f32_e32 v107, 0xbfb8aa3b, v155
	v_exp_f32_e32 v107, v107
	s_nop 0
	v_add_f32_e32 v107, 1.0, v107
	v_rcp_f32_e32 v107, v107
	s_nop 0
	v_mul_f32_e32 v107, v155, v107
	v_mul_f32_e32 v104, v107, v104
	v_mul_f32_e32 v107, 0xbfb8aa3b, v153
	v_cvt_pk_bf16_f32 v104, v106, v104
	v_mul_f32_e32 v106, 0xbfb8aa3b, v152
	v_exp_f32_e32 v107, v107
	v_exp_f32_e32 v106, v106
	v_add_f32_e32 v107, 1.0, v107
	v_add_f32_e32 v106, 1.0, v106
	v_rcp_f32_e32 v107, v107
	v_rcp_f32_e32 v106, v106
	v_mul_f32_e32 v107, v153, v107
	v_mul_f32_e32 v106, v152, v106
	v_mul_f32_e32 v105, v107, v105
	v_mul_f32_e32 v106, v106, v139
	v_cvt_pk_bf16_f32 v105, v106, v105
	v_mov_b32_e32 v240, v104
	v_mov_b32_e32 v241, v105
	v_mov_b32_e32 v104, v186
	v_mov_b32_e32 v105, v186
	v_pk_mul_f32 v[104:105], v[102:103], v[104:105]
	v_pk_mul_f32 v[106:107], v[100:101], v[186:187]
	v_pk_fma_f32 v[100:101], v[104:105], v[126:127], v[130:131]
	v_pk_fma_f32 v[102:103], v[106:107], v[124:125], v[128:129]
	s_nop 0
	s_nop 1
	v_fmac_f32_dpp v102, v106, v120 row_shr:1 row_mask:0xf bank_mask:0xf bound_ctrl:0
	v_fmac_f32_dpp v103, v107, v121 row_shr:1 row_mask:0xf bank_mask:0xf bound_ctrl:0
	v_fmac_f32_dpp v100, v104, v122 row_shr:1 row_mask:0xf bank_mask:0xf bound_ctrl:0
	v_fmac_f32_dpp v101, v105, v123 row_shr:1 row_mask:0xf bank_mask:0xf bound_ctrl:0
	v_fmac_f32_dpp v102, v106, v116 row_shr:2 row_mask:0xf bank_mask:0xf bound_ctrl:0
	v_fmac_f32_dpp v103, v107, v117 row_shr:2 row_mask:0xf bank_mask:0xf bound_ctrl:0
	v_fmac_f32_dpp v100, v104, v118 row_shr:2 row_mask:0xf bank_mask:0xf bound_ctrl:0
	v_fmac_f32_dpp v101, v105, v119 row_shr:2 row_mask:0xf bank_mask:0xf bound_ctrl:0
	v_fmac_f32_dpp v102, v114, v120 row_shl:15 row_mask:0xf bank_mask:0xf bound_ctrl:0
	v_fmac_f32_dpp v103, v115, v121 row_shl:15 row_mask:0xf bank_mask:0xf bound_ctrl:0
	v_fmac_f32_dpp v100, v112, v122 row_shl:15 row_mask:0xf bank_mask:0xf bound_ctrl:0
	v_fmac_f32_dpp v101, v113, v123 row_shl:15 row_mask:0xf bank_mask:0xf bound_ctrl:0
	v_fmac_f32_dpp v102, v114, v116 row_shl:14 row_mask:0xf bank_mask:0xf bound_ctrl:0
	v_fmac_f32_dpp v103, v115, v117 row_shl:14 row_mask:0xf bank_mask:0xf bound_ctrl:0
	v_fmac_f32_dpp v100, v112, v118 row_shl:14 row_mask:0xf bank_mask:0xf bound_ctrl:0
	v_fmac_f32_dpp v101, v113, v119 row_shl:14 row_mask:0xf bank_mask:0xf bound_ctrl:0
	s_cbranch_vccnz .LBB0_704
	v_mov_b32_dpp v108, v106 row_shr:1 row_mask:0xf bank_mask:0xf bound_ctrl:1
	v_mov_b32_dpp v109, v107 row_shr:1 row_mask:0xf bank_mask:0xf bound_ctrl:1
	v_mov_b32_dpp v110, v104 row_shr:1 row_mask:0xf bank_mask:0xf bound_ctrl:1
	v_mov_b32_dpp v111, v105 row_shr:1 row_mask:0xf bank_mask:0xf bound_ctrl:1
	s_and_saveexec_b64 s[48:49], s[10:11]
	s_cbranch_execz .LBB0_703
	v_mov_b64_e32 v[112:113], s[24:25]
	s_mov_b32 s19, 0xb000
	v_mad_u64_u32 v[112:113], s[52:53], v136, s19, v[112:113]
	v_mov_b32_e32 v114, v113
	v_mad_u64_u32 v[114:115], s[52:53], v137, s19, v[114:115]
	v_pk_mul_f32 v[108:109], v[116:117], v[108:109]
	v_mov_b32_e32 v113, v114
	v_pk_mul_f32 v[110:111], v[118:119], v[110:111]
	v_pk_fma_f32 v[108:109], v[106:107], v[120:121], v[108:109]
	v_lshl_add_u64 v[120:121], v[184:185], 2, v[112:113]
	v_pk_fma_f32 v[110:111], v[104:105], v[122:123], v[110:111]
	v_pk_mul_f32 v[114:115], v[104:105], v[118:119]
	v_add_co_u32_e32 v104, vcc, 0x5000, v120
	v_pk_mul_f32 v[112:113], v[106:107], v[116:117]
	s_nop 0
	v_addc_co_u32_e32 v105, vcc, 0, v121, vcc
	global_store_dwordx4 v[120:121], v[112:115], off offset:512
	global_store_dwordx4 v[104:105], v[108:111], off offset:2560

.LBB0_704:
	v_mul_f32_e32 v104, 0xbfb8aa3b, v144
	v_exp_f32_e32 v104, v104
	s_nop 0
	v_add_f32_e32 v104, 1.0, v104
	v_rcp_f32_e32 v104, v104
	s_nop 0
	v_mul_f32_e32 v104, v144, v104
	v_mul_f32_e32 v102, v104, v102
	v_mul_f32_e32 v104, 0xbfb8aa3b, v150
	v_exp_f32_e32 v104, v104
	s_nop 0
	v_add_f32_e32 v104, 1.0, v104
	v_rcp_f32_e32 v104, v104
	s_nop 0
	v_mul_f32_e32 v104, v150, v104
	v_mul_f32_e32 v103, v104, v103
	v_cvt_pk_bf16_f32 v102, v102, v103
	v_mul_f32_e32 v103, 0xbfb8aa3b, v146
	v_exp_f32_e32 v103, v103
	s_nop 0
	v_add_f32_e32 v103, 1.0, v103
	v_rcp_f32_e32 v103, v103
	s_nop 0
	v_mul_f32_e32 v103, v146, v103
	v_mul_f32_e32 v100, v103, v100
	v_mul_f32_e32 v103, 0xbfb8aa3b, v147
	v_exp_f32_e32 v103, v103
	s_nop 0
	v_add_f32_e32 v103, 1.0, v103
	v_rcp_f32_e32 v103, v103
	s_nop 0
	v_mul_f32_e32 v103, v147, v103
	v_mul_f32_e32 v101, v103, v101
	v_cvt_pk_bf16_f32 v103, v100, v101
	v_mov_b32_e32 v244, v102
	v_mov_b32_e32 v245, v103
	v_add_u32_e32 v130, 0x22810, v228
	v_add_u32_e32 v142, 0x23010, v228
	v_add_u32_e32 v131, 0x22c10, v228
	ds_read_b128 v[104:107], v130
	ds_read_b128 v[108:111], v131
	v_add_u32_e32 v143, 0x23410, v228
	ds_read_b128 v[112:115], v142
	ds_read_b128 v[116:119], v143
	v_mov_b32_e32 v120, 0
	s_and_b64 vcc, exec, s[16:17]
	v_mov_b32_e32 v121, 0
	v_mov_b32_e32 v122, 0
	v_mov_b32_e32 v123, 0
	s_cbranch_vccnz .LBB0_706
	s_movk_i32 s19, 0xf840
	v_add3_u32 v100, v145, v3, s19
	ds_read_b128 v[120:123], v100

.LBB0_716:
	s_or_b64 exec, exec, s[16:17]
	s_nop 0
	v_mul_f32_e32 v81, 0xbfb8aa3b, v100
	v_exp_f32_e32 v81, v81
	v_pk_mul_f32 v[76:77], v[76:77], v[190:191]
	s_and_b64 vcc, exec, s[14:15]
	v_add_f32_e32 v81, 1.0, v81
	v_rcp_f32_e32 v81, v81
	s_nop 0
	v_mul_f32_e32 v81, v100, v81
	v_mul_f32_e32 v80, v81, v80
	v_mul_f32_e32 v81, 0xbfb8aa3b, v144
	v_exp_f32_e32 v81, v81
	s_nop 0
	v_add_f32_e32 v81, 1.0, v81
	v_rcp_f32_e32 v81, v81
	s_nop 0
	v_mul_f32_e32 v81, v144, v81
	v_mul_f32_e32 v81, v81, v119
	v_cvt_pk_bf16_f32 v80, v80, v81
	v_mul_f32_e32 v81, 0xbfb8aa3b, v102
	v_exp_f32_e32 v81, v81
	s_nop 0
	v_add_f32_e32 v81, 1.0, v81
	v_rcp_f32_e32 v81, v81
	s_nop 0
	v_mul_f32_e32 v81, v102, v81
	v_mul_f32_e32 v81, v81, v82
	v_mul_f32_e32 v82, 0xbfb8aa3b, v139
	v_exp_f32_e32 v82, v82
	s_nop 0
	v_add_f32_e32 v82, 1.0, v82
	v_rcp_f32_e32 v82, v82
	s_nop 0
	v_mul_f32_e32 v82, v139, v82
	v_mul_f32_e32 v82, v82, v117
	v_cvt_pk_bf16_f32 v81, v81, v82
	v_mov_b32_e32 v234, v80
	v_mov_b32_e32 v235, v81
	global_store_dwordx4 v[132:133], v[232:235], off
	v_mov_b32_e32 v80, v190
	v_mov_b32_e32 v81, v190
	v_pk_mul_f32 v[78:79], v[78:79], v[80:81]
	v_pk_fma_f32 v[82:83], v[76:77], v[92:93], v[96:97]
	v_pk_fma_f32 v[80:81], v[78:79], v[94:95], v[98:99]
	s_nop 0
	v_mov_b32_e32 v100, v80
	v_mul_f32_e32 v80, 0xbfb8aa3b, v128
	v_exp_f32_e32 v80, v80
	s_nop 1
	v_fmac_f32_dpp v82, v76, v88 row_shr:1 row_mask:0xf bank_mask:0xf bound_ctrl:0
	v_fmac_f32_dpp v83, v77, v89 row_shr:1 row_mask:0xf bank_mask:0xf bound_ctrl:0
	v_fmac_f32_dpp v100, v78, v90 row_shr:1 row_mask:0xf bank_mask:0xf bound_ctrl:0
	v_fmac_f32_dpp v81, v79, v91 row_shr:1 row_mask:0xf bank_mask:0xf bound_ctrl:0
	v_fmac_f32_dpp v82, v76, v84 row_shr:2 row_mask:0xf bank_mask:0xf bound_ctrl:0
	v_fmac_f32_dpp v83, v77, v85 row_shr:2 row_mask:0xf bank_mask:0xf bound_ctrl:0
	v_fmac_f32_dpp v100, v78, v86 row_shr:2 row_mask:0xf bank_mask:0xf bound_ctrl:0
	v_fmac_f32_dpp v81, v79, v87 row_shr:2 row_mask:0xf bank_mask:0xf bound_ctrl:0
	v_fmac_f32_dpp v82, v110, v88 row_shl:15 row_mask:0xf bank_mask:0xf bound_ctrl:0
	v_fmac_f32_dpp v83, v111, v89 row_shl:15 row_mask:0xf bank_mask:0xf bound_ctrl:0
	v_fmac_f32_dpp v100, v108, v90 row_shl:15 row_mask:0xf bank_mask:0xf bound_ctrl:0
	v_fmac_f32_dpp v81, v109, v91 row_shl:15 row_mask:0xf bank_mask:0xf bound_ctrl:0
	v_fmac_f32_dpp v82, v110, v84 row_shl:14 row_mask:0xf bank_mask:0xf bound_ctrl:0
	v_fmac_f32_dpp v83, v111, v85 row_shl:14 row_mask:0xf bank_mask:0xf bound_ctrl:0
	v_fmac_f32_dpp v100, v108, v86 row_shl:14 row_mask:0xf bank_mask:0xf bound_ctrl:0
	v_fmac_f32_dpp v81, v109, v87 row_shl:14 row_mask:0xf bank_mask:0xf bound_ctrl:0
	s_nop 0
	v_add_f32_e32 v80, 1.0, v80
	v_rcp_f32_e32 v80, v80
	s_nop 0
	v_mul_f32_e32 v80, v128, v80
	v_mul_f32_e32 v80, v80, v82
	v_mul_f32_e32 v82, 0xbfb8aa3b, v129
	v_exp_f32_e32 v82, v82
	s_nop 0
	v_add_f32_e32 v82, 1.0, v82
	v_rcp_f32_e32 v82, v82
	s_nop 0
	v_mul_f32_e32 v82, v129, v82
	v_mul_f32_e32 v82, v82, v83
	v_mul_f32_e32 v83, 0xbfb8aa3b, v127
	v_cvt_pk_bf16_f32 v80, v80, v82
	v_mul_f32_e32 v82, 0xbfb8aa3b, v126
	v_exp_f32_e32 v83, v83
	v_exp_f32_e32 v82, v82
	v_add_f32_e32 v83, 1.0, v83
	v_add_f32_e32 v82, 1.0, v82
	v_rcp_f32_e32 v83, v83
	v_rcp_f32_e32 v82, v82
	v_mul_f32_e32 v83, v127, v83
	v_mul_f32_e32 v82, v126, v82
	v_mul_f32_e32 v81, v83, v81
	v_mul_f32_e32 v82, v82, v100
	v_cvt_pk_bf16_f32 v81, v82, v81
	v_mov_b32_e32 v238, v80
	v_mov_b32_e32 v239, v81
	global_store_dwordx4 v[132:133], v[236:239], off offset:2048
	v_mov_b32_e32 v80, v188
	v_mov_b32_e32 v81, v188
	v_pk_mul_f32 v[80:81], v[74:75], v[80:81]
	v_pk_mul_f32 v[82:83], v[72:73], v[188:189]
	v_pk_fma_f32 v[72:73], v[80:81], v[94:95], v[98:99]
	v_pk_fma_f32 v[74:75], v[82:83], v[92:93], v[96:97]
	s_nop 0
	s_nop 1
	v_fmac_f32_dpp v74, v82, v88 row_shr:1 row_mask:0xf bank_mask:0xf bound_ctrl:0
	v_fmac_f32_dpp v75, v83, v89 row_shr:1 row_mask:0xf bank_mask:0xf bound_ctrl:0
	v_fmac_f32_dpp v72, v80, v90 row_shr:1 row_mask:0xf bank_mask:0xf bound_ctrl:0
	v_fmac_f32_dpp v73, v81, v91 row_shr:1 row_mask:0xf bank_mask:0xf bound_ctrl:0
	v_fmac_f32_dpp v74, v82, v84 row_shr:2 row_mask:0xf bank_mask:0xf bound_ctrl:0
	v_fmac_f32_dpp v75, v83, v85 row_shr:2 row_mask:0xf bank_mask:0xf bound_ctrl:0
	v_fmac_f32_dpp v72, v80, v86 row_shr:2 row_mask:0xf bank_mask:0xf bound_ctrl:0
	v_fmac_f32_dpp v73, v81, v87 row_shr:2 row_mask:0xf bank_mask:0xf bound_ctrl:0
	v_fmac_f32_dpp v74, v76, v88 row_shl:15 row_mask:0xf bank_mask:0xf bound_ctrl:0
	v_fmac_f32_dpp v75, v77, v89 row_shl:15 row_mask:0xf bank_mask:0xf bound_ctrl:0
	v_fmac_f32_dpp v72, v78, v90 row_shl:15 row_mask:0xf bank_mask:0xf bound_ctrl:0
	v_fmac_f32_dpp v73, v79, v91 row_shl:15 row_mask:0xf bank_mask:0xf bound_ctrl:0
	v_fmac_f32_dpp v74, v76, v84 row_shl:14 row_mask:0xf bank_mask:0xf bound_ctrl:0
	v_fmac_f32_dpp v75, v77, v85 row_shl:14 row_mask:0xf bank_mask:0xf bound_ctrl:0
	v_fmac_f32_dpp v72, v78, v86 row_shl:14 row_mask:0xf bank_mask:0xf bound_ctrl:0
	v_fmac_f32_dpp v73, v79, v87 row_shl:14 row_mask:0xf bank_mask:0xf bound_ctrl:0
	v_mul_f32_e32 v76, 0xbfb8aa3b, v124
	v_exp_f32_e32 v76, v76
	s_nop 0
	v_add_f32_e32 v76, 1.0, v76
	v_rcp_f32_e32 v76, v76
	s_nop 0
	v_mul_f32_e32 v76, v124, v76
	v_mul_f32_e32 v74, v76, v74
	v_mul_f32_e32 v76, 0xbfb8aa3b, v125
	v_exp_f32_e32 v76, v76
	s_nop 0
	v_add_f32_e32 v76, 1.0, v76
	v_rcp_f32_e32 v76, v76
	s_nop 0
	v_mul_f32_e32 v76, v125, v76
	v_mul_f32_e32 v75, v76, v75
	v_cvt_pk_bf16_f32 v74, v74, v75
	v_mul_f32_e32 v75, 0xbfb8aa3b, v122
	v_exp_f32_e32 v75, v75
	s_nop 0
	v_add_f32_e32 v75, 1.0, v75
	v_rcp_f32_e32 v75, v75
	s_nop 0
	v_mul_f32_e32 v75, v122, v75
	v_mul_f32_e32 v72, v75, v72
	v_mul_f32_e32 v75, 0xbfb8aa3b, v123
	v_exp_f32_e32 v75, v75
	s_nop 0
	v_add_f32_e32 v75, 1.0, v75
	v_rcp_f32_e32 v75, v75
	s_nop 0
	v_mul_f32_e32 v75, v123, v75
	v_mul_f32_e32 v73, v75, v73
	v_cvt_pk_bf16_f32 v75, v72, v73
	v_mov_b32_e32 v72, v186
	v_mov_b32_e32 v73, v186
	v_mov_b32_e32 v242, v74
	v_mov_b32_e32 v243, v75
	global_store_dwordx4 v[140:141], v[240:243], off
	v_pk_mul_f32 v[72:73], v[70:71], v[72:73]
	v_pk_mul_f32 v[74:75], v[68:69], v[186:187]
	v_pk_fma_f32 v[68:69], v[72:73], v[94:95], v[98:99]
	v_pk_fma_f32 v[70:71], v[74:75], v[92:93], v[96:97]
	s_nop 0
	s_nop 1
	v_fmac_f32_dpp v70, v74, v88 row_shr:1 row_mask:0xf bank_mask:0xf bound_ctrl:0
	v_fmac_f32_dpp v71, v75, v89 row_shr:1 row_mask:0xf bank_mask:0xf bound_ctrl:0
	v_fmac_f32_dpp v68, v72, v90 row_shr:1 row_mask:0xf bank_mask:0xf bound_ctrl:0
	v_fmac_f32_dpp v69, v73, v91 row_shr:1 row_mask:0xf bank_mask:0xf bound_ctrl:0
	v_fmac_f32_dpp v70, v74, v84 row_shr:2 row_mask:0xf bank_mask:0xf bound_ctrl:0
	v_fmac_f32_dpp v71, v75, v85 row_shr:2 row_mask:0xf bank_mask:0xf bound_ctrl:0
	v_fmac_f32_dpp v68, v72, v86 row_shr:2 row_mask:0xf bank_mask:0xf bound_ctrl:0
	v_fmac_f32_dpp v69, v73, v87 row_shr:2 row_mask:0xf bank_mask:0xf bound_ctrl:0
	v_fmac_f32_dpp v70, v82, v88 row_shl:15 row_mask:0xf bank_mask:0xf bound_ctrl:0
	v_fmac_f32_dpp v71, v83, v89 row_shl:15 row_mask:0xf bank_mask:0xf bound_ctrl:0
	v_fmac_f32_dpp v68, v80, v90 row_shl:15 row_mask:0xf bank_mask:0xf bound_ctrl:0
	v_fmac_f32_dpp v69, v81, v91 row_shl:15 row_mask:0xf bank_mask:0xf bound_ctrl:0
	v_fmac_f32_dpp v70, v82, v84 row_shl:14 row_mask:0xf bank_mask:0xf bound_ctrl:0
	v_fmac_f32_dpp v71, v83, v85 row_shl:14 row_mask:0xf bank_mask:0xf bound_ctrl:0
	v_fmac_f32_dpp v68, v80, v86 row_shl:14 row_mask:0xf bank_mask:0xf bound_ctrl:0
	v_fmac_f32_dpp v69, v81, v87 row_shl:14 row_mask:0xf bank_mask:0xf bound_ctrl:0
	s_cbranch_vccnz .LBB0_720
	v_mov_b32_dpp v76, v74 row_shr:1 row_mask:0xf bank_mask:0xf bound_ctrl:1
	v_mov_b32_dpp v77, v75 row_shr:1 row_mask:0xf bank_mask:0xf bound_ctrl:1
	v_mov_b32_dpp v78, v72 row_shr:1 row_mask:0xf bank_mask:0xf bound_ctrl:1
	v_mov_b32_dpp v79, v73 row_shr:1 row_mask:0xf bank_mask:0xf bound_ctrl:1
	s_and_saveexec_b64 s[14:15], s[10:11]
	s_cbranch_execz .LBB0_719
	v_mov_b64_e32 v[80:81], s[24:25]
	s_mov_b32 s19, 0xb000
	v_mad_u64_u32 v[80:81], s[16:17], v136, s19, v[80:81]
	v_mov_b32_e32 v82, v81
	v_mad_u64_u32 v[82:83], s[16:17], v137, s19, v[82:83]
	v_pk_mul_f32 v[76:77], v[84:85], v[76:77]
	v_mov_b32_e32 v81, v82
	v_pk_mul_f32 v[78:79], v[86:87], v[78:79]
	v_pk_fma_f32 v[76:77], v[74:75], v[88:89], v[76:77]
	v_lshl_add_u64 v[88:89], v[184:185], 2, v[80:81]
	v_pk_fma_f32 v[78:79], v[72:73], v[90:91], v[78:79]
	v_pk_mul_f32 v[82:83], v[72:73], v[86:87]
	v_add_co_u32_e32 v72, vcc, 0x5000, v88
	v_pk_mul_f32 v[80:81], v[74:75], v[84:85]
	s_nop 0
	v_addc_co_u32_e32 v73, vcc, 0, v89, vcc
	global_store_dwordx4 v[88:89], v[80:83], off offset:528
	global_store_dwordx4 v[72:73], v[76:79], off offset:2576

.LBB0_720:
	v_mul_f32_e32 v72, 0xbfb8aa3b, v112
	v_exp_f32_e32 v72, v72
	s_nop 0
	v_add_f32_e32 v72, 1.0, v72
	v_rcp_f32_e32 v72, v72
	s_nop 0
	v_mul_f32_e32 v72, v112, v72
	v_mul_f32_e32 v70, v72, v70
	v_mul_f32_e32 v72, 0xbfb8aa3b, v103
	v_exp_f32_e32 v72, v72
	s_nop 0
	v_add_f32_e32 v72, 1.0, v72
	v_rcp_f32_e32 v72, v72
	s_nop 0
	v_mul_f32_e32 v72, v103, v72
	v_mul_f32_e32 v71, v72, v71
	v_cvt_pk_bf16_f32 v70, v70, v71
	v_mul_f32_e32 v71, 0xbfb8aa3b, v114
	v_exp_f32_e32 v71, v71
	s_nop 0
	v_add_f32_e32 v71, 1.0, v71
	v_rcp_f32_e32 v71, v71
	s_nop 0
	v_mul_f32_e32 v71, v114, v71
	v_mul_f32_e32 v68, v71, v68
	v_mul_f32_e32 v71, 0xbfb8aa3b, v101
	v_exp_f32_e32 v71, v71
	s_nop 0
	v_add_f32_e32 v71, 1.0, v71
	v_rcp_f32_e32 v71, v71
	s_nop 0
	v_mul_f32_e32 v71, v101, v71
	v_mul_f32_e32 v69, v71, v69
	v_cvt_pk_bf16_f32 v71, v68, v69
	ds_read2_b32 v[98:99], v226 offset0:128 offset1:144
	ds_read2_b32 v[94:95], v226 offset0:160 offset1:176
	v_mov_b32_e32 v246, v70
	v_mov_b32_e32 v247, v71
	global_store_dwordx4 v[140:141], v[244:247], off offset:2048
	s_waitcnt lgkmcnt(1)
	v_mov_b32_e32 v96, v99
	s_waitcnt lgkmcnt(0)
	v_mov_b32_e32 v92, v95
	ds_read_b128 v[72:75], v221
	ds_read_b128 v[76:79], v222
	ds_read_b128 v[80:83], v223
	ds_read_b128 v[84:87], v224
	v_cndmask_b32_e64 v68, 0, 1, s[36:37]
	v_mov_b32_e32 v88, 0
	v_cmp_ne_u32_e64 s[14:15], 1, v68
	s_andn2_b64 vcc, exec, s[36:37]
	v_mov_b32_e32 v89, 0
	v_mov_b32_e32 v90, 0
	v_mov_b32_e32 v91, 0
	s_cbranch_vccnz .LBB0_722
	v_add3_u32 v68, s6, v227, v3
	ds_read_b128 v[88:91], v68

.LBB0_732:
	s_or_b64 exec, exec, s[48:49]
	s_nop 0
	v_mul_f32_e32 v49, 0xbfb8aa3b, v68
	v_exp_f32_e32 v49, v49
	v_mov_b32_e32 v139, v2
	s_movk_i32 s19, 0x4000
	v_mov_b32_e32 v97, v96
	v_add_f32_e32 v49, 1.0, v49
	v_rcp_f32_e32 v49, v49
	v_pk_mul_f32 v[44:45], v[44:45], v[96:97]
	v_mov_b32_e32 v95, v94
	v_pk_fma_f32 v[74:75], v[44:45], v[60:61], v[64:65]
	v_mul_f32_e32 v49, v68, v49
	v_mul_f32_e32 v48, v49, v48
	v_mul_f32_e32 v49, 0xbfb8aa3b, v107
	v_exp_f32_e32 v49, v49
	v_lshl_add_u64 v[68:69], v[134:135], 0, v[138:139]
	v_mov_b32_e32 v93, v92
	v_add_f32_e32 v49, 1.0, v49
	v_rcp_f32_e32 v49, v49
	s_nop 0
	v_mul_f32_e32 v49, v107, v49
	v_mul_f32_e32 v49, v49, v87
	v_cvt_pk_bf16_f32 v72, v48, v49
	v_mul_f32_e32 v48, 0xbfb8aa3b, v70
	v_exp_f32_e32 v48, v48
	v_mul_f32_e32 v49, 0xbfb8aa3b, v105
	v_exp_f32_e32 v49, v49
	v_add_f32_e32 v48, 1.0, v48
	v_rcp_f32_e32 v48, v48
	v_add_f32_e32 v49, 1.0, v49
	v_rcp_f32_e32 v49, v49
	v_mul_f32_e32 v48, v70, v48
	v_mul_f32_e32 v48, v48, v50
	v_add_co_u32_e32 v50, vcc, s19, v68
	v_mul_f32_e32 v49, v105, v49
	s_nop 0
	v_addc_co_u32_e32 v51, vcc, 0, v69, vcc
	s_movk_i32 s19, 0x5000
	v_mul_f32_e32 v49, v49, v85
	v_cvt_pk_bf16_f32 v73, v48, v49
	v_add_co_u32_e32 v48, vcc, s19, v68
	v_mov_b32_e32 v70, v74
	s_nop 0
	v_addc_co_u32_e32 v49, vcc, 0, v69, vcc
	v_mov_b32_e32 v232, v72
	v_mov_b32_e32 v233, v73
	v_mov_b32_e32 v72, v96
	v_mov_b32_e32 v73, v96
	v_pk_mul_f32 v[46:47], v[46:47], v[72:73]
	s_and_b64 vcc, exec, s[12:13]
	v_pk_fma_f32 v[72:73], v[46:47], v[62:63], v[66:67]
	s_nop 0
	v_mov_b32_e32 v74, v72
	v_mul_f32_e32 v72, 0xbfb8aa3b, v102
	v_exp_f32_e32 v72, v72
	s_nop 1
	v_fmac_f32_dpp v70, v44, v56 row_shr:1 row_mask:0xf bank_mask:0xf bound_ctrl:0
	v_fmac_f32_dpp v75, v45, v57 row_shr:1 row_mask:0xf bank_mask:0xf bound_ctrl:0
	v_fmac_f32_dpp v74, v46, v58 row_shr:1 row_mask:0xf bank_mask:0xf bound_ctrl:0
	v_fmac_f32_dpp v73, v47, v59 row_shr:1 row_mask:0xf bank_mask:0xf bound_ctrl:0
	v_fmac_f32_dpp v70, v44, v52 row_shr:2 row_mask:0xf bank_mask:0xf bound_ctrl:0
	v_fmac_f32_dpp v75, v45, v53 row_shr:2 row_mask:0xf bank_mask:0xf bound_ctrl:0
	v_fmac_f32_dpp v74, v46, v54 row_shr:2 row_mask:0xf bank_mask:0xf bound_ctrl:0
	v_fmac_f32_dpp v73, v47, v55 row_shr:2 row_mask:0xf bank_mask:0xf bound_ctrl:0
	v_fmac_f32_dpp v70, v78, v56 row_shl:15 row_mask:0xf bank_mask:0xf bound_ctrl:0
	v_fmac_f32_dpp v75, v79, v57 row_shl:15 row_mask:0xf bank_mask:0xf bound_ctrl:0
	v_fmac_f32_dpp v74, v76, v58 row_shl:15 row_mask:0xf bank_mask:0xf bound_ctrl:0
	v_fmac_f32_dpp v73, v77, v59 row_shl:15 row_mask:0xf bank_mask:0xf bound_ctrl:0
	v_fmac_f32_dpp v70, v78, v52 row_shl:14 row_mask:0xf bank_mask:0xf bound_ctrl:0
	v_fmac_f32_dpp v75, v79, v53 row_shl:14 row_mask:0xf bank_mask:0xf bound_ctrl:0
	v_fmac_f32_dpp v74, v76, v54 row_shl:14 row_mask:0xf bank_mask:0xf bound_ctrl:0
	v_fmac_f32_dpp v73, v77, v55 row_shl:14 row_mask:0xf bank_mask:0xf bound_ctrl:0
	s_nop 0
	v_add_f32_e32 v72, 1.0, v72
	v_rcp_f32_e32 v72, v72
	s_nop 0
	v_mul_f32_e32 v72, v102, v72
	v_mul_f32_e32 v70, v72, v70
	v_mul_f32_e32 v72, 0xbfb8aa3b, v103
	v_exp_f32_e32 v72, v72
	s_nop 0
	v_add_f32_e32 v72, 1.0, v72
	v_rcp_f32_e32 v72, v72
	s_nop 0
	v_mul_f32_e32 v72, v103, v72
	v_mul_f32_e32 v72, v72, v75
	v_cvt_pk_bf16_f32 v72, v70, v72
	v_mul_f32_e32 v70, 0xbfb8aa3b, v100
	v_exp_f32_e32 v70, v70
	s_nop 0
	v_add_f32_e32 v70, 1.0, v70
	v_rcp_f32_e32 v70, v70
	s_nop 0
	v_mul_f32_e32 v70, v100, v70
	v_mul_f32_e32 v70, v70, v74
	v_mul_f32_e32 v74, 0xbfb8aa3b, v101
	v_exp_f32_e32 v74, v74
	s_nop 0
	v_add_f32_e32 v74, 1.0, v74
	v_rcp_f32_e32 v74, v74
	s_nop 0
	v_mul_f32_e32 v74, v101, v74
	v_mul_f32_e32 v73, v74, v73
	v_cvt_pk_bf16_f32 v73, v70, v73
	v_mov_b32_e32 v236, v72
	v_mov_b32_e32 v237, v73
	v_mov_b32_e32 v50, v94
	v_mov_b32_e32 v51, v94
	v_pk_mul_f32 v[50:51], v[42:43], v[50:51]
	v_pk_mul_f32 v[72:73], v[40:41], v[94:95]
	v_pk_fma_f32 v[40:41], v[50:51], v[62:63], v[66:67]
	v_pk_fma_f32 v[42:43], v[72:73], v[60:61], v[64:65]
	s_nop 0
	s_nop 1
	v_fmac_f32_dpp v42, v72, v56 row_shr:1 row_mask:0xf bank_mask:0xf bound_ctrl:0
	v_fmac_f32_dpp v43, v73, v57 row_shr:1 row_mask:0xf bank_mask:0xf bound_ctrl:0
	v_fmac_f32_dpp v40, v50, v58 row_shr:1 row_mask:0xf bank_mask:0xf bound_ctrl:0
	v_fmac_f32_dpp v41, v51, v59 row_shr:1 row_mask:0xf bank_mask:0xf bound_ctrl:0
	v_fmac_f32_dpp v42, v72, v52 row_shr:2 row_mask:0xf bank_mask:0xf bound_ctrl:0
	v_fmac_f32_dpp v43, v73, v53 row_shr:2 row_mask:0xf bank_mask:0xf bound_ctrl:0
	v_fmac_f32_dpp v40, v50, v54 row_shr:2 row_mask:0xf bank_mask:0xf bound_ctrl:0
	v_fmac_f32_dpp v41, v51, v55 row_shr:2 row_mask:0xf bank_mask:0xf bound_ctrl:0
	v_fmac_f32_dpp v42, v44, v56 row_shl:15 row_mask:0xf bank_mask:0xf bound_ctrl:0
	v_fmac_f32_dpp v43, v45, v57 row_shl:15 row_mask:0xf bank_mask:0xf bound_ctrl:0
	v_fmac_f32_dpp v40, v46, v58 row_shl:15 row_mask:0xf bank_mask:0xf bound_ctrl:0
	v_fmac_f32_dpp v41, v47, v59 row_shl:15 row_mask:0xf bank_mask:0xf bound_ctrl:0
	v_fmac_f32_dpp v42, v44, v52 row_shl:14 row_mask:0xf bank_mask:0xf bound_ctrl:0
	v_fmac_f32_dpp v43, v45, v53 row_shl:14 row_mask:0xf bank_mask:0xf bound_ctrl:0
	v_fmac_f32_dpp v40, v46, v54 row_shl:14 row_mask:0xf bank_mask:0xf bound_ctrl:0
	v_fmac_f32_dpp v41, v47, v55 row_shl:14 row_mask:0xf bank_mask:0xf bound_ctrl:0
	v_mul_f32_e32 v44, 0xbfb8aa3b, v90
	v_exp_f32_e32 v44, v44
	s_nop 0
	v_add_f32_e32 v44, 1.0, v44
	v_rcp_f32_e32 v44, v44
	s_nop 0
	v_mul_f32_e32 v44, v90, v44
	v_mul_f32_e32 v42, v44, v42
	v_mul_f32_e32 v44, 0xbfb8aa3b, v91
	v_exp_f32_e32 v44, v44
	s_nop 0
	v_add_f32_e32 v44, 1.0, v44
	v_rcp_f32_e32 v44, v44
	s_nop 0
	v_mul_f32_e32 v44, v91, v44
	v_mul_f32_e32 v43, v44, v43
	v_cvt_pk_bf16_f32 v42, v42, v43
	v_mul_f32_e32 v43, 0xbfb8aa3b, v88
	v_exp_f32_e32 v43, v43
	s_nop 0
	v_add_f32_e32 v43, 1.0, v43
	v_rcp_f32_e32 v43, v43
	s_nop 0
	v_mul_f32_e32 v43, v88, v43
	v_mul_f32_e32 v40, v43, v40
	v_mul_f32_e32 v43, 0xbfb8aa3b, v89
	v_exp_f32_e32 v43, v43
	s_nop 0
	v_add_f32_e32 v43, 1.0, v43
	v_rcp_f32_e32 v43, v43
	s_nop 0
	v_mul_f32_e32 v43, v89, v43
	v_mul_f32_e32 v41, v43, v41
	v_cvt_pk_bf16_f32 v43, v40, v41
	v_mov_b32_e32 v40, v92
	v_mov_b32_e32 v41, v92
	v_mov_b32_e32 v240, v42
	v_mov_b32_e32 v241, v43
	v_pk_mul_f32 v[40:41], v[38:39], v[40:41]
	v_pk_mul_f32 v[42:43], v[36:37], v[92:93]
	v_pk_fma_f32 v[36:37], v[40:41], v[62:63], v[66:67]
	v_pk_fma_f32 v[38:39], v[42:43], v[60:61], v[64:65]
	s_nop 0
	s_nop 1
	v_fmac_f32_dpp v38, v42, v56 row_shr:1 row_mask:0xf bank_mask:0xf bound_ctrl:0
	v_fmac_f32_dpp v39, v43, v57 row_shr:1 row_mask:0xf bank_mask:0xf bound_ctrl:0
	v_fmac_f32_dpp v36, v40, v58 row_shr:1 row_mask:0xf bank_mask:0xf bound_ctrl:0
	v_fmac_f32_dpp v37, v41, v59 row_shr:1 row_mask:0xf bank_mask:0xf bound_ctrl:0
	v_fmac_f32_dpp v38, v42, v52 row_shr:2 row_mask:0xf bank_mask:0xf bound_ctrl:0
	v_fmac_f32_dpp v39, v43, v53 row_shr:2 row_mask:0xf bank_mask:0xf bound_ctrl:0
	v_fmac_f32_dpp v36, v40, v54 row_shr:2 row_mask:0xf bank_mask:0xf bound_ctrl:0
	v_fmac_f32_dpp v37, v41, v55 row_shr:2 row_mask:0xf bank_mask:0xf bound_ctrl:0
	v_fmac_f32_dpp v38, v72, v56 row_shl:15 row_mask:0xf bank_mask:0xf bound_ctrl:0
	v_fmac_f32_dpp v39, v73, v57 row_shl:15 row_mask:0xf bank_mask:0xf bound_ctrl:0
	v_fmac_f32_dpp v36, v50, v58 row_shl:15 row_mask:0xf bank_mask:0xf bound_ctrl:0
	v_fmac_f32_dpp v37, v51, v59 row_shl:15 row_mask:0xf bank_mask:0xf bound_ctrl:0
	v_fmac_f32_dpp v38, v72, v52 row_shl:14 row_mask:0xf bank_mask:0xf bound_ctrl:0
	v_fmac_f32_dpp v39, v73, v53 row_shl:14 row_mask:0xf bank_mask:0xf bound_ctrl:0
	v_fmac_f32_dpp v36, v50, v54 row_shl:14 row_mask:0xf bank_mask:0xf bound_ctrl:0
	v_fmac_f32_dpp v37, v51, v55 row_shl:14 row_mask:0xf bank_mask:0xf bound_ctrl:0
	s_cbranch_vccnz .LBB0_736
	v_mov_b32_dpp v44, v42 row_shr:1 row_mask:0xf bank_mask:0xf bound_ctrl:1
	v_mov_b32_dpp v45, v43 row_shr:1 row_mask:0xf bank_mask:0xf bound_ctrl:1
	v_mov_b32_dpp v46, v40 row_shr:1 row_mask:0xf bank_mask:0xf bound_ctrl:1
	v_mov_b32_dpp v47, v41 row_shr:1 row_mask:0xf bank_mask:0xf bound_ctrl:1
	s_and_saveexec_b64 s[48:49], s[10:11]
	s_cbranch_execz .LBB0_735
	v_mov_b64_e32 v[48:49], s[24:25]
	s_mov_b32 s19, 0xb000
	v_mad_u64_u32 v[48:49], s[50:51], v136, s19, v[48:49]
	v_mov_b32_e32 v50, v49
	v_mad_u64_u32 v[50:51], s[50:51], v137, s19, v[50:51]
	v_pk_mul_f32 v[44:45], v[52:53], v[44:45]
	v_mov_b32_e32 v49, v50
	v_pk_mul_f32 v[46:47], v[54:55], v[46:47]
	v_pk_fma_f32 v[44:45], v[42:43], v[56:57], v[44:45]
	v_lshl_add_u64 v[56:57], v[184:185], 2, v[48:49]
	v_pk_fma_f32 v[46:47], v[40:41], v[58:59], v[46:47]
	v_pk_mul_f32 v[50:51], v[40:41], v[54:55]
	v_add_co_u32_e32 v40, vcc, 0x5000, v56
	v_pk_mul_f32 v[48:49], v[42:43], v[52:53]
	s_nop 0
	v_addc_co_u32_e32 v41, vcc, 0, v57, vcc
	global_store_dwordx4 v[56:57], v[48:51], off offset:512
	global_store_dwordx4 v[40:41], v[44:47], off offset:2560

.LBB0_736:
	v_mul_f32_e32 v40, 0xbfb8aa3b, v80
	v_exp_f32_e32 v40, v40
	s_nop 0
	v_add_f32_e32 v40, 1.0, v40
	v_rcp_f32_e32 v40, v40
	s_nop 0
	v_mul_f32_e32 v40, v80, v40
	v_mul_f32_e32 v38, v40, v38
	v_mul_f32_e32 v40, 0xbfb8aa3b, v81
	v_exp_f32_e32 v40, v40
	s_nop 0
	v_add_f32_e32 v40, 1.0, v40
	v_rcp_f32_e32 v40, v40
	s_nop 0
	v_mul_f32_e32 v40, v81, v40
	v_mul_f32_e32 v39, v40, v39
	v_cvt_pk_bf16_f32 v38, v38, v39
	v_mul_f32_e32 v39, 0xbfb8aa3b, v82
	v_exp_f32_e32 v39, v39
	s_nop 0
	v_add_f32_e32 v39, 1.0, v39
	v_rcp_f32_e32 v39, v39
	s_nop 0
	v_mul_f32_e32 v39, v82, v39
	v_mul_f32_e32 v36, v39, v36
	v_mul_f32_e32 v39, 0xbfb8aa3b, v83
	v_exp_f32_e32 v39, v39
	s_nop 0
	v_add_f32_e32 v39, 1.0, v39
	v_rcp_f32_e32 v39, v39
	s_nop 0
	v_mul_f32_e32 v39, v83, v39
	v_mul_f32_e32 v37, v39, v37
	v_cvt_pk_bf16_f32 v39, v36, v37
	v_add_co_u32_e32 v36, vcc, 0x5000, v68
	s_nop 1
	v_addc_co_u32_e32 v37, vcc, 0, v69, vcc
	v_mov_b32_e32 v244, v38
	v_mov_b32_e32 v245, v39
	ds_read_b128 v[40:43], v130
	ds_read_b128 v[44:47], v131
	ds_read_b128 v[48:51], v142
	ds_read_b128 v[52:55], v143
	v_mov_b32_e32 v56, 0
	s_and_b64 vcc, exec, s[14:15]
	v_mov_b32_e32 v57, 0
	v_mov_b32_e32 v58, 0
	v_mov_b32_e32 v59, 0
	s_cbranch_vccnz .LBB0_738
	s_movk_i32 s19, 0xf840
	v_add3_u32 v36, v71, v3, s19
	ds_read_b128 v[56:59], v36

.LBB0_748:
	s_or_b64 exec, exec, s[14:15]
	v_mul_f32_e32 v3, 0xbfb8aa3b, v36
	v_exp_f32_e32 v3, v3
	v_mul_f32_e32 v17, 0xbfb8aa3b, v64
	v_exp_f32_e32 v17, v17
	s_mov_b64 s[14:15], 0x4000
	v_add_f32_e32 v3, 1.0, v3
	v_rcp_f32_e32 v3, v3
	v_add_f32_e32 v17, 1.0, v17
	v_rcp_f32_e32 v17, v17
	v_lshl_add_u64 v[40:41], v[68:69], 0, s[14:15]
	v_mul_f32_e32 v3, v36, v3
	v_mul_f32_e32 v3, v3, v16
	v_mul_f32_e32 v16, 0xbfb8aa3b, v65
	v_exp_f32_e32 v16, v16
	v_mul_f32_e32 v17, v64, v17
	v_mul_f32_e32 v17, v17, v53
	v_pk_mul_f32 v[12:13], v[12:13], v[96:97]
	v_add_f32_e32 v16, 1.0, v16
	v_rcp_f32_e32 v16, v16
	s_movk_i32 s14, 0x4000
	v_mul_f32_e32 v16, v65, v16
	v_mul_f32_e32 v16, v16, v55
	v_cvt_pk_bf16_f32 v16, v3, v16
	v_mul_f32_e32 v3, 0xbfb8aa3b, v38
	v_exp_f32_e32 v3, v3
	s_nop 0
	v_add_f32_e32 v3, 1.0, v3
	v_rcp_f32_e32 v3, v3
	s_nop 0
	v_mul_f32_e32 v3, v38, v3
	v_mul_f32_e32 v3, v3, v18
	v_cvt_pk_bf16_f32 v17, v3, v17
	v_mov_b32_e32 v234, v16
	v_mov_b32_e32 v235, v17
	global_store_dwordx4 v[40:41], v[232:235], off
	v_mov_b32_e32 v16, v96
	v_mov_b32_e32 v17, v96
	v_pk_mul_f32 v[14:15], v[14:15], v[16:17]
	v_pk_fma_f32 v[18:19], v[12:13], v[28:29], v[32:33]
	v_pk_fma_f32 v[16:17], v[14:15], v[30:31], v[34:35]
	v_mov_b32_e32 v3, v18
	v_mov_b32_e32 v18, v16
	v_mul_f32_e32 v16, 0xbfb8aa3b, v62
	v_exp_f32_e32 v16, v16
	s_nop 1
	v_fmac_f32_dpp v3, v12, v24 row_shr:1 row_mask:0xf bank_mask:0xf bound_ctrl:0
	v_fmac_f32_dpp v19, v13, v25 row_shr:1 row_mask:0xf bank_mask:0xf bound_ctrl:0
	v_fmac_f32_dpp v18, v14, v26 row_shr:1 row_mask:0xf bank_mask:0xf bound_ctrl:0
	v_fmac_f32_dpp v17, v15, v27 row_shr:1 row_mask:0xf bank_mask:0xf bound_ctrl:0
	v_fmac_f32_dpp v3, v12, v20 row_shr:2 row_mask:0xf bank_mask:0xf bound_ctrl:0
	v_fmac_f32_dpp v19, v13, v21 row_shr:2 row_mask:0xf bank_mask:0xf bound_ctrl:0
	v_fmac_f32_dpp v18, v14, v22 row_shr:2 row_mask:0xf bank_mask:0xf bound_ctrl:0
	v_fmac_f32_dpp v17, v15, v23 row_shr:2 row_mask:0xf bank_mask:0xf bound_ctrl:0
	v_fmac_f32_dpp v3, v46, v24 row_shl:15 row_mask:0xf bank_mask:0xf bound_ctrl:0
	v_fmac_f32_dpp v19, v47, v25 row_shl:15 row_mask:0xf bank_mask:0xf bound_ctrl:0
	v_fmac_f32_dpp v18, v44, v26 row_shl:15 row_mask:0xf bank_mask:0xf bound_ctrl:0
	v_fmac_f32_dpp v17, v45, v27 row_shl:15 row_mask:0xf bank_mask:0xf bound_ctrl:0
	v_fmac_f32_dpp v3, v46, v20 row_shl:14 row_mask:0xf bank_mask:0xf bound_ctrl:0
	v_fmac_f32_dpp v19, v47, v21 row_shl:14 row_mask:0xf bank_mask:0xf bound_ctrl:0
	v_fmac_f32_dpp v18, v44, v22 row_shl:14 row_mask:0xf bank_mask:0xf bound_ctrl:0
	v_fmac_f32_dpp v17, v45, v23 row_shl:14 row_mask:0xf bank_mask:0xf bound_ctrl:0
	s_nop 0
	v_add_f32_e32 v16, 1.0, v16
	v_rcp_f32_e32 v16, v16
	s_nop 0
	v_mul_f32_e32 v16, v62, v16
	v_mul_f32_e32 v3, v16, v3
	v_mul_f32_e32 v16, 0xbfb8aa3b, v63
	v_exp_f32_e32 v16, v16
	s_nop 0
	v_add_f32_e32 v16, 1.0, v16
	v_rcp_f32_e32 v16, v16
	s_nop 0
	v_mul_f32_e32 v16, v63, v16
	v_mul_f32_e32 v16, v16, v19
	v_cvt_pk_bf16_f32 v16, v3, v16
	v_mul_f32_e32 v3, 0xbfb8aa3b, v60
	v_exp_f32_e32 v3, v3
	s_nop 0
	v_add_f32_e32 v3, 1.0, v3
	v_rcp_f32_e32 v3, v3
	s_nop 0
	v_mul_f32_e32 v3, v60, v3
	v_mul_f32_e32 v3, v3, v18
	v_mul_f32_e32 v18, 0xbfb8aa3b, v61
	v_exp_f32_e32 v18, v18
	s_nop 0
	v_add_f32_e32 v18, 1.0, v18
	v_rcp_f32_e32 v18, v18
	s_nop 0
	v_mul_f32_e32 v18, v61, v18
	v_mul_f32_e32 v17, v18, v17
	v_add_co_u32_e32 v18, vcc, s14, v132
	v_cvt_pk_bf16_f32 v17, v3, v17
	s_movk_i32 s14, 0x5000
	s_nop 0
	v_addc_co_u32_e32 v19, vcc, 0, v133, vcc
	v_mov_b32_e32 v238, v16
	v_mov_b32_e32 v239, v17
	global_store_dwordx4 v[18:19], v[236:239], off offset:2048
	v_mov_b32_e32 v16, v94
	v_mov_b32_e32 v17, v94
	v_pk_mul_f32 v[18:19], v[8:9], v[94:95]
	v_pk_mul_f32 v[16:17], v[10:11], v[16:17]
	v_pk_fma_f32 v[10:11], v[18:19], v[28:29], v[32:33]
	v_pk_fma_f32 v[8:9], v[16:17], v[30:31], v[34:35]
	v_mov_b32_e32 v3, v11
	v_mul_f32_e32 v11, 0xbfb8aa3b, v58
	v_exp_f32_e32 v11, v11
	s_nop 1
	v_fmac_f32_dpp v10, v18, v24 row_shr:1 row_mask:0xf bank_mask:0xf bound_ctrl:0
	v_fmac_f32_dpp v3, v19, v25 row_shr:1 row_mask:0xf bank_mask:0xf bound_ctrl:0
	v_fmac_f32_dpp v8, v16, v26 row_shr:1 row_mask:0xf bank_mask:0xf bound_ctrl:0
	v_fmac_f32_dpp v9, v17, v27 row_shr:1 row_mask:0xf bank_mask:0xf bound_ctrl:0
	v_fmac_f32_dpp v10, v18, v20 row_shr:2 row_mask:0xf bank_mask:0xf bound_ctrl:0
	v_fmac_f32_dpp v3, v19, v21 row_shr:2 row_mask:0xf bank_mask:0xf bound_ctrl:0
	v_fmac_f32_dpp v8, v16, v22 row_shr:2 row_mask:0xf bank_mask:0xf bound_ctrl:0
	v_fmac_f32_dpp v9, v17, v23 row_shr:2 row_mask:0xf bank_mask:0xf bound_ctrl:0
	v_fmac_f32_dpp v10, v12, v24 row_shl:15 row_mask:0xf bank_mask:0xf bound_ctrl:0
	v_fmac_f32_dpp v3, v13, v25 row_shl:15 row_mask:0xf bank_mask:0xf bound_ctrl:0
	v_fmac_f32_dpp v8, v14, v26 row_shl:15 row_mask:0xf bank_mask:0xf bound_ctrl:0
	v_fmac_f32_dpp v9, v15, v27 row_shl:15 row_mask:0xf bank_mask:0xf bound_ctrl:0
	v_fmac_f32_dpp v10, v12, v20 row_shl:14 row_mask:0xf bank_mask:0xf bound_ctrl:0
	v_fmac_f32_dpp v3, v13, v21 row_shl:14 row_mask:0xf bank_mask:0xf bound_ctrl:0
	v_fmac_f32_dpp v8, v14, v22 row_shl:14 row_mask:0xf bank_mask:0xf bound_ctrl:0
	v_fmac_f32_dpp v9, v15, v23 row_shl:14 row_mask:0xf bank_mask:0xf bound_ctrl:0
	s_nop 0
	v_add_f32_e32 v11, 1.0, v11
	v_rcp_f32_e32 v11, v11
	s_nop 0
	v_mul_f32_e32 v11, v58, v11
	v_mul_f32_e32 v10, v11, v10
	v_mul_f32_e32 v11, 0xbfb8aa3b, v59
	v_exp_f32_e32 v11, v11
	s_nop 0
	v_add_f32_e32 v11, 1.0, v11
	v_rcp_f32_e32 v11, v11
	s_nop 0
	v_mul_f32_e32 v11, v59, v11
	v_mul_f32_e32 v3, v11, v3
	v_cvt_pk_bf16_f32 v10, v10, v3
	v_mul_f32_e32 v3, 0xbfb8aa3b, v56
	v_exp_f32_e32 v3, v3
	s_nop 0
	v_add_f32_e32 v3, 1.0, v3
	v_rcp_f32_e32 v3, v3
	s_nop 0
	v_mul_f32_e32 v3, v56, v3
	v_mul_f32_e32 v3, v3, v8
	v_mul_f32_e32 v8, 0xbfb8aa3b, v57
	v_exp_f32_e32 v8, v8
	s_nop 0
	v_add_f32_e32 v8, 1.0, v8
	v_rcp_f32_e32 v8, v8
	s_nop 0
	v_mul_f32_e32 v8, v57, v8
	v_mul_f32_e32 v8, v8, v9
	v_cvt_pk_bf16_f32 v11, v3, v8
	v_add_co_u32_e32 v8, vcc, s14, v132
	s_nop 1
	v_addc_co_u32_e32 v9, vcc, 0, v133, vcc
	v_mov_b32_e32 v242, v10
	v_mov_b32_e32 v243, v11
	global_store_dwordx4 v[8:9], v[240:243], off
	v_mov_b32_e32 v8, v92
	v_mov_b32_e32 v9, v92
	v_pk_mul_f32 v[8:9], v[6:7], v[8:9]
	v_pk_mul_f32 v[10:11], v[4:5], v[92:93]
	v_pk_fma_f32 v[4:5], v[8:9], v[30:31], v[34:35]
	v_pk_fma_f32 v[6:7], v[10:11], v[28:29], v[32:33]
	v_mov_b32_e32 v3, v4
	s_and_b64 vcc, exec, s[12:13]
	s_nop 1
	v_fmac_f32_dpp v6, v10, v24 row_shr:1 row_mask:0xf bank_mask:0xf bound_ctrl:0
	v_fmac_f32_dpp v7, v11, v25 row_shr:1 row_mask:0xf bank_mask:0xf bound_ctrl:0
	v_fmac_f32_dpp v3, v8, v26 row_shr:1 row_mask:0xf bank_mask:0xf bound_ctrl:0
	v_fmac_f32_dpp v5, v9, v27 row_shr:1 row_mask:0xf bank_mask:0xf bound_ctrl:0
	v_fmac_f32_dpp v6, v10, v20 row_shr:2 row_mask:0xf bank_mask:0xf bound_ctrl:0
	v_fmac_f32_dpp v7, v11, v21 row_shr:2 row_mask:0xf bank_mask:0xf bound_ctrl:0
	v_fmac_f32_dpp v3, v8, v22 row_shr:2 row_mask:0xf bank_mask:0xf bound_ctrl:0
	v_fmac_f32_dpp v5, v9, v23 row_shr:2 row_mask:0xf bank_mask:0xf bound_ctrl:0
	v_fmac_f32_dpp v6, v18, v24 row_shl:15 row_mask:0xf bank_mask:0xf bound_ctrl:0
	v_fmac_f32_dpp v7, v19, v25 row_shl:15 row_mask:0xf bank_mask:0xf bound_ctrl:0
	v_fmac_f32_dpp v3, v16, v26 row_shl:15 row_mask:0xf bank_mask:0xf bound_ctrl:0
	v_fmac_f32_dpp v5, v17, v27 row_shl:15 row_mask:0xf bank_mask:0xf bound_ctrl:0
	v_fmac_f32_dpp v6, v18, v20 row_shl:14 row_mask:0xf bank_mask:0xf bound_ctrl:0
	v_fmac_f32_dpp v7, v19, v21 row_shl:14 row_mask:0xf bank_mask:0xf bound_ctrl:0
	v_fmac_f32_dpp v3, v16, v22 row_shl:14 row_mask:0xf bank_mask:0xf bound_ctrl:0
	v_fmac_f32_dpp v5, v17, v23 row_shl:14 row_mask:0xf bank_mask:0xf bound_ctrl:0
	s_cbranch_vccnz .LBB0_752
	v_mov_b32_dpp v12, v10 row_shr:1 row_mask:0xf bank_mask:0xf bound_ctrl:1
	v_mov_b32_dpp v13, v11 row_shr:1 row_mask:0xf bank_mask:0xf bound_ctrl:1
	v_mov_b32_dpp v14, v8 row_shr:1 row_mask:0xf bank_mask:0xf bound_ctrl:1
	v_mov_b32_dpp v15, v9 row_shr:1 row_mask:0xf bank_mask:0xf bound_ctrl:1
	s_and_saveexec_b64 s[12:13], s[10:11]
	s_cbranch_execz .LBB0_751
	v_mov_b64_e32 v[16:17], s[24:25]
	s_mov_b32 s14, 0xb000
	v_mad_u64_u32 v[16:17], s[10:11], v136, s14, v[16:17]
	v_mov_b32_e32 v4, v17
	v_mad_u64_u32 v[18:19], s[10:11], v137, s14, v[4:5]
	v_pk_mul_f32 v[12:13], v[20:21], v[12:13]
	v_mov_b32_e32 v17, v18
	v_pk_mul_f32 v[14:15], v[22:23], v[14:15]
	v_pk_fma_f32 v[12:13], v[10:11], v[24:25], v[12:13]
	v_lshl_add_u64 v[24:25], v[184:185], 2, v[16:17]
	v_pk_fma_f32 v[14:15], v[8:9], v[26:27], v[14:15]
	v_pk_mul_f32 v[18:19], v[8:9], v[22:23]
	v_add_co_u32_e32 v8, vcc, 0x5000, v24
	v_pk_mul_f32 v[16:17], v[10:11], v[20:21]
	s_nop 0
	v_addc_co_u32_e32 v9, vcc, 0, v25, vcc
	global_store_dwordx4 v[24:25], v[16:19], off offset:528
	global_store_dwordx4 v[8:9], v[12:15], off offset:2576

.LBB0_752:
	v_mul_f32_e32 v4, 0xbfb8aa3b, v39
	v_exp_f32_e32 v4, v4
	s_mov_b64 s[10:11], -1
	v_add_f32_e32 v4, 1.0, v4
	v_rcp_f32_e32 v4, v4
	s_nop 0
	v_mul_f32_e32 v4, v39, v4
	v_mul_f32_e32 v4, v4, v6
	v_mul_f32_e32 v6, 0xbfb8aa3b, v49
	v_exp_f32_e32 v6, v6
	s_nop 0
	v_add_f32_e32 v6, 1.0, v6
	v_rcp_f32_e32 v6, v6
	s_nop 0
	v_mul_f32_e32 v6, v49, v6
	v_mul_f32_e32 v6, v6, v7
	v_cvt_pk_bf16_f32 v4, v4, v6
	v_mul_f32_e32 v6, 0xbfb8aa3b, v37
	v_exp_f32_e32 v6, v6
	s_nop 0
	v_add_f32_e32 v6, 1.0, v6
	v_rcp_f32_e32 v6, v6
	s_nop 0
	v_mul_f32_e32 v6, v37, v6
	v_mul_f32_e32 v3, v6, v3
	v_mul_f32_e32 v6, 0xbfb8aa3b, v51
	v_exp_f32_e32 v6, v6
	s_nop 0
	v_add_f32_e32 v6, 1.0, v6
	v_rcp_f32_e32 v6, v6
	s_nop 0
	v_mul_f32_e32 v6, v51, v6
	v_mul_f32_e32 v5, v6, v5
	v_add_co_u32_e32 v6, vcc, 0x5000, v132
	v_cvt_pk_bf16_f32 v5, v3, v5
	s_nop 1
	v_addc_co_u32_e32 v7, vcc, 0, v133, vcc
	s_andn2_b64 vcc, exec, s[8:9]
	v_mov_b32_e32 v246, v4
	v_mov_b32_e32 v247, v5
	global_store_dwordx4 v[6:7], v[244:247], off offset:2048
	s_cbranch_vccnz .LBB0_675
	v_readlane_b32 s8, v253, 13
	v_readlane_b32 s9, v253, 14
	s_andn2_b64 vcc, exec, s[8:9]
	s_cbranch_vccnz .LBB0_674
	s_barrier
	s_branch .LBB0_674

.LBB0_823:
	s_add_u32 s26, s24, 0x4000
	s_addc_u32 s27, s25, 0
	s_cmp_eq_u32 s52, 40
	s_cselect_b32 s30, s10, s26
	s_cselect_b32 s31, s11, s27
	s_cselect_b32 s28, s22, s50
	s_cselect_b32 s29, s23, s51
	s_add_u32 s26, s30, 0x8000
	s_addc_u32 s27, s31, 0
	s_add_i32 s53, 0, 0x10000
	v_add_u32_e32 v142, s53, v145
	s_add_i32 s56, 0, 0x14000
	ds_read_b128 v[148:151], v142
	ds_read_b128 v[152:155], v142 offset:1024
	ds_read_b128 v[158:161], v142 offset:2048
	ds_read_b128 v[170:173], v142 offset:3072
	v_add_u32_e32 v142, s56, v145
	ds_read_b128 v[174:177], v142
	ds_read_b128 v[178:181], v142 offset:1024
	ds_read_b128 v[182:185], v142 offset:2048
	ds_read_b128 v[186:189], v142 offset:3072
	v_lshl_add_u64 v[142:143], s[24:25], 0, v[138:139]
	s_add_i32 m0, s7, 0xc000
	ds_read_b128 v[190:193], v146
	ds_read_b128 v[194:197], v146 offset:1024
	ds_read_b128 v[198:201], v146 offset:2048
	ds_read_b128 v[202:205], v146 offset:3072
	ds_read_b128 v[220:223], v146 offset:4096
	ds_read_b128 v[224:227], v146 offset:5120
	ds_read_b128 v[228:231], v146 offset:6144
	ds_read_b128 v[232:235], v146 offset:7168
	global_load_lds_dwordx4 v[142:143], off
	v_lshl_add_u64 v[142:143], s[24:25], 0, v[140:141]
	s_add_i32 m0, s7, 0xe000
	s_nop 0
	global_load_lds_dwordx4 v[142:143], off
	s_waitcnt vmcnt(8)
	s_waitcnt lgkmcnt(0)
	s_barrier
	s_setprio 1
	s_waitcnt lgkmcnt(0)
	v_mfma_f32_16x16x32_bf16 v[128:131], v[148:151], v[190:193], v[128:131]
	v_mfma_f32_16x16x32_bf16 v[124:127], v[158:161], v[190:193], v[124:127]
	v_mfma_f32_16x16x32_bf16 v[112:115], v[148:151], v[198:201], v[112:115]
	v_mfma_f32_16x16x32_bf16 v[108:111], v[158:161], v[198:201], v[108:111]
	v_mfma_f32_16x16x32_bf16 v[96:99], v[148:151], v[220:223], v[96:99]
	v_mfma_f32_16x16x32_bf16 v[92:95], v[158:161], v[220:223], v[92:95]
	v_mfma_f32_16x16x32_bf16 v[80:83], v[148:151], v[228:231], v[80:83]
	v_mfma_f32_16x16x32_bf16 v[76:79], v[158:161], v[228:231], v[76:79]
	v_mfma_f32_16x16x32_bf16 v[128:131], v[152:155], v[194:197], v[128:131]
	v_mfma_f32_16x16x32_bf16 v[124:127], v[170:173], v[194:197], v[124:127]
	v_mfma_f32_16x16x32_bf16 v[112:115], v[152:155], v[202:205], v[112:115]
	v_mfma_f32_16x16x32_bf16 v[108:111], v[170:173], v[202:205], v[108:111]
	v_mfma_f32_16x16x32_bf16 v[96:99], v[152:155], v[224:227], v[96:99]
	v_mfma_f32_16x16x32_bf16 v[92:95], v[170:173], v[224:227], v[92:95]
	v_mfma_f32_16x16x32_bf16 v[80:83], v[152:155], v[232:235], v[80:83]
	v_mfma_f32_16x16x32_bf16 v[76:79], v[170:173], v[232:235], v[76:79]
	v_mfma_f32_16x16x32_bf16 v[120:123], v[174:177], v[190:193], v[120:123]
	v_mfma_f32_16x16x32_bf16 v[116:119], v[182:185], v[190:193], v[116:119]
	v_mfma_f32_16x16x32_bf16 v[104:107], v[174:177], v[198:201], v[104:107]
	v_mfma_f32_16x16x32_bf16 v[100:103], v[182:185], v[198:201], v[100:103]
	v_mfma_f32_16x16x32_bf16 v[88:91], v[174:177], v[220:223], v[88:91]
	v_mfma_f32_16x16x32_bf16 v[84:87], v[182:185], v[220:223], v[84:87]
	v_mfma_f32_16x16x32_bf16 v[72:75], v[174:177], v[228:231], v[72:75]
	v_mfma_f32_16x16x32_bf16 v[68:71], v[182:185], v[228:231], v[68:71]
	v_mfma_f32_16x16x32_bf16 v[120:123], v[178:181], v[194:197], v[120:123]
	v_mfma_f32_16x16x32_bf16 v[116:119], v[186:189], v[194:197], v[116:119]
	v_mfma_f32_16x16x32_bf16 v[104:107], v[178:181], v[202:205], v[104:107]
	v_mfma_f32_16x16x32_bf16 v[100:103], v[186:189], v[202:205], v[100:103]
	v_mfma_f32_16x16x32_bf16 v[88:91], v[178:181], v[224:227], v[88:91]
	v_mfma_f32_16x16x32_bf16 v[84:87], v[186:189], v[224:227], v[84:87]
	v_mfma_f32_16x16x32_bf16 v[72:75], v[178:181], v[232:235], v[72:75]
	v_mfma_f32_16x16x32_bf16 v[68:71], v[186:189], v[232:235], v[68:71]
	s_setprio 0
	s_barrier
	s_add_i32 s53, s53, s6
	v_lshl_add_u64 v[142:143], s[28:29], 0, v[134:135]
	s_mov_b32 m0, s53
	ds_read_b128 v[190:193], v146 offset:16384
	ds_read_b128 v[194:197], v146 offset:17408
	ds_read_b128 v[198:201], v146 offset:18432
	ds_read_b128 v[202:205], v146 offset:19456
	ds_read_b128 v[220:223], v146 offset:20480
	ds_read_b128 v[224:227], v146 offset:21504
	ds_read_b128 v[228:231], v146 offset:22528
	ds_read_b128 v[232:235], v146 offset:23552
	global_load_lds_dwordx4 v[142:143], off
	s_add_i32 m0, s53, 0x2000
	s_add_u32 s54, s28, 0xb0000
	v_lshl_add_u64 v[206:207], s[28:29], 0, v[0:1]
	s_addc_u32 s55, s29, 0
	s_add_i32 s53, s56, s6
	global_load_lds_dwordx4 v[206:207], off
	v_lshl_add_u64 v[236:237], s[54:55], 0, v[134:135]
	s_mov_b32 m0, s53
	s_nop 0
	global_load_lds_dwordx4 v[236:237], off
	v_lshl_add_u64 v[236:237], s[54:55], 0, v[0:1]
	s_add_i32 m0, s53, 0x2000
	s_nop 0
	global_load_lds_dwordx4 v[236:237], off
	v_lshl_add_u64 v[236:237], s[30:31], 0, v[136:137]
	s_mov_b32 m0, s7
	s_nop 0
	global_load_lds_dwordx4 v[236:237], off
	v_lshl_add_u64 v[236:237], s[30:31], 0, v[132:133]
	s_mov_b32 m0, s38
	s_nop 0
	global_load_lds_dwordx4 v[236:237], off
	s_waitcnt vmcnt(8)
	s_waitcnt lgkmcnt(0)
	s_barrier
	s_setprio 1
	s_waitcnt lgkmcnt(0)
	v_mfma_f32_16x16x32_bf16 v[64:67], v[148:151], v[190:193], v[64:67]
	v_mfma_f32_16x16x32_bf16 v[60:63], v[158:161], v[190:193], v[60:63]
	v_mfma_f32_16x16x32_bf16 v[48:51], v[148:151], v[198:201], v[48:51]
	v_mfma_f32_16x16x32_bf16 v[44:47], v[158:161], v[198:201], v[44:47]
	v_mfma_f32_16x16x32_bf16 v[32:35], v[148:151], v[220:223], v[32:35]
	v_mfma_f32_16x16x32_bf16 v[28:31], v[158:161], v[220:223], v[28:31]
	v_mfma_f32_16x16x32_bf16 v[16:19], v[148:151], v[228:231], v[16:19]
	v_mfma_f32_16x16x32_bf16 v[12:15], v[158:161], v[228:231], v[12:15]
	v_mfma_f32_16x16x32_bf16 v[64:67], v[152:155], v[194:197], v[64:67]
	v_mfma_f32_16x16x32_bf16 v[60:63], v[170:173], v[194:197], v[60:63]
	v_mfma_f32_16x16x32_bf16 v[48:51], v[152:155], v[202:205], v[48:51]
	v_mfma_f32_16x16x32_bf16 v[44:47], v[170:173], v[202:205], v[44:47]
	v_mfma_f32_16x16x32_bf16 v[32:35], v[152:155], v[224:227], v[32:35]
	v_mfma_f32_16x16x32_bf16 v[28:31], v[170:173], v[224:227], v[28:31]
	v_mfma_f32_16x16x32_bf16 v[16:19], v[152:155], v[232:235], v[16:19]
	v_mfma_f32_16x16x32_bf16 v[12:15], v[170:173], v[232:235], v[12:15]
	v_mfma_f32_16x16x32_bf16 v[56:59], v[174:177], v[190:193], v[56:59]
	v_mfma_f32_16x16x32_bf16 v[52:55], v[182:185], v[190:193], v[52:55]
	v_mfma_f32_16x16x32_bf16 v[40:43], v[174:177], v[198:201], v[40:43]
	v_mfma_f32_16x16x32_bf16 v[36:39], v[182:185], v[198:201], v[36:39]
	v_mfma_f32_16x16x32_bf16 v[24:27], v[174:177], v[220:223], v[24:27]
	v_mfma_f32_16x16x32_bf16 v[20:23], v[182:185], v[220:223], v[20:23]
	v_mfma_f32_16x16x32_bf16 v[8:11], v[174:177], v[228:231], v[8:11]
	v_mfma_f32_16x16x32_bf16 v[4:7], v[182:185], v[228:231], v[4:7]
	v_mfma_f32_16x16x32_bf16 v[56:59], v[178:181], v[194:197], v[56:59]
	v_mfma_f32_16x16x32_bf16 v[52:55], v[186:189], v[194:197], v[52:55]
	v_mfma_f32_16x16x32_bf16 v[40:43], v[178:181], v[202:205], v[40:43]
	v_mfma_f32_16x16x32_bf16 v[36:39], v[186:189], v[202:205], v[36:39]
	v_mfma_f32_16x16x32_bf16 v[24:27], v[178:181], v[224:227], v[24:27]
	v_mfma_f32_16x16x32_bf16 v[20:23], v[186:189], v[224:227], v[20:23]
	v_mfma_f32_16x16x32_bf16 v[8:11], v[178:181], v[232:235], v[8:11]
	v_mfma_f32_16x16x32_bf16 v[4:7], v[186:189], v[232:235], v[4:7]
	s_setprio 0
	s_barrier
	s_add_i32 s53, 0, 0x18000
	v_add_u32_e32 v147, s53, v145
	s_add_i32 s54, 0, 0x1c000
	ds_read_b128 v[148:151], v147
	ds_read_b128 v[152:155], v147 offset:1024
	ds_read_b128 v[158:161], v147 offset:2048
	ds_read_b128 v[170:173], v147 offset:3072
	v_add_u32_e32 v147, s54, v145
	ds_read_b128 v[174:177], v147
	ds_read_b128 v[178:181], v147 offset:1024
	ds_read_b128 v[182:185], v147 offset:2048
	ds_read_b128 v[186:189], v147 offset:3072
	s_add_u32 s30, s30, 0x4000
	s_addc_u32 s31, s31, 0
	s_mov_b32 m0, s39
	v_lshl_add_u64 v[236:237], s[30:31], 0, v[136:137]
	ds_read_b128 v[190:193], v146 offset:32768
	ds_read_b128 v[194:197], v146 offset:33792
	ds_read_b128 v[198:201], v146 offset:34816
	ds_read_b128 v[202:205], v146 offset:35840
	ds_read_b128 v[220:223], v146 offset:36864
	ds_read_b128 v[224:227], v146 offset:37888
	ds_read_b128 v[228:231], v146 offset:38912
	ds_read_b128 v[232:235], v146 offset:39936
	global_load_lds_dwordx4 v[236:237], off
	v_lshl_add_u64 v[236:237], s[30:31], 0, v[132:133]
	s_mov_b32 m0, s40
	s_nop 0
	global_load_lds_dwordx4 v[236:237], off
	s_waitcnt vmcnt(8)
	s_waitcnt lgkmcnt(0)
	s_barrier
	s_setprio 1
	s_waitcnt lgkmcnt(0)
	v_mfma_f32_16x16x32_bf16 v[128:131], v[148:151], v[190:193], v[128:131]
	v_mfma_f32_16x16x32_bf16 v[124:127], v[158:161], v[190:193], v[124:127]
	v_mfma_f32_16x16x32_bf16 v[112:115], v[148:151], v[198:201], v[112:115]
	v_mfma_f32_16x16x32_bf16 v[108:111], v[158:161], v[198:201], v[108:111]
	v_mfma_f32_16x16x32_bf16 v[96:99], v[148:151], v[220:223], v[96:99]
	v_mfma_f32_16x16x32_bf16 v[92:95], v[158:161], v[220:223], v[92:95]
	v_mfma_f32_16x16x32_bf16 v[80:83], v[148:151], v[228:231], v[80:83]
	v_mfma_f32_16x16x32_bf16 v[76:79], v[158:161], v[228:231], v[76:79]
	v_mfma_f32_16x16x32_bf16 v[128:131], v[152:155], v[194:197], v[128:131]
	v_mfma_f32_16x16x32_bf16 v[124:127], v[170:173], v[194:197], v[124:127]
	v_mfma_f32_16x16x32_bf16 v[112:115], v[152:155], v[202:205], v[112:115]
	v_mfma_f32_16x16x32_bf16 v[108:111], v[170:173], v[202:205], v[108:111]
	v_mfma_f32_16x16x32_bf16 v[96:99], v[152:155], v[224:227], v[96:99]
	v_mfma_f32_16x16x32_bf16 v[92:95], v[170:173], v[224:227], v[92:95]
	v_mfma_f32_16x16x32_bf16 v[80:83], v[152:155], v[232:235], v[80:83]
	v_mfma_f32_16x16x32_bf16 v[76:79], v[170:173], v[232:235], v[76:79]
	v_mfma_f32_16x16x32_bf16 v[120:123], v[174:177], v[190:193], v[120:123]
	v_mfma_f32_16x16x32_bf16 v[116:119], v[182:185], v[190:193], v[116:119]
	v_mfma_f32_16x16x32_bf16 v[104:107], v[174:177], v[198:201], v[104:107]
	v_mfma_f32_16x16x32_bf16 v[100:103], v[182:185], v[198:201], v[100:103]
	v_mfma_f32_16x16x32_bf16 v[88:91], v[174:177], v[220:223], v[88:91]
	v_mfma_f32_16x16x32_bf16 v[84:87], v[182:185], v[220:223], v[84:87]
	v_mfma_f32_16x16x32_bf16 v[72:75], v[174:177], v[228:231], v[72:75]
	v_mfma_f32_16x16x32_bf16 v[68:71], v[182:185], v[228:231], v[68:71]
	v_mfma_f32_16x16x32_bf16 v[120:123], v[178:181], v[194:197], v[120:123]
	v_mfma_f32_16x16x32_bf16 v[116:119], v[186:189], v[194:197], v[116:119]
	v_mfma_f32_16x16x32_bf16 v[104:107], v[178:181], v[202:205], v[104:107]
	v_mfma_f32_16x16x32_bf16 v[100:103], v[186:189], v[202:205], v[100:103]
	v_mfma_f32_16x16x32_bf16 v[88:91], v[178:181], v[224:227], v[88:91]
	v_mfma_f32_16x16x32_bf16 v[84:87], v[186:189], v[224:227], v[84:87]
	v_mfma_f32_16x16x32_bf16 v[72:75], v[178:181], v[232:235], v[72:75]
	v_mfma_f32_16x16x32_bf16 v[68:71], v[186:189], v[232:235], v[68:71]
	s_setprio 0
	s_barrier
	s_add_i32 s30, s53, s6
	v_lshl_add_u64 v[142:143], v[142:143], 0, s[76:77]
	s_mov_b32 m0, s30
	ds_read_b128 v[190:193], v146 offset:49152
	ds_read_b128 v[194:197], v146 offset:50176
	ds_read_b128 v[198:201], v146 offset:51200
	ds_read_b128 v[202:205], v146 offset:52224
	ds_read_b128 v[220:223], v146 offset:53248
	ds_read_b128 v[224:227], v146 offset:54272
	ds_read_b128 v[228:231], v146 offset:55296
	ds_read_b128 v[232:235], v146 offset:56320
	global_load_lds_dwordx4 v[142:143], off
	s_add_i32 m0, s30, 0x2000
	s_add_u32 s28, s28, 0xb0080
	v_lshl_add_u64 v[142:143], v[206:207], 0, s[76:77]
	s_addc_u32 s29, s29, 0
	s_add_i32 s30, s54, s6
	global_load_lds_dwordx4 v[142:143], off
	v_lshl_add_u64 v[142:143], s[28:29], 0, v[134:135]
	s_mov_b32 m0, s30
	s_nop 0
	global_load_lds_dwordx4 v[142:143], off
	v_lshl_add_u64 v[142:143], s[28:29], 0, v[0:1]
	s_add_i32 m0, s30, 0x2000
	s_nop 0
	global_load_lds_dwordx4 v[142:143], off
	v_lshl_add_u64 v[142:143], s[26:27], 0, v[136:137]
	s_mov_b32 m0, s43
	s_nop 0
	global_load_lds_dwordx4 v[142:143], off
	v_lshl_add_u64 v[142:143], s[26:27], 0, v[132:133]
	s_mov_b32 m0, s44
	s_nop 0
	global_load_lds_dwordx4 v[142:143], off
	s_waitcnt vmcnt(8)
	s_waitcnt lgkmcnt(0)
	s_barrier
	s_setprio 1
	s_waitcnt lgkmcnt(0)
	v_mfma_f32_16x16x32_bf16 v[64:67], v[148:151], v[190:193], v[64:67]
	v_mfma_f32_16x16x32_bf16 v[60:63], v[158:161], v[190:193], v[60:63]
	v_mfma_f32_16x16x32_bf16 v[48:51], v[148:151], v[198:201], v[48:51]
	v_mfma_f32_16x16x32_bf16 v[44:47], v[158:161], v[198:201], v[44:47]
	v_mfma_f32_16x16x32_bf16 v[32:35], v[148:151], v[220:223], v[32:35]
	v_mfma_f32_16x16x32_bf16 v[28:31], v[158:161], v[220:223], v[28:31]
	v_mfma_f32_16x16x32_bf16 v[16:19], v[148:151], v[228:231], v[16:19]
	v_mfma_f32_16x16x32_bf16 v[12:15], v[158:161], v[228:231], v[12:15]
	v_mfma_f32_16x16x32_bf16 v[64:67], v[152:155], v[194:197], v[64:67]
	v_mfma_f32_16x16x32_bf16 v[60:63], v[170:173], v[194:197], v[60:63]
	v_mfma_f32_16x16x32_bf16 v[48:51], v[152:155], v[202:205], v[48:51]
	v_mfma_f32_16x16x32_bf16 v[44:47], v[170:173], v[202:205], v[44:47]
	v_mfma_f32_16x16x32_bf16 v[32:35], v[152:155], v[224:227], v[32:35]
	v_mfma_f32_16x16x32_bf16 v[28:31], v[170:173], v[224:227], v[28:31]
	v_mfma_f32_16x16x32_bf16 v[16:19], v[152:155], v[232:235], v[16:19]
	v_mfma_f32_16x16x32_bf16 v[12:15], v[170:173], v[232:235], v[12:15]
	v_mfma_f32_16x16x32_bf16 v[56:59], v[174:177], v[190:193], v[56:59]
	v_mfma_f32_16x16x32_bf16 v[52:55], v[182:185], v[190:193], v[52:55]
	v_mfma_f32_16x16x32_bf16 v[40:43], v[174:177], v[198:201], v[40:43]
	v_mfma_f32_16x16x32_bf16 v[36:39], v[182:185], v[198:201], v[36:39]
	v_mfma_f32_16x16x32_bf16 v[24:27], v[174:177], v[220:223], v[24:27]
	v_mfma_f32_16x16x32_bf16 v[20:23], v[182:185], v[220:223], v[20:23]
	v_mfma_f32_16x16x32_bf16 v[8:11], v[174:177], v[228:231], v[8:11]
	v_mfma_f32_16x16x32_bf16 v[4:7], v[182:185], v[228:231], v[4:7]
	v_mfma_f32_16x16x32_bf16 v[56:59], v[178:181], v[194:197], v[56:59]
	v_mfma_f32_16x16x32_bf16 v[52:55], v[186:189], v[194:197], v[52:55]
	v_mfma_f32_16x16x32_bf16 v[40:43], v[178:181], v[202:205], v[40:43]
	v_mfma_f32_16x16x32_bf16 v[36:39], v[186:189], v[202:205], v[36:39]
	v_mfma_f32_16x16x32_bf16 v[24:27], v[178:181], v[224:227], v[24:27]
	v_mfma_f32_16x16x32_bf16 v[20:23], v[186:189], v[224:227], v[20:23]
	v_mfma_f32_16x16x32_bf16 v[8:11], v[178:181], v[232:235], v[8:11]
	v_mfma_f32_16x16x32_bf16 v[4:7], v[186:189], v[232:235], v[4:7]
	s_setprio 0
	s_barrier
	s_add_i32 s52, s52, 2
	s_add_u32 s50, s50, 0x100
	s_addc_u32 s51, s51, 0
	s_add_u32 s24, s24, 0x10000
	s_addc_u32 s25, s25, 0
	s_cmp_gt_u32 s52, 41
	s_cbranch_scc0 .LBB0_823
	s_lshl_b32 s29, s49, 8
	s_add_i32 s29, s29, s41
	v_add_u32_e32 v147, s29, v3
	s_lshl_b32 s29, s48, 8
	s_or_b32 s29, s29, s42
	v_lshlrev_b32_e32 v142, 10, v147
	v_lshl_add_u32 v147, v144, 3, s29
	v_add_u32_e32 v142, v142, v147
	v_lshlrev_b32_e32 v143, 2, v142
	v_lshlrev_b32_e32 v142, 1, v142
	s_mov_b64 s[26:27], s[12:13]
	global_load_dwordx4 v[170:173], v142, s[26:27]
	global_load_dwordx4 v[174:177], v142, s[26:27] offset:256
	s_add_u32 s26, s26, 0x8000
	s_addc_u32 s27, s27, 0
	global_load_dwordx4 v[178:181], v142, s[26:27]
	global_load_dwordx4 v[182:185], v142, s[26:27] offset:256
	s_add_u32 s26, s26, 0x8000
	s_addc_u32 s27, s27, 0
	global_load_dwordx4 v[186:189], v142, s[26:27]
	global_load_dwordx4 v[190:193], v142, s[26:27] offset:256
	s_add_u32 s26, s26, 0x8000
	s_addc_u32 s27, s27, 0
	global_load_dwordx4 v[194:197], v142, s[26:27]
	global_load_dwordx4 v[198:201], v142, s[26:27] offset:256
	s_add_u32 s26, s26, 0x28000
	s_addc_u32 s27, s27, 0
	global_load_dwordx4 v[202:205], v142, s[26:27]
	global_load_dwordx4 v[220:223], v142, s[26:27] offset:256
	s_add_u32 s26, s26, 0x8000
	s_addc_u32 s27, s27, 0
	global_load_dwordx4 v[224:227], v142, s[26:27]
	global_load_dwordx4 v[228:231], v142, s[26:27] offset:256
	s_add_u32 s26, s26, 0x8000
	s_addc_u32 s27, s27, 0
	global_load_dwordx4 v[232:235], v142, s[26:27]
	global_load_dwordx4 v[158:161], v142, s[26:27] offset:256
	s_add_u32 s26, s26, 0x8000
	s_addc_u32 s27, s27, 0
	global_load_dwordx4 v[152:155], v142, s[26:27]
	global_load_dwordx4 v[148:151], v142, s[26:27] offset:256
	s_and_b64 vcc, exec, s[20:21]
	s_cbranch_vccz .Lres7a_nobar
	s_barrier

.LBB0_849:
	s_add_u32 s20, s8, 0x4000
	s_addc_u32 s21, s9, 0
	s_cmp_eq_u32 s50, 40
	s_cselect_b32 s24, s14, s20
	s_cselect_b32 s25, s15, s21
	s_cselect_b32 s22, s18, s48
	s_cselect_b32 s23, s19, s49
	s_add_u32 s20, s24, 0x8000
	s_addc_u32 s21, s25, 0
	s_add_i32 s51, 0, 0x10000
	v_add_u32_e32 v149, s51, v147
	s_add_i32 s54, 0, 0x14000
	ds_read_b128 v[142:145], v149
	ds_read_b128 v[150:153], v149 offset:1024
	ds_read_b128 v[158:161], v149 offset:2048
	ds_read_b128 v[170:173], v149 offset:3072
	v_add_u32_e32 v149, s54, v147
	ds_read_b128 v[174:177], v149
	ds_read_b128 v[178:181], v149 offset:1024
	ds_read_b128 v[182:185], v149 offset:2048
	ds_read_b128 v[186:189], v149 offset:3072
	v_lshl_add_u64 v[154:155], s[8:9], 0, v[138:139]
	s_add_i32 m0, s27, 0xc000
	ds_read_b128 v[190:193], v148
	ds_read_b128 v[194:197], v148 offset:1024
	ds_read_b128 v[198:201], v148 offset:2048
	ds_read_b128 v[202:205], v148 offset:3072
	ds_read_b128 v[220:223], v148 offset:4096
	ds_read_b128 v[224:227], v148 offset:5120
	ds_read_b128 v[228:231], v148 offset:6144
	ds_read_b128 v[232:235], v148 offset:7168
	global_load_lds_dwordx4 v[154:155], off
	v_lshl_add_u64 v[154:155], s[8:9], 0, v[140:141]
	s_add_i32 m0, s27, 0xe000
	s_nop 0
	global_load_lds_dwordx4 v[154:155], off
	s_waitcnt vmcnt(8)
	s_waitcnt lgkmcnt(0)
	s_barrier
	s_setprio 1
	s_waitcnt lgkmcnt(0)
	v_mfma_f32_16x16x32_bf16 v[128:131], v[142:145], v[190:193], v[128:131]
	v_mfma_f32_16x16x32_bf16 v[124:127], v[158:161], v[190:193], v[124:127]
	v_mfma_f32_16x16x32_bf16 v[112:115], v[142:145], v[198:201], v[112:115]
	v_mfma_f32_16x16x32_bf16 v[108:111], v[158:161], v[198:201], v[108:111]
	v_mfma_f32_16x16x32_bf16 v[96:99], v[142:145], v[220:223], v[96:99]
	v_mfma_f32_16x16x32_bf16 v[92:95], v[158:161], v[220:223], v[92:95]
	v_mfma_f32_16x16x32_bf16 v[80:83], v[142:145], v[228:231], v[80:83]
	v_mfma_f32_16x16x32_bf16 v[76:79], v[158:161], v[228:231], v[76:79]
	v_mfma_f32_16x16x32_bf16 v[128:131], v[150:153], v[194:197], v[128:131]
	v_mfma_f32_16x16x32_bf16 v[124:127], v[170:173], v[194:197], v[124:127]
	v_mfma_f32_16x16x32_bf16 v[112:115], v[150:153], v[202:205], v[112:115]
	v_mfma_f32_16x16x32_bf16 v[108:111], v[170:173], v[202:205], v[108:111]
	v_mfma_f32_16x16x32_bf16 v[96:99], v[150:153], v[224:227], v[96:99]
	v_mfma_f32_16x16x32_bf16 v[92:95], v[170:173], v[224:227], v[92:95]
	v_mfma_f32_16x16x32_bf16 v[80:83], v[150:153], v[232:235], v[80:83]
	v_mfma_f32_16x16x32_bf16 v[76:79], v[170:173], v[232:235], v[76:79]
	v_mfma_f32_16x16x32_bf16 v[120:123], v[174:177], v[190:193], v[120:123]
	v_mfma_f32_16x16x32_bf16 v[116:119], v[182:185], v[190:193], v[116:119]
	v_mfma_f32_16x16x32_bf16 v[104:107], v[174:177], v[198:201], v[104:107]
	v_mfma_f32_16x16x32_bf16 v[100:103], v[182:185], v[198:201], v[100:103]
	v_mfma_f32_16x16x32_bf16 v[88:91], v[174:177], v[220:223], v[88:91]
	v_mfma_f32_16x16x32_bf16 v[84:87], v[182:185], v[220:223], v[84:87]
	v_mfma_f32_16x16x32_bf16 v[72:75], v[174:177], v[228:231], v[72:75]
	v_mfma_f32_16x16x32_bf16 v[68:71], v[182:185], v[228:231], v[68:71]
	v_mfma_f32_16x16x32_bf16 v[120:123], v[178:181], v[194:197], v[120:123]
	v_mfma_f32_16x16x32_bf16 v[116:119], v[186:189], v[194:197], v[116:119]
	v_mfma_f32_16x16x32_bf16 v[104:107], v[178:181], v[202:205], v[104:107]
	v_mfma_f32_16x16x32_bf16 v[100:103], v[186:189], v[202:205], v[100:103]
	v_mfma_f32_16x16x32_bf16 v[88:91], v[178:181], v[224:227], v[88:91]
	v_mfma_f32_16x16x32_bf16 v[84:87], v[186:189], v[224:227], v[84:87]
	v_mfma_f32_16x16x32_bf16 v[72:75], v[178:181], v[232:235], v[72:75]
	v_mfma_f32_16x16x32_bf16 v[68:71], v[186:189], v[232:235], v[68:71]
	s_setprio 0
	s_barrier
	s_add_i32 s51, s51, s26
	v_lshl_add_u64 v[154:155], s[22:23], 0, v[134:135]
	s_mov_b32 m0, s51
	ds_read_b128 v[190:193], v148 offset:16384
	ds_read_b128 v[194:197], v148 offset:17408
	ds_read_b128 v[198:201], v148 offset:18432
	ds_read_b128 v[202:205], v148 offset:19456
	ds_read_b128 v[220:223], v148 offset:20480
	ds_read_b128 v[224:227], v148 offset:21504
	ds_read_b128 v[228:231], v148 offset:22528
	ds_read_b128 v[232:235], v148 offset:23552
	global_load_lds_dwordx4 v[154:155], off
	s_add_i32 m0, s51, 0x2000
	s_add_u32 s52, s22, 0xb0000
	v_lshl_add_u64 v[206:207], s[22:23], 0, v[0:1]
	s_addc_u32 s53, s23, 0
	s_add_i32 s51, s54, s26
	global_load_lds_dwordx4 v[206:207], off
	v_lshl_add_u64 v[236:237], s[52:53], 0, v[134:135]
	s_mov_b32 m0, s51
	s_nop 0
	global_load_lds_dwordx4 v[236:237], off
	v_lshl_add_u64 v[236:237], s[52:53], 0, v[0:1]
	s_add_i32 m0, s51, 0x2000
	s_nop 0
	global_load_lds_dwordx4 v[236:237], off
	v_lshl_add_u64 v[236:237], s[24:25], 0, v[136:137]
	s_mov_b32 m0, s27
	s_nop 0
	global_load_lds_dwordx4 v[236:237], off
	v_lshl_add_u64 v[236:237], s[24:25], 0, v[132:133]
	s_mov_b32 m0, s28
	s_nop 0
	global_load_lds_dwordx4 v[236:237], off
	s_waitcnt vmcnt(8)
	s_waitcnt lgkmcnt(0)
	s_barrier
	s_setprio 1
	s_waitcnt lgkmcnt(0)
	v_mfma_f32_16x16x32_bf16 v[64:67], v[142:145], v[190:193], v[64:67]
	v_mfma_f32_16x16x32_bf16 v[60:63], v[158:161], v[190:193], v[60:63]
	v_mfma_f32_16x16x32_bf16 v[48:51], v[142:145], v[198:201], v[48:51]
	v_mfma_f32_16x16x32_bf16 v[44:47], v[158:161], v[198:201], v[44:47]
	v_mfma_f32_16x16x32_bf16 v[32:35], v[142:145], v[220:223], v[32:35]
	v_mfma_f32_16x16x32_bf16 v[28:31], v[158:161], v[220:223], v[28:31]
	v_mfma_f32_16x16x32_bf16 v[16:19], v[142:145], v[228:231], v[16:19]
	v_mfma_f32_16x16x32_bf16 v[12:15], v[158:161], v[228:231], v[12:15]
	v_mfma_f32_16x16x32_bf16 v[64:67], v[150:153], v[194:197], v[64:67]
	v_mfma_f32_16x16x32_bf16 v[60:63], v[170:173], v[194:197], v[60:63]
	v_mfma_f32_16x16x32_bf16 v[48:51], v[150:153], v[202:205], v[48:51]
	v_mfma_f32_16x16x32_bf16 v[44:47], v[170:173], v[202:205], v[44:47]
	v_mfma_f32_16x16x32_bf16 v[32:35], v[150:153], v[224:227], v[32:35]
	v_mfma_f32_16x16x32_bf16 v[28:31], v[170:173], v[224:227], v[28:31]
	v_mfma_f32_16x16x32_bf16 v[16:19], v[150:153], v[232:235], v[16:19]
	v_mfma_f32_16x16x32_bf16 v[12:15], v[170:173], v[232:235], v[12:15]
	v_mfma_f32_16x16x32_bf16 v[56:59], v[174:177], v[190:193], v[56:59]
	v_mfma_f32_16x16x32_bf16 v[52:55], v[182:185], v[190:193], v[52:55]
	v_mfma_f32_16x16x32_bf16 v[40:43], v[174:177], v[198:201], v[40:43]
	v_mfma_f32_16x16x32_bf16 v[36:39], v[182:185], v[198:201], v[36:39]
	v_mfma_f32_16x16x32_bf16 v[24:27], v[174:177], v[220:223], v[24:27]
	v_mfma_f32_16x16x32_bf16 v[20:23], v[182:185], v[220:223], v[20:23]
	v_mfma_f32_16x16x32_bf16 v[8:11], v[174:177], v[228:231], v[8:11]
	v_mfma_f32_16x16x32_bf16 v[4:7], v[182:185], v[228:231], v[4:7]
	v_mfma_f32_16x16x32_bf16 v[56:59], v[178:181], v[194:197], v[56:59]
	v_mfma_f32_16x16x32_bf16 v[52:55], v[186:189], v[194:197], v[52:55]
	v_mfma_f32_16x16x32_bf16 v[40:43], v[178:181], v[202:205], v[40:43]
	v_mfma_f32_16x16x32_bf16 v[36:39], v[186:189], v[202:205], v[36:39]
	v_mfma_f32_16x16x32_bf16 v[24:27], v[178:181], v[224:227], v[24:27]
	v_mfma_f32_16x16x32_bf16 v[20:23], v[186:189], v[224:227], v[20:23]
	v_mfma_f32_16x16x32_bf16 v[8:11], v[178:181], v[232:235], v[8:11]
	v_mfma_f32_16x16x32_bf16 v[4:7], v[186:189], v[232:235], v[4:7]
	s_setprio 0
	s_barrier
	s_add_i32 s51, 0, 0x18000
	v_add_u32_e32 v149, s51, v147
	s_add_i32 s52, 0, 0x1c000
	ds_read_b128 v[142:145], v149
	ds_read_b128 v[150:153], v149 offset:1024
	ds_read_b128 v[158:161], v149 offset:2048
	ds_read_b128 v[170:173], v149 offset:3072
	v_add_u32_e32 v149, s52, v147
	ds_read_b128 v[174:177], v149
	ds_read_b128 v[178:181], v149 offset:1024
	ds_read_b128 v[182:185], v149 offset:2048
	ds_read_b128 v[186:189], v149 offset:3072
	s_add_u32 s24, s24, 0x4000
	s_addc_u32 s25, s25, 0
	s_mov_b32 m0, s29
	v_lshl_add_u64 v[236:237], s[24:25], 0, v[136:137]
	ds_read_b128 v[190:193], v148 offset:32768
	ds_read_b128 v[194:197], v148 offset:33792
	ds_read_b128 v[198:201], v148 offset:34816
	ds_read_b128 v[202:205], v148 offset:35840
	ds_read_b128 v[220:223], v148 offset:36864
	ds_read_b128 v[224:227], v148 offset:37888
	ds_read_b128 v[228:231], v148 offset:38912
	ds_read_b128 v[232:235], v148 offset:39936
	global_load_lds_dwordx4 v[236:237], off
	v_lshl_add_u64 v[236:237], s[24:25], 0, v[132:133]
	s_mov_b32 m0, s30
	s_nop 0
	global_load_lds_dwordx4 v[236:237], off
	s_waitcnt vmcnt(8)
	s_waitcnt lgkmcnt(0)
	s_barrier
	s_setprio 1
	s_waitcnt lgkmcnt(0)
	v_mfma_f32_16x16x32_bf16 v[128:131], v[142:145], v[190:193], v[128:131]
	v_mfma_f32_16x16x32_bf16 v[124:127], v[158:161], v[190:193], v[124:127]
	v_mfma_f32_16x16x32_bf16 v[112:115], v[142:145], v[198:201], v[112:115]
	v_mfma_f32_16x16x32_bf16 v[108:111], v[158:161], v[198:201], v[108:111]
	v_mfma_f32_16x16x32_bf16 v[96:99], v[142:145], v[220:223], v[96:99]
	v_mfma_f32_16x16x32_bf16 v[92:95], v[158:161], v[220:223], v[92:95]
	v_mfma_f32_16x16x32_bf16 v[80:83], v[142:145], v[228:231], v[80:83]
	v_mfma_f32_16x16x32_bf16 v[76:79], v[158:161], v[228:231], v[76:79]
	v_mfma_f32_16x16x32_bf16 v[128:131], v[150:153], v[194:197], v[128:131]
	v_mfma_f32_16x16x32_bf16 v[124:127], v[170:173], v[194:197], v[124:127]
	v_mfma_f32_16x16x32_bf16 v[112:115], v[150:153], v[202:205], v[112:115]
	v_mfma_f32_16x16x32_bf16 v[108:111], v[170:173], v[202:205], v[108:111]
	v_mfma_f32_16x16x32_bf16 v[96:99], v[150:153], v[224:227], v[96:99]
	v_mfma_f32_16x16x32_bf16 v[92:95], v[170:173], v[224:227], v[92:95]
	v_mfma_f32_16x16x32_bf16 v[80:83], v[150:153], v[232:235], v[80:83]
	v_mfma_f32_16x16x32_bf16 v[76:79], v[170:173], v[232:235], v[76:79]
	v_mfma_f32_16x16x32_bf16 v[120:123], v[174:177], v[190:193], v[120:123]
	v_mfma_f32_16x16x32_bf16 v[116:119], v[182:185], v[190:193], v[116:119]
	v_mfma_f32_16x16x32_bf16 v[104:107], v[174:177], v[198:201], v[104:107]
	v_mfma_f32_16x16x32_bf16 v[100:103], v[182:185], v[198:201], v[100:103]
	v_mfma_f32_16x16x32_bf16 v[88:91], v[174:177], v[220:223], v[88:91]
	v_mfma_f32_16x16x32_bf16 v[84:87], v[182:185], v[220:223], v[84:87]
	v_mfma_f32_16x16x32_bf16 v[72:75], v[174:177], v[228:231], v[72:75]
	v_mfma_f32_16x16x32_bf16 v[68:71], v[182:185], v[228:231], v[68:71]
	v_mfma_f32_16x16x32_bf16 v[120:123], v[178:181], v[194:197], v[120:123]
	v_mfma_f32_16x16x32_bf16 v[116:119], v[186:189], v[194:197], v[116:119]
	v_mfma_f32_16x16x32_bf16 v[104:107], v[178:181], v[202:205], v[104:107]
	v_mfma_f32_16x16x32_bf16 v[100:103], v[186:189], v[202:205], v[100:103]
	v_mfma_f32_16x16x32_bf16 v[88:91], v[178:181], v[224:227], v[88:91]
	v_mfma_f32_16x16x32_bf16 v[84:87], v[186:189], v[224:227], v[84:87]
	v_mfma_f32_16x16x32_bf16 v[72:75], v[178:181], v[232:235], v[72:75]
	v_mfma_f32_16x16x32_bf16 v[68:71], v[186:189], v[232:235], v[68:71]
	s_setprio 0
	s_barrier
	s_add_i32 s24, s51, s26
	v_lshl_add_u64 v[154:155], v[154:155], 0, s[76:77]
	s_mov_b32 m0, s24
	ds_read_b128 v[190:193], v148 offset:49152
	ds_read_b128 v[194:197], v148 offset:50176
	ds_read_b128 v[198:201], v148 offset:51200
	ds_read_b128 v[202:205], v148 offset:52224
	ds_read_b128 v[220:223], v148 offset:53248
	ds_read_b128 v[224:227], v148 offset:54272
	ds_read_b128 v[228:231], v148 offset:55296
	ds_read_b128 v[232:235], v148 offset:56320
	global_load_lds_dwordx4 v[154:155], off
	s_add_i32 m0, s24, 0x2000
	s_add_u32 s22, s22, 0xb0080
	v_lshl_add_u64 v[154:155], v[206:207], 0, s[76:77]
	s_addc_u32 s23, s23, 0
	s_add_i32 s24, s52, s26
	global_load_lds_dwordx4 v[154:155], off
	v_lshl_add_u64 v[154:155], s[22:23], 0, v[134:135]
	s_mov_b32 m0, s24
	s_nop 0
	global_load_lds_dwordx4 v[154:155], off
	v_lshl_add_u64 v[154:155], s[22:23], 0, v[0:1]
	s_add_i32 m0, s24, 0x2000
	s_nop 0
	global_load_lds_dwordx4 v[154:155], off
	v_lshl_add_u64 v[154:155], s[20:21], 0, v[136:137]
	s_mov_b32 m0, s39
	s_nop 0
	global_load_lds_dwordx4 v[154:155], off
	v_lshl_add_u64 v[154:155], s[20:21], 0, v[132:133]
	s_mov_b32 m0, s40
	s_nop 0
	global_load_lds_dwordx4 v[154:155], off
	s_waitcnt vmcnt(8)
	s_waitcnt lgkmcnt(0)
	s_barrier
	s_setprio 1
	s_waitcnt lgkmcnt(0)
	v_mfma_f32_16x16x32_bf16 v[64:67], v[142:145], v[190:193], v[64:67]
	v_mfma_f32_16x16x32_bf16 v[60:63], v[158:161], v[190:193], v[60:63]
	v_mfma_f32_16x16x32_bf16 v[48:51], v[142:145], v[198:201], v[48:51]
	v_mfma_f32_16x16x32_bf16 v[44:47], v[158:161], v[198:201], v[44:47]
	v_mfma_f32_16x16x32_bf16 v[32:35], v[142:145], v[220:223], v[32:35]
	v_mfma_f32_16x16x32_bf16 v[28:31], v[158:161], v[220:223], v[28:31]
	v_mfma_f32_16x16x32_bf16 v[16:19], v[142:145], v[228:231], v[16:19]
	v_mfma_f32_16x16x32_bf16 v[12:15], v[158:161], v[228:231], v[12:15]
	v_mfma_f32_16x16x32_bf16 v[64:67], v[150:153], v[194:197], v[64:67]
	v_mfma_f32_16x16x32_bf16 v[60:63], v[170:173], v[194:197], v[60:63]
	v_mfma_f32_16x16x32_bf16 v[48:51], v[150:153], v[202:205], v[48:51]
	v_mfma_f32_16x16x32_bf16 v[44:47], v[170:173], v[202:205], v[44:47]
	v_mfma_f32_16x16x32_bf16 v[32:35], v[150:153], v[224:227], v[32:35]
	v_mfma_f32_16x16x32_bf16 v[28:31], v[170:173], v[224:227], v[28:31]
	v_mfma_f32_16x16x32_bf16 v[16:19], v[150:153], v[232:235], v[16:19]
	v_mfma_f32_16x16x32_bf16 v[12:15], v[170:173], v[232:235], v[12:15]
	v_mfma_f32_16x16x32_bf16 v[56:59], v[174:177], v[190:193], v[56:59]
	v_mfma_f32_16x16x32_bf16 v[52:55], v[182:185], v[190:193], v[52:55]
	v_mfma_f32_16x16x32_bf16 v[40:43], v[174:177], v[198:201], v[40:43]
	v_mfma_f32_16x16x32_bf16 v[36:39], v[182:185], v[198:201], v[36:39]
	v_mfma_f32_16x16x32_bf16 v[24:27], v[174:177], v[220:223], v[24:27]
	v_mfma_f32_16x16x32_bf16 v[20:23], v[182:185], v[220:223], v[20:23]
	v_mfma_f32_16x16x32_bf16 v[8:11], v[174:177], v[228:231], v[8:11]
	v_mfma_f32_16x16x32_bf16 v[4:7], v[182:185], v[228:231], v[4:7]
	v_mfma_f32_16x16x32_bf16 v[56:59], v[178:181], v[194:197], v[56:59]
	v_mfma_f32_16x16x32_bf16 v[52:55], v[186:189], v[194:197], v[52:55]
	v_mfma_f32_16x16x32_bf16 v[40:43], v[178:181], v[202:205], v[40:43]
	v_mfma_f32_16x16x32_bf16 v[36:39], v[186:189], v[202:205], v[36:39]
	v_mfma_f32_16x16x32_bf16 v[24:27], v[178:181], v[224:227], v[24:27]
	v_mfma_f32_16x16x32_bf16 v[20:23], v[186:189], v[224:227], v[20:23]
	v_mfma_f32_16x16x32_bf16 v[8:11], v[178:181], v[232:235], v[8:11]
	v_mfma_f32_16x16x32_bf16 v[4:7], v[186:189], v[232:235], v[4:7]
	s_setprio 0
	s_barrier
	s_add_i32 s50, s50, 2
	s_add_u32 s48, s48, 0x100
	s_addc_u32 s49, s49, 0
	s_add_u32 s8, s8, 0x10000
	s_addc_u32 s9, s9, 0
	s_cmp_gt_u32 s50, 41
	s_cbranch_scc0 .LBB0_849
	s_lshl_b32 s25, s47, 8
	s_add_i32 s25, s25, s31
	v_add_u32_e32 v155, s25, v3
	s_lshl_b32 s25, s46, 8
	s_or_b32 s25, s25, s38
	v_lshlrev_b32_e32 v149, 10, v155
	v_lshlrev_b32_e32 v154, 6, v155
	v_lshl_add_u32 v155, v146, 3, s25
	v_add_u32_e32 v149, v149, v155
	v_lshlrev_b32_e32 v149, 1, v149
	v_cmp_eq_u32_e64 s[50:51], 0, v146
	s_lshl_b32 s25, s46, 4
	s_add_u32 s20, s41, s25
	s_addc_u32 s21, s42, 0
	s_add_u32 s22, s20, 0x2000
	s_addc_u32 s23, s21, 0
	s_mov_b64 s[8:9], s[12:13]
	global_load_dwordx4 v[170:173], v149, s[8:9]
	global_load_dwordx4 v[174:177], v149, s[8:9] offset:256
	s_add_u32 s8, s8, 0x8000
	s_addc_u32 s9, s9, 0
	global_load_dwordx4 v[178:181], v149, s[8:9]
	global_load_dwordx4 v[182:185], v149, s[8:9] offset:256
	s_add_u32 s8, s8, 0x8000
	s_addc_u32 s9, s9, 0
	global_load_dwordx4 v[186:189], v149, s[8:9]
	global_load_dwordx4 v[190:193], v149, s[8:9] offset:256
	s_add_u32 s8, s8, 0x8000
	s_addc_u32 s9, s9, 0
	global_load_dwordx4 v[194:197], v149, s[8:9]
	global_load_dwordx4 v[198:201], v149, s[8:9] offset:256
	s_add_u32 s8, s8, 0x28000
	s_addc_u32 s9, s9, 0
	global_load_dwordx4 v[202:205], v149, s[8:9]
	global_load_dwordx4 v[220:223], v149, s[8:9] offset:256
	s_add_u32 s8, s8, 0x8000
	s_addc_u32 s9, s9, 0
	global_load_dwordx4 v[224:227], v149, s[8:9]
	global_load_dwordx4 v[228:231], v149, s[8:9] offset:256
	s_add_u32 s8, s8, 0x8000
	s_addc_u32 s9, s9, 0
	global_load_dwordx4 v[232:235], v149, s[8:9]
	global_load_dwordx4 v[158:161], v149, s[8:9] offset:256
	s_add_u32 s8, s8, 0x8000
	s_addc_u32 s9, s9, 0
	global_load_dwordx4 v[150:153], v149, s[8:9]
	global_load_dwordx4 v[142:145], v149, s[8:9] offset:256
	s_and_b64 vcc, exec, s[16:17]
	s_cbranch_vccz .Lres7b_nobar
	s_barrier
